# GEMM K-loops: issue the two tight A-half-tile LDS-DMAs at the top of their sub-phase (before the ds_reads), dedicated address VGPR pair v250:251; on top of v42
# baseline (speedup 1.0000x reference)
; #define PG8_STAGE(bufoff, gbase, V0, V1) do { \
;         __builtin_amdgcn_global_load_lds((const unsigned*)((const char*)(gbase) + (V0)), (LAS unsigned*)(lds + (bufoff) + ldsw), 16, 0, 0); \
;         __builtin_amdgcn_global_load_lds((const unsigned*)((const char*)(gbase) + (V1)), (LAS unsigned*)(lds + (bufoff) + ldsw + 8192), 16, 0, 0); } while (0)
; #define PG8_LDA(dst, b, h) do { _Pragma("unroll") for (int m = 0; m < 4; ++m) _Pragma("unroll") for (int k = 0; k < 2; ++k) dst[m][k] = *(const LAS bf16x8*)(lds + PG8_SA(b, h) + aoff + m * 2048 + k * 1024); } while (0)
; #define PG8_LDB(dst, b, h) do { _Pragma("unroll") for (int n = 0; n < 2; ++n) _Pragma("unroll") for (int k = 0; k < 2; ++k) dst[n][k] = *(const LAS bf16x8*)(lds + PG8_SB(b, h) + boff + n * 2048 + k * 1024); } while (0)
; #define PG8_MMA(ai, bj, At, Bt) do { __builtin_amdgcn_s_setprio(1); _Pragma("unroll") for (int m = 0; m < 4; ++m) _Pragma("unroll") for (int n = 0; n < 2; ++n) _Pragma("unroll") for (int k = 0; k < 2; ++k) \
;         acc[ai][bj][m][n] = __builtin_amdgcn_mfma_f32_16x16x32_bf16(Bt[n][k], At[m][k], acc[ai][bj][m][n], 0, 0, 0); __builtin_amdgcn_s_setprio(0); } while (0)
; #define PG8_WAIT_V(n) asm volatile("s_waitcnt vmcnt(" #n ")" ::: "memory")
; #define PG8_WAIT_L(n) asm volatile("s_waitcnt lgkmcnt(" #n ")" ::: "memory")
; #define PG8_BAR __builtin_amdgcn_s_barrier()
; #define PG8_SCHED __builtin_amdgcn_sched_barrier(0)
; template <class Epi, class Sched>
; DI void gemm_phase(LAS unsigned char* lds, const int lda2, const int ldb2, const int nt, const Sched& S, const Epi& E) {
;     ...
;             PG8_LDB(B0, 0, 0); PG8_LDB(B1, 0, 1); PG8_SCHED; PG8_LDA(At, 0, 0); PG8_STAGE(PG8_SA(1, 1), a1 + hstepA, vA0, vA1);
;             PG8_WAIT_V(8); PG8_WAIT_L(0); PG8_BAR; PG8_MMA(0, 0, At, B0); PG8_MMA(0, 1, At, B1); PG8_BAR; PG8_SCHED;
;             PG8_LDA(At, 0, 1); PG8_STAGE(PG8_SB(0, 0), b2, vB0, vB1); PG8_STAGE(PG8_SB(0, 1), b2 + hstepB, vB0, vB1); PG8_STAGE(PG8_SA(0, 0), a2, vA0, vA1);
;             PG8_WAIT_V(8); PG8_WAIT_L(0); PG8_BAR; PG8_MMA(1, 0, At, B0); PG8_MMA(1, 1, At, B1); PG8_BAR; PG8_SCHED;
.LBB0_198:
	s_add_u32 s4, s4, 0x40080
	s_addc_u32 s5, s5, 0
	s_add_u32 s7, s22, 0x100
	s_addc_u32 s15, s23, 0
	s_mov_b32 s17, -2
	s_add_u32 s22, s4, 0xfffc0080
	s_addc_u32 s23, s5, -1
	s_add_i32 s27, 0, 0x10000
	s_cmp_eq_u32 s17, 12
	s_cselect_b32 s25, s19, s23
	s_cselect_b32 s24, s18, s22
	s_cselect_b32 s23, s21, s15
	s_cselect_b32 s22, s20, s7
	s_add_i32 s48, 0, 0x14000
	v_add_u32_e32 v152, s27, v158
	v_add_u32_e32 v172, s48, v158
	v_lshl_add_u64 v[250:251], s[4:5], 0, v[136:137]
	s_add_i32 m0, s55, 0xc000
	s_nop 0
	global_load_lds_dwordx4 v[250:251], off
	v_lshl_add_u64 v[250:251], s[4:5], 0, v[138:139]
	s_add_i32 m0, s55, 0xe000
	s_nop 0
	global_load_lds_dwordx4 v[250:251], off
	ds_read_b128 v[140:143], v152
	ds_read_b128 v[144:147], v152 offset:1024
	ds_read_b128 v[148:151], v152 offset:2048
	ds_read_b128 v[152:155], v152 offset:3072
	ds_read_b128 v[160:163], v172
	ds_read_b128 v[164:167], v172 offset:1024
	ds_read_b128 v[168:171], v172 offset:2048
	ds_read_b128 v[172:175], v172 offset:3072
	ds_read_b128 v[176:179], v159
	ds_read_b128 v[180:183], v159 offset:1024
	ds_read_b128 v[184:187], v159 offset:2048
	ds_read_b128 v[188:191], v159 offset:3072
	ds_read_b128 v[192:195], v159 offset:4096
	ds_read_b128 v[202:205], v159 offset:5120
	ds_read_b128 v[206:209], v159 offset:6144
	ds_read_b128 v[210:213], v159 offset:7168
	s_waitcnt vmcnt(8)
	s_waitcnt lgkmcnt(0)
	s_barrier
	s_setprio 1
	s_waitcnt lgkmcnt(0)
	v_mfma_f32_16x16x32_bf16 v[126:129], v[140:143], v[176:179], 0
	v_mfma_f32_16x16x32_bf16 v[122:125], v[148:151], v[176:179], 0
	v_mfma_f32_16x16x32_bf16 v[106:109], v[148:151], v[184:187], 0
	v_mfma_f32_16x16x32_bf16 v[110:113], v[140:143], v[184:187], 0
	v_mfma_f32_16x16x32_bf16 v[92:95], v[140:143], v[192:195], 0
	v_mfma_f32_16x16x32_bf16 v[88:91], v[148:151], v[192:195], 0
	v_mfma_f32_16x16x32_bf16 v[72:75], v[148:151], v[206:209], 0
	v_mfma_f32_16x16x32_bf16 v[76:79], v[140:143], v[206:209], 0
	v_mfma_f32_16x16x32_bf16 v[126:129], v[144:147], v[180:183], v[126:129]
	v_mfma_f32_16x16x32_bf16 v[122:125], v[152:155], v[180:183], v[122:125]
	v_mfma_f32_16x16x32_bf16 v[106:109], v[152:155], v[188:191], v[106:109]
	v_mfma_f32_16x16x32_bf16 v[110:113], v[144:147], v[188:191], v[110:113]
	v_mfma_f32_16x16x32_bf16 v[92:95], v[144:147], v[202:205], v[92:95]
	v_mfma_f32_16x16x32_bf16 v[88:91], v[152:155], v[202:205], v[88:91]
	v_mfma_f32_16x16x32_bf16 v[72:75], v[152:155], v[210:213], v[72:75]
	v_mfma_f32_16x16x32_bf16 v[76:79], v[144:147], v[210:213], v[76:79]
	s_setprio 0
	s_setprio 1
	v_mfma_f32_16x16x32_bf16 v[118:121], v[160:163], v[176:179], 0
	v_mfma_f32_16x16x32_bf16 v[114:117], v[168:171], v[176:179], 0
	v_mfma_f32_16x16x32_bf16 v[98:101], v[168:171], v[184:187], 0
	v_mfma_f32_16x16x32_bf16 v[102:105], v[160:163], v[184:187], 0
	v_mfma_f32_16x16x32_bf16 v[84:87], v[160:163], v[192:195], 0
	v_mfma_f32_16x16x32_bf16 v[80:83], v[168:171], v[192:195], 0
	v_mfma_f32_16x16x32_bf16 v[64:67], v[168:171], v[206:209], 0
	v_mfma_f32_16x16x32_bf16 v[68:71], v[160:163], v[206:209], 0
	v_mfma_f32_16x16x32_bf16 v[118:121], v[164:167], v[180:183], v[118:121]
	v_mfma_f32_16x16x32_bf16 v[114:117], v[172:175], v[180:183], v[114:117]
	v_mfma_f32_16x16x32_bf16 v[98:101], v[172:175], v[188:191], v[98:101]
	v_mfma_f32_16x16x32_bf16 v[102:105], v[164:167], v[188:191], v[102:105]
	v_mfma_f32_16x16x32_bf16 v[84:87], v[164:167], v[202:205], v[84:87]
	v_mfma_f32_16x16x32_bf16 v[80:83], v[172:175], v[202:205], v[80:83]
	v_mfma_f32_16x16x32_bf16 v[64:67], v[172:175], v[210:213], v[64:67]
	v_mfma_f32_16x16x32_bf16 v[68:71], v[164:167], v[210:213], v[68:71]
	s_setprio 0
	s_barrier
	s_add_i32 s27, s27, s54
	v_lshl_add_u64 v[214:215], s[22:23], 0, v[96:97]
	s_mov_b32 m0, s27
	ds_read_b128 v[176:179], v159 offset:16384
	ds_read_b128 v[180:183], v159 offset:17408
	ds_read_b128 v[184:187], v159 offset:18432
	ds_read_b128 v[188:191], v159 offset:19456
	ds_read_b128 v[192:195], v159 offset:20480
	ds_read_b128 v[202:205], v159 offset:21504
	ds_read_b128 v[206:209], v159 offset:22528
	ds_read_b128 v[210:213], v159 offset:23552
	global_load_lds_dwordx4 v[214:215], off
	s_add_i32 m0, s27, 0x2000
	s_add_u32 s28, s22, 0x40000
	v_lshl_add_u64 v[216:217], s[22:23], 0, v[130:131]
	s_addc_u32 s29, s23, 0
	s_add_i32 s27, s48, s54
	global_load_lds_dwordx4 v[216:217], off
	v_lshl_add_u64 v[218:219], s[28:29], 0, v[96:97]
	s_mov_b32 m0, s27
	v_lshl_add_u64 v[220:221], s[24:25], 0, v[134:135]
	global_load_lds_dwordx4 v[218:219], off
	v_lshl_add_u64 v[218:219], s[28:29], 0, v[130:131]
	s_add_i32 m0, s27, 0x2000
	s_nop 0
	global_load_lds_dwordx4 v[218:219], off
	v_lshl_add_u64 v[218:219], s[24:25], 0, v[132:133]
	s_mov_b32 m0, s55
	s_nop 0
	global_load_lds_dwordx4 v[218:219], off
	s_mov_b32 m0, s72
	s_nop 0
	global_load_lds_dwordx4 v[220:221], off
	s_waitcnt vmcnt(8)
	s_waitcnt lgkmcnt(0)
	s_barrier
; #define PG8_STAGE(bufoff, gbase, V0, V1) do { \
;         __builtin_amdgcn_global_load_lds((const unsigned*)((const char*)(gbase) + (V0)), (LAS unsigned*)(lds + (bufoff) + ldsw), 16, 0, 0); \
;         __builtin_amdgcn_global_load_lds((const unsigned*)((const char*)(gbase) + (V1)), (LAS unsigned*)(lds + (bufoff) + ldsw + 8192), 16, 0, 0); } while (0)
; #define PG8_LDA(dst, b, h) do { _Pragma("unroll") for (int m = 0; m < 4; ++m) _Pragma("unroll") for (int k = 0; k < 2; ++k) dst[m][k] = *(const LAS bf16x8*)(lds + PG8_SA(b, h) + aoff + m * 2048 + k * 1024); } while (0)
; #define PG8_LDB(dst, b, h) do { _Pragma("unroll") for (int n = 0; n < 2; ++n) _Pragma("unroll") for (int k = 0; k < 2; ++k) dst[n][k] = *(const LAS bf16x8*)(lds + PG8_SB(b, h) + boff + n * 2048 + k * 1024); } while (0)
; #define PG8_MMA(ai, bj, At, Bt) do { __builtin_amdgcn_s_setprio(1); _Pragma("unroll") for (int m = 0; m < 4; ++m) _Pragma("unroll") for (int n = 0; n < 2; ++n) _Pragma("unroll") for (int k = 0; k < 2; ++k) \
;         acc[ai][bj][m][n] = __builtin_amdgcn_mfma_f32_16x16x32_bf16(Bt[n][k], At[m][k], acc[ai][bj][m][n], 0, 0, 0); __builtin_amdgcn_s_setprio(0); } while (0)
; #define PG8_WAIT_V(n) asm volatile("s_waitcnt vmcnt(" #n ")" ::: "memory")
; #define PG8_WAIT_L(n) asm volatile("s_waitcnt lgkmcnt(" #n ")" ::: "memory")
; #define PG8_BAR __builtin_amdgcn_s_barrier()
; #define PG8_SCHED __builtin_amdgcn_sched_barrier(0)
; template <class Epi, class Sched>
; DI void gemm_phase(LAS unsigned char* lds, const int lda2, const int ldb2, const int nt, const Sched& S, const Epi& E) {
;     ...
;             PG8_WAIT_V(8); PG8_WAIT_L(0); PG8_BAR; PG8_MMA(1, 0, At, B0); PG8_MMA(1, 1, At, B1); PG8_BAR; PG8_SCHED;
;             PG8_LDB(B0, 1, 0); PG8_LDB(B1, 1, 1); PG8_SCHED; PG8_LDA(At, 1, 0); PG8_STAGE(PG8_SA(0, 1), a2 + hstepA, vA0, vA1);
;             PG8_WAIT_V(8); PG8_WAIT_L(0); PG8_BAR; PG8_MMA(0, 0, At, B0); PG8_MMA(0, 1, At, B1); PG8_BAR; PG8_SCHED;
;             PG8_LDA(At, 1, 1); PG8_STAGE(PG8_SB(1, 0), b3, vB0, vB1); PG8_STAGE(PG8_SB(1, 1), b3 + hstepB, vB0, vB1); PG8_STAGE(PG8_SA(1, 0), a3, vA0, vA1);
;             PG8_WAIT_V(8); PG8_WAIT_L(0); PG8_BAR; PG8_MMA(1, 0, At, B0); PG8_MMA(1, 1, At, B1); PG8_BAR; PG8_SCHED;
	s_setprio 1
	s_waitcnt lgkmcnt(0)
	v_mfma_f32_16x16x32_bf16 v[60:63], v[140:143], v[176:179], 0
	v_mfma_f32_16x16x32_bf16 v[56:59], v[148:151], v[176:179], 0
	v_mfma_f32_16x16x32_bf16 v[40:43], v[148:151], v[184:187], 0
	v_mfma_f32_16x16x32_bf16 v[44:47], v[140:143], v[184:187], 0
	v_mfma_f32_16x16x32_bf16 v[28:31], v[140:143], v[192:195], 0
	v_mfma_f32_16x16x32_bf16 v[24:27], v[148:151], v[192:195], 0
	v_mfma_f32_16x16x32_bf16 v[8:11], v[148:151], v[206:209], 0
	v_mfma_f32_16x16x32_bf16 v[12:15], v[140:143], v[206:209], 0
	v_mfma_f32_16x16x32_bf16 v[60:63], v[144:147], v[180:183], v[60:63]
	v_mfma_f32_16x16x32_bf16 v[56:59], v[152:155], v[180:183], v[56:59]
	v_mfma_f32_16x16x32_bf16 v[40:43], v[152:155], v[188:191], v[40:43]
	v_mfma_f32_16x16x32_bf16 v[44:47], v[144:147], v[188:191], v[44:47]
	v_mfma_f32_16x16x32_bf16 v[28:31], v[144:147], v[202:205], v[28:31]
	v_mfma_f32_16x16x32_bf16 v[24:27], v[152:155], v[202:205], v[24:27]
	v_mfma_f32_16x16x32_bf16 v[8:11], v[152:155], v[210:213], v[8:11]
	v_mfma_f32_16x16x32_bf16 v[12:15], v[144:147], v[210:213], v[12:15]
	s_setprio 0
	s_setprio 1
	v_mfma_f32_16x16x32_bf16 v[52:55], v[160:163], v[176:179], 0
	v_mfma_f32_16x16x32_bf16 v[48:51], v[168:171], v[176:179], 0
	v_mfma_f32_16x16x32_bf16 v[32:35], v[168:171], v[184:187], 0
	v_mfma_f32_16x16x32_bf16 v[36:39], v[160:163], v[184:187], 0
	v_mfma_f32_16x16x32_bf16 v[20:23], v[160:163], v[192:195], 0
	v_mfma_f32_16x16x32_bf16 v[16:19], v[168:171], v[192:195], 0
	v_mfma_f32_16x16x32_bf16 v[0:3], v[168:171], v[206:209], 0
	v_mfma_f32_16x16x32_bf16 v[4:7], v[160:163], v[206:209], 0
	v_mfma_f32_16x16x32_bf16 v[52:55], v[164:167], v[180:183], v[52:55]
	v_mfma_f32_16x16x32_bf16 v[48:51], v[172:175], v[180:183], v[48:51]
	v_mfma_f32_16x16x32_bf16 v[32:35], v[172:175], v[188:191], v[32:35]
	v_mfma_f32_16x16x32_bf16 v[36:39], v[164:167], v[188:191], v[36:39]
	v_mfma_f32_16x16x32_bf16 v[20:23], v[164:167], v[202:205], v[20:23]
	v_mfma_f32_16x16x32_bf16 v[16:19], v[172:175], v[202:205], v[16:19]
	v_mfma_f32_16x16x32_bf16 v[0:3], v[172:175], v[210:213], v[0:3]
	v_mfma_f32_16x16x32_bf16 v[4:7], v[164:167], v[210:213], v[4:7]
	s_setprio 0
	s_barrier
	s_add_i32 s27, 0, 0x18000
	s_add_i32 s28, 0, 0x1c000
	v_add_u32_e32 v152, s27, v158
	v_add_u32_e32 v172, s28, v158
	s_add_u32 s24, s24, 0x40000
	s_addc_u32 s25, s25, 0
	s_mov_b32 m0, s73
	v_lshl_add_u64 v[250:251], s[24:25], 0, v[132:133]
	s_nop 0
	global_load_lds_dwordx4 v[250:251], off
	v_lshl_add_u64 v[250:251], s[24:25], 0, v[134:135]
	s_mov_b32 m0, s74
	s_nop 0
	global_load_lds_dwordx4 v[250:251], off
	ds_read_b128 v[140:143], v152
	ds_read_b128 v[144:147], v152 offset:1024
	ds_read_b128 v[148:151], v152 offset:2048
	ds_read_b128 v[152:155], v152 offset:3072
	ds_read_b128 v[160:163], v172
	ds_read_b128 v[164:167], v172 offset:1024
	ds_read_b128 v[168:171], v172 offset:2048
	ds_read_b128 v[172:175], v172 offset:3072
	ds_read_b128 v[176:179], v159 offset:32768
	ds_read_b128 v[180:183], v159 offset:33792
	ds_read_b128 v[184:187], v159 offset:34816
	ds_read_b128 v[188:191], v159 offset:35840
	ds_read_b128 v[192:195], v159 offset:36864
	ds_read_b128 v[202:205], v159 offset:37888
	ds_read_b128 v[206:209], v159 offset:38912
	ds_read_b128 v[210:213], v159 offset:39936
	s_waitcnt vmcnt(8)
	s_waitcnt lgkmcnt(0)
	s_barrier
	s_setprio 1
	s_waitcnt lgkmcnt(0)
	v_mfma_f32_16x16x32_bf16 v[126:129], v[140:143], v[176:179], v[126:129]
	v_mfma_f32_16x16x32_bf16 v[122:125], v[148:151], v[176:179], v[122:125]
	v_mfma_f32_16x16x32_bf16 v[106:109], v[148:151], v[184:187], v[106:109]
	v_mfma_f32_16x16x32_bf16 v[110:113], v[140:143], v[184:187], v[110:113]
	v_mfma_f32_16x16x32_bf16 v[92:95], v[140:143], v[192:195], v[92:95]
	v_mfma_f32_16x16x32_bf16 v[88:91], v[148:151], v[192:195], v[88:91]
	v_mfma_f32_16x16x32_bf16 v[72:75], v[148:151], v[206:209], v[72:75]
	v_mfma_f32_16x16x32_bf16 v[76:79], v[140:143], v[206:209], v[76:79]
	v_mfma_f32_16x16x32_bf16 v[126:129], v[144:147], v[180:183], v[126:129]
	v_mfma_f32_16x16x32_bf16 v[122:125], v[152:155], v[180:183], v[122:125]
	v_mfma_f32_16x16x32_bf16 v[106:109], v[152:155], v[188:191], v[106:109]
	v_mfma_f32_16x16x32_bf16 v[110:113], v[144:147], v[188:191], v[110:113]
	v_mfma_f32_16x16x32_bf16 v[92:95], v[144:147], v[202:205], v[92:95]
	v_mfma_f32_16x16x32_bf16 v[88:91], v[152:155], v[202:205], v[88:91]
	v_mfma_f32_16x16x32_bf16 v[72:75], v[152:155], v[210:213], v[72:75]
	v_mfma_f32_16x16x32_bf16 v[76:79], v[144:147], v[210:213], v[76:79]
	s_setprio 0
	s_setprio 1
	v_mfma_f32_16x16x32_bf16 v[118:121], v[160:163], v[176:179], v[118:121]
	v_mfma_f32_16x16x32_bf16 v[114:117], v[168:171], v[176:179], v[114:117]
	v_mfma_f32_16x16x32_bf16 v[98:101], v[168:171], v[184:187], v[98:101]
	v_mfma_f32_16x16x32_bf16 v[102:105], v[160:163], v[184:187], v[102:105]
	v_mfma_f32_16x16x32_bf16 v[84:87], v[160:163], v[192:195], v[84:87]
	v_mfma_f32_16x16x32_bf16 v[80:83], v[168:171], v[192:195], v[80:83]
	v_mfma_f32_16x16x32_bf16 v[64:67], v[168:171], v[206:209], v[64:67]
	v_mfma_f32_16x16x32_bf16 v[68:71], v[160:163], v[206:209], v[68:71]
	v_mfma_f32_16x16x32_bf16 v[118:121], v[164:167], v[180:183], v[118:121]
	v_mfma_f32_16x16x32_bf16 v[114:117], v[172:175], v[180:183], v[114:117]
	v_mfma_f32_16x16x32_bf16 v[98:101], v[172:175], v[188:191], v[98:101]
	v_mfma_f32_16x16x32_bf16 v[102:105], v[164:167], v[188:191], v[102:105]
	v_mfma_f32_16x16x32_bf16 v[84:87], v[164:167], v[202:205], v[84:87]
	v_mfma_f32_16x16x32_bf16 v[80:83], v[172:175], v[202:205], v[80:83]
	v_mfma_f32_16x16x32_bf16 v[64:67], v[172:175], v[210:213], v[64:67]
	v_mfma_f32_16x16x32_bf16 v[68:71], v[164:167], v[210:213], v[68:71]
	s_setprio 0
	s_barrier
; #define PG8_STAGE(bufoff, gbase, V0, V1) do { \
;         __builtin_amdgcn_global_load_lds((const unsigned*)((const char*)(gbase) + (V0)), (LAS unsigned*)(lds + (bufoff) + ldsw), 16, 0, 0); \
;         __builtin_amdgcn_global_load_lds((const unsigned*)((const char*)(gbase) + (V1)), (LAS unsigned*)(lds + (bufoff) + ldsw + 8192), 16, 0, 0); } while (0)
; #define PG8_LDA(dst, b, h) do { _Pragma("unroll") for (int m = 0; m < 4; ++m) _Pragma("unroll") for (int k = 0; k < 2; ++k) dst[m][k] = *(const LAS bf16x8*)(lds + PG8_SA(b, h) + aoff + m * 2048 + k * 1024); } while (0)
; #define PG8_LDB(dst, b, h) do { _Pragma("unroll") for (int n = 0; n < 2; ++n) _Pragma("unroll") for (int k = 0; k < 2; ++k) dst[n][k] = *(const LAS bf16x8*)(lds + PG8_SB(b, h) + boff + n * 2048 + k * 1024); } while (0)
; #define PG8_MMA(ai, bj, At, Bt) do { __builtin_amdgcn_s_setprio(1); _Pragma("unroll") for (int m = 0; m < 4; ++m) _Pragma("unroll") for (int n = 0; n < 2; ++n) _Pragma("unroll") for (int k = 0; k < 2; ++k) \
;         acc[ai][bj][m][n] = __builtin_amdgcn_mfma_f32_16x16x32_bf16(Bt[n][k], At[m][k], acc[ai][bj][m][n], 0, 0, 0); __builtin_amdgcn_s_setprio(0); } while (0)
; #define PG8_WAIT_V(n) asm volatile("s_waitcnt vmcnt(" #n ")" ::: "memory")
; #define PG8_WAIT_L(n) asm volatile("s_waitcnt lgkmcnt(" #n ")" ::: "memory")
; #define PG8_BAR __builtin_amdgcn_s_barrier()
; #define PG8_SCHED __builtin_amdgcn_sched_barrier(0)
; template <class Epi, class Sched>
; DI void gemm_phase(LAS unsigned char* lds, const int lda2, const int ldb2, const int nt, const Sched& S, const Epi& E) {
;     ...
;         for (int t = 0; t < nt; t += 2) {
;             const bool last = (t == nt - 2);
;             const char* a1 = cA + (size_t)(t + 1) * kstep;
;             const char* a2 = last ? nA : cA + (size_t)(t + 2) * kstep; const char* b2 = last ? nB : cB + (size_t)(t + 2) * kstep;
;             const char* a3 = a2 + kstep; const char* b3 = b2 + kstep;
;             PG8_LDB(B0, 0, 0); PG8_LDB(B1, 0, 1); PG8_SCHED; PG8_LDA(At, 0, 0); PG8_STAGE(PG8_SA(1, 1), a1 + hstepA, vA0, vA1);
;     ...
;             PG8_LDA(At, 1, 1); PG8_STAGE(PG8_SB(1, 0), b3, vB0, vB1); PG8_STAGE(PG8_SB(1, 1), b3 + hstepB, vB0, vB1); PG8_STAGE(PG8_SA(1, 0), a3, vA0, vA1);
;             PG8_WAIT_V(8); PG8_WAIT_L(0); PG8_BAR; PG8_MMA(1, 0, At, B0); PG8_MMA(1, 1, At, B1); PG8_BAR; PG8_SCHED;
	s_add_i32 s24, s27, s54
	v_lshl_add_u64 v[214:215], v[214:215], 0, s[86:87]
	s_mov_b32 m0, s24
	ds_read_b128 v[176:179], v159 offset:49152
	ds_read_b128 v[180:183], v159 offset:50176
	ds_read_b128 v[184:187], v159 offset:51200
	ds_read_b128 v[188:191], v159 offset:52224
	ds_read_b128 v[192:195], v159 offset:53248
	ds_read_b128 v[202:205], v159 offset:54272
	ds_read_b128 v[206:209], v159 offset:55296
	ds_read_b128 v[210:213], v159 offset:56320
	global_load_lds_dwordx4 v[214:215], off
	s_add_i32 m0, s24, 0x2000
	s_add_u32 s22, s22, 0x40080
	v_lshl_add_u64 v[214:215], v[216:217], 0, s[86:87]
	s_addc_u32 s23, s23, 0
	s_add_i32 s24, s28, s54
	global_load_lds_dwordx4 v[214:215], off
	v_lshl_add_u64 v[214:215], s[22:23], 0, v[96:97]
	s_mov_b32 m0, s24
	s_nop 0
	global_load_lds_dwordx4 v[214:215], off
	v_lshl_add_u64 v[214:215], s[22:23], 0, v[130:131]
	s_add_i32 m0, s24, 0x2000
	s_nop 0
	global_load_lds_dwordx4 v[214:215], off
	v_lshl_add_u64 v[214:215], v[218:219], 0, s[86:87]
	s_mov_b32 m0, s77
	s_nop 0
	global_load_lds_dwordx4 v[214:215], off
	v_lshl_add_u64 v[214:215], v[220:221], 0, s[86:87]
	s_mov_b32 m0, s78
	s_nop 0
	global_load_lds_dwordx4 v[214:215], off
	s_waitcnt vmcnt(8)
	s_waitcnt lgkmcnt(0)
	s_barrier
	s_setprio 1
	s_waitcnt lgkmcnt(0)
	v_mfma_f32_16x16x32_bf16 v[60:63], v[140:143], v[176:179], v[60:63]
	v_mfma_f32_16x16x32_bf16 v[56:59], v[148:151], v[176:179], v[56:59]
	v_mfma_f32_16x16x32_bf16 v[40:43], v[148:151], v[184:187], v[40:43]
	v_mfma_f32_16x16x32_bf16 v[44:47], v[140:143], v[184:187], v[44:47]
	v_mfma_f32_16x16x32_bf16 v[28:31], v[140:143], v[192:195], v[28:31]
	v_mfma_f32_16x16x32_bf16 v[24:27], v[148:151], v[192:195], v[24:27]
	v_mfma_f32_16x16x32_bf16 v[8:11], v[148:151], v[206:209], v[8:11]
	v_mfma_f32_16x16x32_bf16 v[12:15], v[140:143], v[206:209], v[12:15]
	v_mfma_f32_16x16x32_bf16 v[60:63], v[144:147], v[180:183], v[60:63]
	v_mfma_f32_16x16x32_bf16 v[56:59], v[152:155], v[180:183], v[56:59]
	v_mfma_f32_16x16x32_bf16 v[40:43], v[152:155], v[188:191], v[40:43]
	v_mfma_f32_16x16x32_bf16 v[44:47], v[144:147], v[188:191], v[44:47]
	v_mfma_f32_16x16x32_bf16 v[28:31], v[144:147], v[202:205], v[28:31]
	v_mfma_f32_16x16x32_bf16 v[24:27], v[152:155], v[202:205], v[24:27]
	v_mfma_f32_16x16x32_bf16 v[8:11], v[152:155], v[210:213], v[8:11]
	v_mfma_f32_16x16x32_bf16 v[12:15], v[144:147], v[210:213], v[12:15]
	s_setprio 0
	s_setprio 1
	v_mfma_f32_16x16x32_bf16 v[52:55], v[160:163], v[176:179], v[52:55]
	v_mfma_f32_16x16x32_bf16 v[48:51], v[168:171], v[176:179], v[48:51]
	v_mfma_f32_16x16x32_bf16 v[32:35], v[168:171], v[184:187], v[32:35]
	v_mfma_f32_16x16x32_bf16 v[36:39], v[160:163], v[184:187], v[36:39]
	v_mfma_f32_16x16x32_bf16 v[20:23], v[160:163], v[192:195], v[20:23]
	v_mfma_f32_16x16x32_bf16 v[16:19], v[168:171], v[192:195], v[16:19]
	v_mfma_f32_16x16x32_bf16 v[0:3], v[168:171], v[206:209], v[0:3]
	v_mfma_f32_16x16x32_bf16 v[4:7], v[160:163], v[206:209], v[4:7]
	v_mfma_f32_16x16x32_bf16 v[52:55], v[164:167], v[180:183], v[52:55]
	v_mfma_f32_16x16x32_bf16 v[48:51], v[172:175], v[180:183], v[48:51]
	v_mfma_f32_16x16x32_bf16 v[32:35], v[172:175], v[188:191], v[32:35]
	v_mfma_f32_16x16x32_bf16 v[36:39], v[164:167], v[188:191], v[36:39]
	v_mfma_f32_16x16x32_bf16 v[20:23], v[164:167], v[202:205], v[20:23]
	v_mfma_f32_16x16x32_bf16 v[16:19], v[172:175], v[202:205], v[16:19]
	v_mfma_f32_16x16x32_bf16 v[0:3], v[172:175], v[210:213], v[0:3]
	v_mfma_f32_16x16x32_bf16 v[4:7], v[164:167], v[210:213], v[4:7]
	s_setprio 0
	s_barrier
	s_add_i32 s17, s17, 2
	s_add_u32 s4, s4, 0x100
	s_addc_u32 s5, s5, 0
	s_add_u32 s7, s7, 0x100
	s_addc_u32 s15, s15, 0
.LBB0_199:
	s_add_u32 s22, s4, 0xfffc0080
	s_addc_u32 s23, s5, -1
	s_add_i32 s27, 0, 0x10000
	s_cmp_eq_u32 s17, 12
	s_cselect_b32 s25, s19, s23
	s_cselect_b32 s24, s18, s22
	s_cselect_b32 s23, s21, s15
	s_cselect_b32 s22, s20, s7
	s_add_i32 s48, 0, 0x14000
	v_add_u32_e32 v152, s27, v158
	v_add_u32_e32 v172, s48, v158
	v_lshl_add_u64 v[250:251], s[4:5], 0, v[136:137]
	s_add_i32 m0, s55, 0xc000
	s_nop 0
	global_load_lds_dwordx4 v[250:251], off
	v_lshl_add_u64 v[250:251], s[4:5], 0, v[138:139]
	s_add_i32 m0, s55, 0xe000
	s_nop 0
	global_load_lds_dwordx4 v[250:251], off
	ds_read_b128 v[140:143], v152
	ds_read_b128 v[144:147], v152 offset:1024
	ds_read_b128 v[148:151], v152 offset:2048
	ds_read_b128 v[152:155], v152 offset:3072
	ds_read_b128 v[160:163], v172
	ds_read_b128 v[164:167], v172 offset:1024
	ds_read_b128 v[168:171], v172 offset:2048
	ds_read_b128 v[172:175], v172 offset:3072
	ds_read_b128 v[176:179], v159
	ds_read_b128 v[180:183], v159 offset:1024
	ds_read_b128 v[184:187], v159 offset:2048
	ds_read_b128 v[188:191], v159 offset:3072
	ds_read_b128 v[192:195], v159 offset:4096
	ds_read_b128 v[202:205], v159 offset:5120
	ds_read_b128 v[206:209], v159 offset:6144
	ds_read_b128 v[210:213], v159 offset:7168
	s_waitcnt vmcnt(8)
	s_waitcnt lgkmcnt(0)
	s_barrier
; #define PG8_STAGE(bufoff, gbase, V0, V1) do { \
;         __builtin_amdgcn_global_load_lds((const unsigned*)((const char*)(gbase) + (V0)), (LAS unsigned*)(lds + (bufoff) + ldsw), 16, 0, 0); \
;         __builtin_amdgcn_global_load_lds((const unsigned*)((const char*)(gbase) + (V1)), (LAS unsigned*)(lds + (bufoff) + ldsw + 8192), 16, 0, 0); } while (0)
; #define PG8_LDA(dst, b, h) do { _Pragma("unroll") for (int m = 0; m < 4; ++m) _Pragma("unroll") for (int k = 0; k < 2; ++k) dst[m][k] = *(const LAS bf16x8*)(lds + PG8_SA(b, h) + aoff + m * 2048 + k * 1024); } while (0)
; #define PG8_LDB(dst, b, h) do { _Pragma("unroll") for (int n = 0; n < 2; ++n) _Pragma("unroll") for (int k = 0; k < 2; ++k) dst[n][k] = *(const LAS bf16x8*)(lds + PG8_SB(b, h) + boff + n * 2048 + k * 1024); } while (0)
; #define PG8_MMA(ai, bj, At, Bt) do { __builtin_amdgcn_s_setprio(1); _Pragma("unroll") for (int m = 0; m < 4; ++m) _Pragma("unroll") for (int n = 0; n < 2; ++n) _Pragma("unroll") for (int k = 0; k < 2; ++k) \
;         acc[ai][bj][m][n] = __builtin_amdgcn_mfma_f32_16x16x32_bf16(Bt[n][k], At[m][k], acc[ai][bj][m][n], 0, 0, 0); __builtin_amdgcn_s_setprio(0); } while (0)
; #define PG8_WAIT_V(n) asm volatile("s_waitcnt vmcnt(" #n ")" ::: "memory")
; #define PG8_WAIT_L(n) asm volatile("s_waitcnt lgkmcnt(" #n ")" ::: "memory")
; #define PG8_BAR __builtin_amdgcn_s_barrier()
; #define PG8_SCHED __builtin_amdgcn_sched_barrier(0)
; template <class Epi, class Sched>
; DI void gemm_phase(LAS unsigned char* lds, const int lda2, const int ldb2, const int nt, const Sched& S, const Epi& E) {
;     ...
;             PG8_WAIT_V(8); PG8_WAIT_L(0); PG8_BAR; PG8_MMA(0, 0, At, B0); PG8_MMA(0, 1, At, B1); PG8_BAR; PG8_SCHED;
;             PG8_LDA(At, 0, 1); PG8_STAGE(PG8_SB(0, 0), b2, vB0, vB1); PG8_STAGE(PG8_SB(0, 1), b2 + hstepB, vB0, vB1); PG8_STAGE(PG8_SA(0, 0), a2, vA0, vA1);
;             PG8_WAIT_V(8); PG8_WAIT_L(0); PG8_BAR; PG8_MMA(1, 0, At, B0); PG8_MMA(1, 1, At, B1); PG8_BAR; PG8_SCHED;
;             PG8_LDB(B0, 1, 0); PG8_LDB(B1, 1, 1); PG8_SCHED; PG8_LDA(At, 1, 0); PG8_STAGE(PG8_SA(0, 1), a2 + hstepA, vA0, vA1);
;             PG8_WAIT_V(8); PG8_WAIT_L(0); PG8_BAR; PG8_MMA(0, 0, At, B0); PG8_MMA(0, 1, At, B1); PG8_BAR; PG8_SCHED;
	s_setprio 1
	s_waitcnt lgkmcnt(0)
	v_mfma_f32_16x16x32_bf16 v[126:129], v[140:143], v[176:179], v[126:129]
	v_mfma_f32_16x16x32_bf16 v[122:125], v[148:151], v[176:179], v[122:125]
	v_mfma_f32_16x16x32_bf16 v[106:109], v[148:151], v[184:187], v[106:109]
	v_mfma_f32_16x16x32_bf16 v[110:113], v[140:143], v[184:187], v[110:113]
	v_mfma_f32_16x16x32_bf16 v[92:95], v[140:143], v[192:195], v[92:95]
	v_mfma_f32_16x16x32_bf16 v[88:91], v[148:151], v[192:195], v[88:91]
	v_mfma_f32_16x16x32_bf16 v[72:75], v[148:151], v[206:209], v[72:75]
	v_mfma_f32_16x16x32_bf16 v[76:79], v[140:143], v[206:209], v[76:79]
	v_mfma_f32_16x16x32_bf16 v[126:129], v[144:147], v[180:183], v[126:129]
	v_mfma_f32_16x16x32_bf16 v[122:125], v[152:155], v[180:183], v[122:125]
	v_mfma_f32_16x16x32_bf16 v[106:109], v[152:155], v[188:191], v[106:109]
	v_mfma_f32_16x16x32_bf16 v[110:113], v[144:147], v[188:191], v[110:113]
	v_mfma_f32_16x16x32_bf16 v[92:95], v[144:147], v[202:205], v[92:95]
	v_mfma_f32_16x16x32_bf16 v[88:91], v[152:155], v[202:205], v[88:91]
	v_mfma_f32_16x16x32_bf16 v[72:75], v[152:155], v[210:213], v[72:75]
	v_mfma_f32_16x16x32_bf16 v[76:79], v[144:147], v[210:213], v[76:79]
	s_setprio 0
	s_setprio 1
	v_mfma_f32_16x16x32_bf16 v[118:121], v[160:163], v[176:179], v[118:121]
	v_mfma_f32_16x16x32_bf16 v[114:117], v[168:171], v[176:179], v[114:117]
	v_mfma_f32_16x16x32_bf16 v[98:101], v[168:171], v[184:187], v[98:101]
	v_mfma_f32_16x16x32_bf16 v[102:105], v[160:163], v[184:187], v[102:105]
	v_mfma_f32_16x16x32_bf16 v[84:87], v[160:163], v[192:195], v[84:87]
	v_mfma_f32_16x16x32_bf16 v[80:83], v[168:171], v[192:195], v[80:83]
	v_mfma_f32_16x16x32_bf16 v[64:67], v[168:171], v[206:209], v[64:67]
	v_mfma_f32_16x16x32_bf16 v[68:71], v[160:163], v[206:209], v[68:71]
	v_mfma_f32_16x16x32_bf16 v[118:121], v[164:167], v[180:183], v[118:121]
	v_mfma_f32_16x16x32_bf16 v[114:117], v[172:175], v[180:183], v[114:117]
	v_mfma_f32_16x16x32_bf16 v[98:101], v[172:175], v[188:191], v[98:101]
	v_mfma_f32_16x16x32_bf16 v[102:105], v[164:167], v[188:191], v[102:105]
	v_mfma_f32_16x16x32_bf16 v[84:87], v[164:167], v[202:205], v[84:87]
	v_mfma_f32_16x16x32_bf16 v[80:83], v[172:175], v[202:205], v[80:83]
	v_mfma_f32_16x16x32_bf16 v[64:67], v[172:175], v[210:213], v[64:67]
	v_mfma_f32_16x16x32_bf16 v[68:71], v[164:167], v[210:213], v[68:71]
	s_setprio 0
	s_barrier
	s_add_i32 s27, s27, s54
	v_lshl_add_u64 v[214:215], s[22:23], 0, v[96:97]
	s_mov_b32 m0, s27
	ds_read_b128 v[176:179], v159 offset:16384
	ds_read_b128 v[180:183], v159 offset:17408
	ds_read_b128 v[184:187], v159 offset:18432
	ds_read_b128 v[188:191], v159 offset:19456
	ds_read_b128 v[192:195], v159 offset:20480
	ds_read_b128 v[202:205], v159 offset:21504
	ds_read_b128 v[206:209], v159 offset:22528
	ds_read_b128 v[210:213], v159 offset:23552
	global_load_lds_dwordx4 v[214:215], off
	s_add_i32 m0, s27, 0x2000
	s_add_u32 s28, s22, 0x40000
	v_lshl_add_u64 v[216:217], s[22:23], 0, v[130:131]
	s_addc_u32 s29, s23, 0
	s_add_i32 s27, s48, s54
	global_load_lds_dwordx4 v[216:217], off
	v_lshl_add_u64 v[218:219], s[28:29], 0, v[96:97]
	s_mov_b32 m0, s27
	v_lshl_add_u64 v[220:221], s[24:25], 0, v[134:135]
	global_load_lds_dwordx4 v[218:219], off
	v_lshl_add_u64 v[218:219], s[28:29], 0, v[130:131]
	s_add_i32 m0, s27, 0x2000
	s_nop 0
	global_load_lds_dwordx4 v[218:219], off
	v_lshl_add_u64 v[218:219], s[24:25], 0, v[132:133]
	s_mov_b32 m0, s55
	s_nop 0
	global_load_lds_dwordx4 v[218:219], off
	s_mov_b32 m0, s72
	s_nop 0
	global_load_lds_dwordx4 v[220:221], off
	s_waitcnt vmcnt(8)
	s_waitcnt lgkmcnt(0)
	s_barrier
	s_setprio 1
	s_waitcnt lgkmcnt(0)
	v_mfma_f32_16x16x32_bf16 v[60:63], v[140:143], v[176:179], v[60:63]
	v_mfma_f32_16x16x32_bf16 v[56:59], v[148:151], v[176:179], v[56:59]
	v_mfma_f32_16x16x32_bf16 v[40:43], v[148:151], v[184:187], v[40:43]
	v_mfma_f32_16x16x32_bf16 v[44:47], v[140:143], v[184:187], v[44:47]
	v_mfma_f32_16x16x32_bf16 v[28:31], v[140:143], v[192:195], v[28:31]
	v_mfma_f32_16x16x32_bf16 v[24:27], v[148:151], v[192:195], v[24:27]
	v_mfma_f32_16x16x32_bf16 v[8:11], v[148:151], v[206:209], v[8:11]
	v_mfma_f32_16x16x32_bf16 v[12:15], v[140:143], v[206:209], v[12:15]
	v_mfma_f32_16x16x32_bf16 v[60:63], v[144:147], v[180:183], v[60:63]
	v_mfma_f32_16x16x32_bf16 v[56:59], v[152:155], v[180:183], v[56:59]
	v_mfma_f32_16x16x32_bf16 v[40:43], v[152:155], v[188:191], v[40:43]
	v_mfma_f32_16x16x32_bf16 v[44:47], v[144:147], v[188:191], v[44:47]
	v_mfma_f32_16x16x32_bf16 v[28:31], v[144:147], v[202:205], v[28:31]
	v_mfma_f32_16x16x32_bf16 v[24:27], v[152:155], v[202:205], v[24:27]
	v_mfma_f32_16x16x32_bf16 v[8:11], v[152:155], v[210:213], v[8:11]
	v_mfma_f32_16x16x32_bf16 v[12:15], v[144:147], v[210:213], v[12:15]
	s_setprio 0
	s_setprio 1
	v_mfma_f32_16x16x32_bf16 v[52:55], v[160:163], v[176:179], v[52:55]
	v_mfma_f32_16x16x32_bf16 v[48:51], v[168:171], v[176:179], v[48:51]
	v_mfma_f32_16x16x32_bf16 v[32:35], v[168:171], v[184:187], v[32:35]
	v_mfma_f32_16x16x32_bf16 v[36:39], v[160:163], v[184:187], v[36:39]
	v_mfma_f32_16x16x32_bf16 v[20:23], v[160:163], v[192:195], v[20:23]
	v_mfma_f32_16x16x32_bf16 v[16:19], v[168:171], v[192:195], v[16:19]
	v_mfma_f32_16x16x32_bf16 v[0:3], v[168:171], v[206:209], v[0:3]
	v_mfma_f32_16x16x32_bf16 v[4:7], v[160:163], v[206:209], v[4:7]
	v_mfma_f32_16x16x32_bf16 v[52:55], v[164:167], v[180:183], v[52:55]
	v_mfma_f32_16x16x32_bf16 v[48:51], v[172:175], v[180:183], v[48:51]
	v_mfma_f32_16x16x32_bf16 v[32:35], v[172:175], v[188:191], v[32:35]
	v_mfma_f32_16x16x32_bf16 v[36:39], v[164:167], v[188:191], v[36:39]
	v_mfma_f32_16x16x32_bf16 v[20:23], v[164:167], v[202:205], v[20:23]
	v_mfma_f32_16x16x32_bf16 v[16:19], v[172:175], v[202:205], v[16:19]
	v_mfma_f32_16x16x32_bf16 v[0:3], v[172:175], v[210:213], v[0:3]
	v_mfma_f32_16x16x32_bf16 v[4:7], v[164:167], v[210:213], v[4:7]
	s_setprio 0
	s_barrier
; #define PG8_STAGE(bufoff, gbase, V0, V1) do { \
;         __builtin_amdgcn_global_load_lds((const unsigned*)((const char*)(gbase) + (V0)), (LAS unsigned*)(lds + (bufoff) + ldsw), 16, 0, 0); \
;         __builtin_amdgcn_global_load_lds((const unsigned*)((const char*)(gbase) + (V1)), (LAS unsigned*)(lds + (bufoff) + ldsw + 8192), 16, 0, 0); } while (0)
; #define PG8_LDA(dst, b, h) do { _Pragma("unroll") for (int m = 0; m < 4; ++m) _Pragma("unroll") for (int k = 0; k < 2; ++k) dst[m][k] = *(const LAS bf16x8*)(lds + PG8_SA(b, h) + aoff + m * 2048 + k * 1024); } while (0)
; #define PG8_LDB(dst, b, h) do { _Pragma("unroll") for (int n = 0; n < 2; ++n) _Pragma("unroll") for (int k = 0; k < 2; ++k) dst[n][k] = *(const LAS bf16x8*)(lds + PG8_SB(b, h) + boff + n * 2048 + k * 1024); } while (0)
; #define PG8_MMA(ai, bj, At, Bt) do { __builtin_amdgcn_s_setprio(1); _Pragma("unroll") for (int m = 0; m < 4; ++m) _Pragma("unroll") for (int n = 0; n < 2; ++n) _Pragma("unroll") for (int k = 0; k < 2; ++k) \
;         acc[ai][bj][m][n] = __builtin_amdgcn_mfma_f32_16x16x32_bf16(Bt[n][k], At[m][k], acc[ai][bj][m][n], 0, 0, 0); __builtin_amdgcn_s_setprio(0); } while (0)
; #define PG8_WAIT_V(n) asm volatile("s_waitcnt vmcnt(" #n ")" ::: "memory")
; #define PG8_WAIT_L(n) asm volatile("s_waitcnt lgkmcnt(" #n ")" ::: "memory")
; #define PG8_BAR __builtin_amdgcn_s_barrier()
; #define PG8_SCHED __builtin_amdgcn_sched_barrier(0)
; template <class Epi, class Sched>
; DI void gemm_phase(LAS unsigned char* lds, const int lda2, const int ldb2, const int nt, const Sched& S, const Epi& E) {
;     ...
;             PG8_LDB(B0, 1, 0); PG8_LDB(B1, 1, 1); PG8_SCHED; PG8_LDA(At, 1, 0); PG8_STAGE(PG8_SA(0, 1), a2 + hstepA, vA0, vA1);
;             PG8_WAIT_V(8); PG8_WAIT_L(0); PG8_BAR; PG8_MMA(0, 0, At, B0); PG8_MMA(0, 1, At, B1); PG8_BAR; PG8_SCHED;
	s_add_i32 s27, 0, 0x18000
	s_add_i32 s28, 0, 0x1c000
	v_add_u32_e32 v152, s27, v158
	v_add_u32_e32 v172, s28, v158
	s_add_u32 s24, s24, 0x40000
	s_addc_u32 s25, s25, 0
	s_mov_b32 m0, s73
	v_lshl_add_u64 v[250:251], s[24:25], 0, v[132:133]
	s_nop 0
	global_load_lds_dwordx4 v[250:251], off
	v_lshl_add_u64 v[250:251], s[24:25], 0, v[134:135]
	s_mov_b32 m0, s74
	s_nop 0
	global_load_lds_dwordx4 v[250:251], off
	ds_read_b128 v[140:143], v152
	ds_read_b128 v[144:147], v152 offset:1024
	ds_read_b128 v[148:151], v152 offset:2048
	ds_read_b128 v[152:155], v152 offset:3072
	ds_read_b128 v[160:163], v172
	ds_read_b128 v[164:167], v172 offset:1024
	ds_read_b128 v[168:171], v172 offset:2048
	ds_read_b128 v[172:175], v172 offset:3072
	ds_read_b128 v[176:179], v159 offset:32768
	ds_read_b128 v[180:183], v159 offset:33792
	ds_read_b128 v[184:187], v159 offset:34816
	ds_read_b128 v[188:191], v159 offset:35840
	ds_read_b128 v[192:195], v159 offset:36864
	ds_read_b128 v[202:205], v159 offset:37888
	ds_read_b128 v[206:209], v159 offset:38912
	ds_read_b128 v[210:213], v159 offset:39936
	s_waitcnt vmcnt(8)
	s_waitcnt lgkmcnt(0)
	s_barrier
	s_setprio 1
	s_waitcnt lgkmcnt(0)
	v_mfma_f32_16x16x32_bf16 v[126:129], v[140:143], v[176:179], v[126:129]
	v_mfma_f32_16x16x32_bf16 v[122:125], v[148:151], v[176:179], v[122:125]
	v_mfma_f32_16x16x32_bf16 v[106:109], v[148:151], v[184:187], v[106:109]
	v_mfma_f32_16x16x32_bf16 v[110:113], v[140:143], v[184:187], v[110:113]
	v_mfma_f32_16x16x32_bf16 v[92:95], v[140:143], v[192:195], v[92:95]
	v_mfma_f32_16x16x32_bf16 v[88:91], v[148:151], v[192:195], v[88:91]
	v_mfma_f32_16x16x32_bf16 v[72:75], v[148:151], v[206:209], v[72:75]
	v_mfma_f32_16x16x32_bf16 v[76:79], v[140:143], v[206:209], v[76:79]
	v_mfma_f32_16x16x32_bf16 v[126:129], v[144:147], v[180:183], v[126:129]
	v_mfma_f32_16x16x32_bf16 v[122:125], v[152:155], v[180:183], v[122:125]
	v_mfma_f32_16x16x32_bf16 v[106:109], v[152:155], v[188:191], v[106:109]
	v_mfma_f32_16x16x32_bf16 v[110:113], v[144:147], v[188:191], v[110:113]
	v_mfma_f32_16x16x32_bf16 v[92:95], v[144:147], v[202:205], v[92:95]
	v_mfma_f32_16x16x32_bf16 v[88:91], v[152:155], v[202:205], v[88:91]
	v_mfma_f32_16x16x32_bf16 v[72:75], v[152:155], v[210:213], v[72:75]
	v_mfma_f32_16x16x32_bf16 v[76:79], v[144:147], v[210:213], v[76:79]
	s_setprio 0
	s_setprio 1
	v_mfma_f32_16x16x32_bf16 v[118:121], v[160:163], v[176:179], v[118:121]
	v_mfma_f32_16x16x32_bf16 v[114:117], v[168:171], v[176:179], v[114:117]
	v_mfma_f32_16x16x32_bf16 v[98:101], v[168:171], v[184:187], v[98:101]
	v_mfma_f32_16x16x32_bf16 v[102:105], v[160:163], v[184:187], v[102:105]
	v_mfma_f32_16x16x32_bf16 v[84:87], v[160:163], v[192:195], v[84:87]
	v_mfma_f32_16x16x32_bf16 v[80:83], v[168:171], v[192:195], v[80:83]
	v_mfma_f32_16x16x32_bf16 v[64:67], v[168:171], v[206:209], v[64:67]
	v_mfma_f32_16x16x32_bf16 v[68:71], v[160:163], v[206:209], v[68:71]
	v_mfma_f32_16x16x32_bf16 v[118:121], v[164:167], v[180:183], v[118:121]
	v_mfma_f32_16x16x32_bf16 v[114:117], v[172:175], v[180:183], v[114:117]
	v_mfma_f32_16x16x32_bf16 v[98:101], v[172:175], v[188:191], v[98:101]
	v_mfma_f32_16x16x32_bf16 v[102:105], v[164:167], v[188:191], v[102:105]
	v_mfma_f32_16x16x32_bf16 v[84:87], v[164:167], v[202:205], v[84:87]
	v_mfma_f32_16x16x32_bf16 v[80:83], v[172:175], v[202:205], v[80:83]
	v_mfma_f32_16x16x32_bf16 v[64:67], v[172:175], v[210:213], v[64:67]
	v_mfma_f32_16x16x32_bf16 v[68:71], v[164:167], v[210:213], v[68:71]
	s_setprio 0
	s_barrier
; #define PG8_STAGE(bufoff, gbase, V0, V1) do { \
;         __builtin_amdgcn_global_load_lds((const unsigned*)((const char*)(gbase) + (V0)), (LAS unsigned*)(lds + (bufoff) + ldsw), 16, 0, 0); \
;         __builtin_amdgcn_global_load_lds((const unsigned*)((const char*)(gbase) + (V1)), (LAS unsigned*)(lds + (bufoff) + ldsw + 8192), 16, 0, 0); } while (0)
; #define PG8_LDA(dst, b, h) do { _Pragma("unroll") for (int m = 0; m < 4; ++m) _Pragma("unroll") for (int k = 0; k < 2; ++k) dst[m][k] = *(const LAS bf16x8*)(lds + PG8_SA(b, h) + aoff + m * 2048 + k * 1024); } while (0)
; #define PG8_MMA(ai, bj, At, Bt) do { __builtin_amdgcn_s_setprio(1); _Pragma("unroll") for (int m = 0; m < 4; ++m) _Pragma("unroll") for (int n = 0; n < 2; ++n) _Pragma("unroll") for (int k = 0; k < 2; ++k) \
;         acc[ai][bj][m][n] = __builtin_amdgcn_mfma_f32_16x16x32_bf16(Bt[n][k], At[m][k], acc[ai][bj][m][n], 0, 0, 0); __builtin_amdgcn_s_setprio(0); } while (0)
; #define PG8_WAIT_V(n) asm volatile("s_waitcnt vmcnt(" #n ")" ::: "memory")
; #define PG8_WAIT_L(n) asm volatile("s_waitcnt lgkmcnt(" #n ")" ::: "memory")
; #define PG8_BAR __builtin_amdgcn_s_barrier()
; #define PG8_SCHED __builtin_amdgcn_sched_barrier(0)
; template <class Epi, class Sched>
; DI void gemm_phase(LAS unsigned char* lds, const int lda2, const int ldb2, const int nt, const Sched& S, const Epi& E) {
;     ...
;             PG8_LDA(At, 1, 1); PG8_STAGE(PG8_SB(1, 0), b3, vB0, vB1); PG8_STAGE(PG8_SB(1, 1), b3 + hstepB, vB0, vB1); PG8_STAGE(PG8_SA(1, 0), a3, vA0, vA1);
;             PG8_WAIT_V(8); PG8_WAIT_L(0); PG8_BAR; PG8_MMA(1, 0, At, B0); PG8_MMA(1, 1, At, B1); PG8_BAR; PG8_SCHED;
;         }
;         if (wr == 0) PG8_BAR;
	s_add_i32 s24, s27, s54
	v_lshl_add_u64 v[214:215], v[214:215], 0, s[86:87]
	s_mov_b32 m0, s24
	ds_read_b128 v[176:179], v159 offset:49152
	ds_read_b128 v[180:183], v159 offset:50176
	ds_read_b128 v[184:187], v159 offset:51200
	ds_read_b128 v[188:191], v159 offset:52224
	ds_read_b128 v[192:195], v159 offset:53248
	ds_read_b128 v[202:205], v159 offset:54272
	ds_read_b128 v[206:209], v159 offset:55296
	ds_read_b128 v[210:213], v159 offset:56320
	global_load_lds_dwordx4 v[214:215], off
	s_add_i32 m0, s24, 0x2000
	s_add_u32 s22, s22, 0x40080
	v_lshl_add_u64 v[214:215], v[216:217], 0, s[86:87]
	s_addc_u32 s23, s23, 0
	s_add_i32 s24, s28, s54
	global_load_lds_dwordx4 v[214:215], off
	v_lshl_add_u64 v[214:215], s[22:23], 0, v[96:97]
	s_mov_b32 m0, s24
	s_nop 0
	global_load_lds_dwordx4 v[214:215], off
	v_lshl_add_u64 v[214:215], s[22:23], 0, v[130:131]
	s_add_i32 m0, s24, 0x2000
	s_nop 0
	global_load_lds_dwordx4 v[214:215], off
	v_lshl_add_u64 v[214:215], v[218:219], 0, s[86:87]
	s_mov_b32 m0, s77
	s_nop 0
	global_load_lds_dwordx4 v[214:215], off
	v_lshl_add_u64 v[214:215], v[220:221], 0, s[86:87]
	s_mov_b32 m0, s78
	s_nop 0
	global_load_lds_dwordx4 v[214:215], off
	s_waitcnt vmcnt(8)
	s_waitcnt lgkmcnt(0)
	s_barrier
	s_setprio 1
	s_waitcnt lgkmcnt(0)
	v_mfma_f32_16x16x32_bf16 v[60:63], v[140:143], v[176:179], v[60:63]
	v_mfma_f32_16x16x32_bf16 v[56:59], v[148:151], v[176:179], v[56:59]
	v_mfma_f32_16x16x32_bf16 v[40:43], v[148:151], v[184:187], v[40:43]
	v_mfma_f32_16x16x32_bf16 v[44:47], v[140:143], v[184:187], v[44:47]
	v_mfma_f32_16x16x32_bf16 v[28:31], v[140:143], v[192:195], v[28:31]
	v_mfma_f32_16x16x32_bf16 v[24:27], v[148:151], v[192:195], v[24:27]
	v_mfma_f32_16x16x32_bf16 v[8:11], v[148:151], v[206:209], v[8:11]
	v_mfma_f32_16x16x32_bf16 v[12:15], v[140:143], v[206:209], v[12:15]
	v_mfma_f32_16x16x32_bf16 v[60:63], v[144:147], v[180:183], v[60:63]
	v_mfma_f32_16x16x32_bf16 v[56:59], v[152:155], v[180:183], v[56:59]
	v_mfma_f32_16x16x32_bf16 v[40:43], v[152:155], v[188:191], v[40:43]
	v_mfma_f32_16x16x32_bf16 v[44:47], v[144:147], v[188:191], v[44:47]
	v_mfma_f32_16x16x32_bf16 v[28:31], v[144:147], v[202:205], v[28:31]
	v_mfma_f32_16x16x32_bf16 v[24:27], v[152:155], v[202:205], v[24:27]
	v_mfma_f32_16x16x32_bf16 v[8:11], v[152:155], v[210:213], v[8:11]
	v_mfma_f32_16x16x32_bf16 v[12:15], v[144:147], v[210:213], v[12:15]
	s_setprio 0
	s_setprio 1
	v_mfma_f32_16x16x32_bf16 v[52:55], v[160:163], v[176:179], v[52:55]
	v_mfma_f32_16x16x32_bf16 v[48:51], v[168:171], v[176:179], v[48:51]
	v_mfma_f32_16x16x32_bf16 v[32:35], v[168:171], v[184:187], v[32:35]
	v_mfma_f32_16x16x32_bf16 v[36:39], v[160:163], v[184:187], v[36:39]
	v_mfma_f32_16x16x32_bf16 v[20:23], v[160:163], v[192:195], v[20:23]
	v_mfma_f32_16x16x32_bf16 v[16:19], v[168:171], v[192:195], v[16:19]
	v_mfma_f32_16x16x32_bf16 v[0:3], v[168:171], v[206:209], v[0:3]
	v_mfma_f32_16x16x32_bf16 v[4:7], v[160:163], v[206:209], v[4:7]
	v_mfma_f32_16x16x32_bf16 v[52:55], v[164:167], v[180:183], v[52:55]
	v_mfma_f32_16x16x32_bf16 v[48:51], v[172:175], v[180:183], v[48:51]
	v_mfma_f32_16x16x32_bf16 v[32:35], v[172:175], v[188:191], v[32:35]
	v_mfma_f32_16x16x32_bf16 v[36:39], v[164:167], v[188:191], v[36:39]
	v_mfma_f32_16x16x32_bf16 v[20:23], v[164:167], v[202:205], v[20:23]
	v_mfma_f32_16x16x32_bf16 v[16:19], v[172:175], v[202:205], v[16:19]
	v_mfma_f32_16x16x32_bf16 v[0:3], v[172:175], v[210:213], v[0:3]
	v_mfma_f32_16x16x32_bf16 v[4:7], v[164:167], v[210:213], v[4:7]
	s_setprio 0
	s_barrier
	s_add_i32 s17, s17, 2
	s_add_u32 s4, s4, 0x100
	s_addc_u32 s5, s5, 0
	s_add_u32 s7, s7, 0x100
	s_addc_u32 s15, s15, 0
	s_cmp_gt_u32 s17, 13
	s_cbranch_scc0 .LBB0_199
	s_and_b64 vcc, exec, s[12:13]
	s_cbranch_vccz .LBB0_202
	s_barrier

; #define PG8_STAGE(bufoff, gbase, V0, V1) do { \
;         __builtin_amdgcn_global_load_lds((const unsigned*)((const char*)(gbase) + (V0)), (LAS unsigned*)(lds + (bufoff) + ldsw), 16, 0, 0); \
;         __builtin_amdgcn_global_load_lds((const unsigned*)((const char*)(gbase) + (V1)), (LAS unsigned*)(lds + (bufoff) + ldsw + 8192), 16, 0, 0); } while (0)
; #define PG8_LDA(dst, b, h) do { _Pragma("unroll") for (int m = 0; m < 4; ++m) _Pragma("unroll") for (int k = 0; k < 2; ++k) dst[m][k] = *(const LAS bf16x8*)(lds + PG8_SA(b, h) + aoff + m * 2048 + k * 1024); } while (0)
; #define PG8_LDB(dst, b, h) do { _Pragma("unroll") for (int n = 0; n < 2; ++n) _Pragma("unroll") for (int k = 0; k < 2; ++k) dst[n][k] = *(const LAS bf16x8*)(lds + PG8_SB(b, h) + boff + n * 2048 + k * 1024); } while (0)
; #define PG8_MMA(ai, bj, At, Bt) do { __builtin_amdgcn_s_setprio(1); _Pragma("unroll") for (int m = 0; m < 4; ++m) _Pragma("unroll") for (int n = 0; n < 2; ++n) _Pragma("unroll") for (int k = 0; k < 2; ++k) \
;         acc[ai][bj][m][n] = __builtin_amdgcn_mfma_f32_16x16x32_bf16(Bt[n][k], At[m][k], acc[ai][bj][m][n], 0, 0, 0); __builtin_amdgcn_s_setprio(0); } while (0)
; #define PG8_WAIT_V(n) asm volatile("s_waitcnt vmcnt(" #n ")" ::: "memory")
; #define PG8_WAIT_L(n) asm volatile("s_waitcnt lgkmcnt(" #n ")" ::: "memory")
; #define PG8_BAR __builtin_amdgcn_s_barrier()
; #define PG8_SCHED __builtin_amdgcn_sched_barrier(0)
; template <class Epi, class Sched>
; DI void gemm_phase(LAS unsigned char* lds, const int lda2, const int ldb2, const int nt, const Sched& S, const Epi& E) {
;     ...
;             PG8_LDB(B0, 0, 0); PG8_LDB(B1, 0, 1); PG8_SCHED; PG8_LDA(At, 0, 0); PG8_STAGE(PG8_SA(1, 1), a1 + hstepA, vA0, vA1);
;             PG8_WAIT_V(8); PG8_WAIT_L(0); PG8_BAR; PG8_MMA(0, 0, At, B0); PG8_MMA(0, 1, At, B1); PG8_BAR; PG8_SCHED;
;             PG8_LDA(At, 0, 1); PG8_STAGE(PG8_SB(0, 0), b2, vB0, vB1); PG8_STAGE(PG8_SB(0, 1), b2 + hstepB, vB0, vB1); PG8_STAGE(PG8_SA(0, 0), a2, vA0, vA1);
;             PG8_WAIT_V(8); PG8_WAIT_L(0); PG8_BAR; PG8_MMA(1, 0, At, B0); PG8_MMA(1, 1, At, B1); PG8_BAR; PG8_SCHED;
.LBB0_680:
	s_add_u32 s24, s6, 0xffe90080
	s_addc_u32 s25, s7, -1
	s_add_i32 s51, 0, 0x10000
	s_cmp_eq_u32 s50, 4
	s_cselect_b32 s27, s21, s25
	s_cselect_b32 s26, s20, s24
	v_add_u32_e32 v96, s51, v238
	s_cselect_b32 s25, s23, s49
	s_cselect_b32 s24, s22, s5
	s_add_i32 s85, 0, 0x14000
	v_lshl_add_u64 v[250:251], s[6:7], 0, v[210:211]
	s_add_i32 m0, s52, 0xc000
	s_nop 0
	global_load_lds_dwordx4 v[250:251], off
	v_lshl_add_u64 v[250:251], s[6:7], 0, v[212:213]
	s_add_i32 m0, s52, 0xe000
	s_nop 0
	global_load_lds_dwordx4 v[250:251], off
	ds_read_b128 v[132:135], v96
	ds_read_b128 v[136:139], v96 offset:1024
	ds_read_b128 v[140:143], v96 offset:2048
	ds_read_b128 v[144:147], v96 offset:3072
	v_add_u32_e32 v96, s85, v238
	ds_read_b128 v[148:151], v96
	ds_read_b128 v[152:155], v96 offset:1024
	ds_read_b128 v[156:159], v96 offset:2048
	ds_read_b128 v[160:163], v96 offset:3072
	ds_read_b128 v[164:167], v239
	ds_read_b128 v[168:171], v239 offset:1024
	ds_read_b128 v[172:175], v239 offset:2048
	ds_read_b128 v[176:179], v239 offset:3072
	ds_read_b128 v[180:183], v239 offset:4096
	ds_read_b128 v[184:187], v239 offset:5120
	ds_read_b128 v[188:191], v239 offset:6144
	ds_read_b128 v[192:195], v239 offset:7168
	s_waitcnt vmcnt(8)
	s_waitcnt lgkmcnt(0)
	s_barrier
	s_setprio 1
	s_waitcnt lgkmcnt(0)
	v_mfma_f32_16x16x32_bf16 v[128:131], v[132:135], v[164:167], v[128:131]
	v_mfma_f32_16x16x32_bf16 v[124:127], v[140:143], v[164:167], v[124:127]
	v_mfma_f32_16x16x32_bf16 v[116:119], v[140:143], v[172:175], v[116:119]
	v_mfma_f32_16x16x32_bf16 v[120:123], v[132:135], v[172:175], v[120:123]
	v_mfma_f32_16x16x32_bf16 v[112:115], v[132:135], v[180:183], v[112:115]
	v_mfma_f32_16x16x32_bf16 v[108:111], v[140:143], v[180:183], v[108:111]
	v_mfma_f32_16x16x32_bf16 v[98:101], v[140:143], v[188:191], v[100:103]
	v_mfma_f32_16x16x32_bf16 v[104:107], v[132:135], v[188:191], v[104:107]
	v_mfma_f32_16x16x32_bf16 v[128:131], v[136:139], v[168:171], v[128:131]
	v_mfma_f32_16x16x32_bf16 v[124:127], v[144:147], v[168:171], v[124:127]
	v_mfma_f32_16x16x32_bf16 v[116:119], v[144:147], v[176:179], v[116:119]
	v_mfma_f32_16x16x32_bf16 v[120:123], v[136:139], v[176:179], v[120:123]
	v_mfma_f32_16x16x32_bf16 v[112:115], v[136:139], v[184:187], v[112:115]
	v_mfma_f32_16x16x32_bf16 v[108:111], v[144:147], v[184:187], v[108:111]
	v_mfma_f32_16x16x32_bf16 v[98:101], v[144:147], v[192:195], v[98:101]
	v_mfma_f32_16x16x32_bf16 v[104:107], v[136:139], v[192:195], v[104:107]
	s_setprio 0
	s_setprio 1
	v_mfma_f32_16x16x32_bf16 v[92:95], v[148:151], v[164:167], v[92:95]
	v_mfma_f32_16x16x32_bf16 v[88:91], v[156:159], v[164:167], v[88:91]
	v_mfma_f32_16x16x32_bf16 v[80:83], v[156:159], v[172:175], v[80:83]
	v_mfma_f32_16x16x32_bf16 v[84:87], v[148:151], v[172:175], v[84:87]
	v_mfma_f32_16x16x32_bf16 v[76:79], v[148:151], v[180:183], v[76:79]
	v_mfma_f32_16x16x32_bf16 v[72:75], v[156:159], v[180:183], v[72:75]
	v_mfma_f32_16x16x32_bf16 v[64:67], v[156:159], v[188:191], v[64:67]
	v_mfma_f32_16x16x32_bf16 v[68:71], v[148:151], v[188:191], v[68:71]
	v_mfma_f32_16x16x32_bf16 v[92:95], v[152:155], v[168:171], v[92:95]
	v_mfma_f32_16x16x32_bf16 v[88:91], v[160:163], v[168:171], v[88:91]
	v_mfma_f32_16x16x32_bf16 v[80:83], v[160:163], v[176:179], v[80:83]
	v_mfma_f32_16x16x32_bf16 v[84:87], v[152:155], v[176:179], v[84:87]
	v_mfma_f32_16x16x32_bf16 v[76:79], v[152:155], v[184:187], v[76:79]
	v_mfma_f32_16x16x32_bf16 v[72:75], v[160:163], v[184:187], v[72:75]
	v_mfma_f32_16x16x32_bf16 v[64:67], v[160:163], v[192:195], v[64:67]
	v_mfma_f32_16x16x32_bf16 v[68:71], v[152:155], v[192:195], v[68:71]
	s_setprio 0
	s_barrier
	s_add_i32 s51, s51, s47
	v_lshl_add_u64 v[214:215], s[24:25], 0, v[202:203]
	s_mov_b32 m0, s51
	ds_read_b128 v[164:167], v239 offset:16384
	ds_read_b128 v[168:171], v239 offset:17408
	ds_read_b128 v[172:175], v239 offset:18432
	ds_read_b128 v[176:179], v239 offset:19456
	ds_read_b128 v[180:183], v239 offset:20480
	ds_read_b128 v[184:187], v239 offset:21504
	ds_read_b128 v[188:191], v239 offset:22528
	ds_read_b128 v[192:195], v239 offset:23552
	global_load_lds_dwordx4 v[214:215], off
	s_add_i32 m0, s51, 0x2000
	s_add_u32 s56, s24, 0x60000
	v_lshl_add_u64 v[216:217], s[24:25], 0, v[204:205]
	s_addc_u32 s57, s25, 0
	s_add_i32 s51, s85, s47
	global_load_lds_dwordx4 v[216:217], off
	v_lshl_add_u64 v[102:103], s[56:57], 0, v[202:203]
	s_mov_b32 m0, s51
	v_lshl_add_u64 v[218:219], s[26:27], 0, v[206:207]
	global_load_lds_dwordx4 v[102:103], off
	v_lshl_add_u64 v[102:103], s[56:57], 0, v[204:205]
	s_add_i32 m0, s51, 0x2000
	v_lshl_add_u64 v[220:221], s[26:27], 0, v[208:209]
	global_load_lds_dwordx4 v[102:103], off
	s_mov_b32 m0, s52
	s_nop 0
	global_load_lds_dwordx4 v[218:219], off
	s_mov_b32 m0, s53
	s_nop 0
	global_load_lds_dwordx4 v[220:221], off
	s_waitcnt vmcnt(8)
	s_waitcnt lgkmcnt(0)
	s_barrier
; #define PG8_STAGE(bufoff, gbase, V0, V1) do { \
;         __builtin_amdgcn_global_load_lds((const unsigned*)((const char*)(gbase) + (V0)), (LAS unsigned*)(lds + (bufoff) + ldsw), 16, 0, 0); \
;         __builtin_amdgcn_global_load_lds((const unsigned*)((const char*)(gbase) + (V1)), (LAS unsigned*)(lds + (bufoff) + ldsw + 8192), 16, 0, 0); } while (0)
; #define PG8_LDA(dst, b, h) do { _Pragma("unroll") for (int m = 0; m < 4; ++m) _Pragma("unroll") for (int k = 0; k < 2; ++k) dst[m][k] = *(const LAS bf16x8*)(lds + PG8_SA(b, h) + aoff + m * 2048 + k * 1024); } while (0)
; #define PG8_LDB(dst, b, h) do { _Pragma("unroll") for (int n = 0; n < 2; ++n) _Pragma("unroll") for (int k = 0; k < 2; ++k) dst[n][k] = *(const LAS bf16x8*)(lds + PG8_SB(b, h) + boff + n * 2048 + k * 1024); } while (0)
; #define PG8_MMA(ai, bj, At, Bt) do { __builtin_amdgcn_s_setprio(1); _Pragma("unroll") for (int m = 0; m < 4; ++m) _Pragma("unroll") for (int n = 0; n < 2; ++n) _Pragma("unroll") for (int k = 0; k < 2; ++k) \
;         acc[ai][bj][m][n] = __builtin_amdgcn_mfma_f32_16x16x32_bf16(Bt[n][k], At[m][k], acc[ai][bj][m][n], 0, 0, 0); __builtin_amdgcn_s_setprio(0); } while (0)
; #define PG8_WAIT_V(n) asm volatile("s_waitcnt vmcnt(" #n ")" ::: "memory")
; #define PG8_WAIT_L(n) asm volatile("s_waitcnt lgkmcnt(" #n ")" ::: "memory")
; #define PG8_BAR __builtin_amdgcn_s_barrier()
; #define PG8_SCHED __builtin_amdgcn_sched_barrier(0)
; template <class Epi, class Sched>
; DI void gemm_phase(LAS unsigned char* lds, const int lda2, const int ldb2, const int nt, const Sched& S, const Epi& E) {
;     ...
;             PG8_WAIT_V(8); PG8_WAIT_L(0); PG8_BAR; PG8_MMA(1, 0, At, B0); PG8_MMA(1, 1, At, B1); PG8_BAR; PG8_SCHED;
;             PG8_LDB(B0, 1, 0); PG8_LDB(B1, 1, 1); PG8_SCHED; PG8_LDA(At, 1, 0); PG8_STAGE(PG8_SA(0, 1), a2 + hstepA, vA0, vA1);
;             PG8_WAIT_V(8); PG8_WAIT_L(0); PG8_BAR; PG8_MMA(0, 0, At, B0); PG8_MMA(0, 1, At, B1); PG8_BAR; PG8_SCHED;
	s_setprio 1
	s_waitcnt lgkmcnt(0)
	v_mfma_f32_16x16x32_bf16 v[60:63], v[132:135], v[164:167], v[60:63]
	v_mfma_f32_16x16x32_bf16 v[56:59], v[140:143], v[164:167], v[56:59]
	v_mfma_f32_16x16x32_bf16 v[48:51], v[140:143], v[172:175], v[48:51]
	v_mfma_f32_16x16x32_bf16 v[52:55], v[132:135], v[172:175], v[52:55]
	v_mfma_f32_16x16x32_bf16 v[44:47], v[132:135], v[180:183], v[44:47]
	v_mfma_f32_16x16x32_bf16 v[40:43], v[140:143], v[180:183], v[40:43]
	v_mfma_f32_16x16x32_bf16 v[32:35], v[140:143], v[188:191], v[32:35]
	v_mfma_f32_16x16x32_bf16 v[36:39], v[132:135], v[188:191], v[36:39]
	v_mfma_f32_16x16x32_bf16 v[60:63], v[136:139], v[168:171], v[60:63]
	v_mfma_f32_16x16x32_bf16 v[56:59], v[144:147], v[168:171], v[56:59]
	v_mfma_f32_16x16x32_bf16 v[48:51], v[144:147], v[176:179], v[48:51]
	v_mfma_f32_16x16x32_bf16 v[52:55], v[136:139], v[176:179], v[52:55]
	v_mfma_f32_16x16x32_bf16 v[44:47], v[136:139], v[184:187], v[44:47]
	v_mfma_f32_16x16x32_bf16 v[40:43], v[144:147], v[184:187], v[40:43]
	v_mfma_f32_16x16x32_bf16 v[32:35], v[144:147], v[192:195], v[32:35]
	v_mfma_f32_16x16x32_bf16 v[36:39], v[136:139], v[192:195], v[36:39]
	s_setprio 0
	s_setprio 1
	v_mfma_f32_16x16x32_bf16 v[28:31], v[148:151], v[164:167], v[28:31]
	v_mfma_f32_16x16x32_bf16 v[24:27], v[156:159], v[164:167], v[24:27]
	v_mfma_f32_16x16x32_bf16 v[16:19], v[156:159], v[172:175], v[16:19]
	v_mfma_f32_16x16x32_bf16 v[20:23], v[148:151], v[172:175], v[20:23]
	v_mfma_f32_16x16x32_bf16 v[12:15], v[148:151], v[180:183], v[12:15]
	v_mfma_f32_16x16x32_bf16 v[8:11], v[156:159], v[180:183], v[8:11]
	v_mfma_f32_16x16x32_bf16 v[0:3], v[156:159], v[188:191], v[0:3]
	v_mfma_f32_16x16x32_bf16 v[4:7], v[148:151], v[188:191], v[4:7]
	v_mfma_f32_16x16x32_bf16 v[28:31], v[152:155], v[168:171], v[28:31]
	v_mfma_f32_16x16x32_bf16 v[24:27], v[160:163], v[168:171], v[24:27]
	v_mfma_f32_16x16x32_bf16 v[16:19], v[160:163], v[176:179], v[16:19]
	v_mfma_f32_16x16x32_bf16 v[20:23], v[152:155], v[176:179], v[20:23]
	v_mfma_f32_16x16x32_bf16 v[12:15], v[152:155], v[184:187], v[12:15]
	v_mfma_f32_16x16x32_bf16 v[8:11], v[160:163], v[184:187], v[8:11]
	v_mfma_f32_16x16x32_bf16 v[0:3], v[160:163], v[192:195], v[0:3]
	v_mfma_f32_16x16x32_bf16 v[4:7], v[152:155], v[192:195], v[4:7]
	s_setprio 0
	s_barrier
	s_add_i32 s51, 0, 0x18000
	v_add_u32_e32 v96, s51, v238
	s_add_i32 s56, 0, 0x1c000
	s_add_u32 s26, s26, 0x170000
	s_addc_u32 s27, s27, 0
	s_mov_b32 m0, s55
	v_lshl_add_u64 v[250:251], s[26:27], 0, v[206:207]
	s_nop 0
	global_load_lds_dwordx4 v[250:251], off
	v_lshl_add_u64 v[250:251], s[26:27], 0, v[208:209]
	s_mov_b32 m0, s72
	s_nop 0
	global_load_lds_dwordx4 v[250:251], off
	ds_read_b128 v[132:135], v96
	ds_read_b128 v[136:139], v96 offset:1024
	ds_read_b128 v[140:143], v96 offset:2048
	ds_read_b128 v[144:147], v96 offset:3072
	v_add_u32_e32 v96, s56, v238
	ds_read_b128 v[148:151], v96
	ds_read_b128 v[152:155], v96 offset:1024
	ds_read_b128 v[156:159], v96 offset:2048
	ds_read_b128 v[160:163], v96 offset:3072
	ds_read_b128 v[164:167], v239 offset:32768
	ds_read_b128 v[168:171], v239 offset:33792
	ds_read_b128 v[172:175], v239 offset:34816
	ds_read_b128 v[176:179], v239 offset:35840
	ds_read_b128 v[180:183], v239 offset:36864
	ds_read_b128 v[184:187], v239 offset:37888
	ds_read_b128 v[188:191], v239 offset:38912
	ds_read_b128 v[192:195], v239 offset:39936
	s_waitcnt vmcnt(8)
	s_waitcnt lgkmcnt(0)
	s_barrier
	s_setprio 1
	s_waitcnt lgkmcnt(0)
	v_mfma_f32_16x16x32_bf16 v[128:131], v[132:135], v[164:167], v[128:131]
	v_mfma_f32_16x16x32_bf16 v[124:127], v[140:143], v[164:167], v[124:127]
	v_mfma_f32_16x16x32_bf16 v[116:119], v[140:143], v[172:175], v[116:119]
	v_mfma_f32_16x16x32_bf16 v[120:123], v[132:135], v[172:175], v[120:123]
	v_mfma_f32_16x16x32_bf16 v[112:115], v[132:135], v[180:183], v[112:115]
	v_mfma_f32_16x16x32_bf16 v[108:111], v[140:143], v[180:183], v[108:111]
	v_mfma_f32_16x16x32_bf16 v[98:101], v[140:143], v[188:191], v[98:101]
	v_mfma_f32_16x16x32_bf16 v[102:105], v[132:135], v[188:191], v[104:107]
	v_mfma_f32_16x16x32_bf16 v[128:131], v[136:139], v[168:171], v[128:131]
	v_mfma_f32_16x16x32_bf16 v[124:127], v[144:147], v[168:171], v[124:127]
	v_mfma_f32_16x16x32_bf16 v[116:119], v[144:147], v[176:179], v[116:119]
	v_mfma_f32_16x16x32_bf16 v[120:123], v[136:139], v[176:179], v[120:123]
	v_mfma_f32_16x16x32_bf16 v[112:115], v[136:139], v[184:187], v[112:115]
	v_mfma_f32_16x16x32_bf16 v[108:111], v[144:147], v[184:187], v[108:111]
	v_mfma_f32_16x16x32_bf16 v[100:103], v[144:147], v[192:195], v[98:101]
	v_mfma_f32_16x16x32_bf16 v[104:107], v[136:139], v[192:195], v[102:105]
	s_setprio 0
	s_setprio 1
	v_mfma_f32_16x16x32_bf16 v[92:95], v[148:151], v[164:167], v[92:95]
	v_mfma_f32_16x16x32_bf16 v[88:91], v[156:159], v[164:167], v[88:91]
	v_mfma_f32_16x16x32_bf16 v[80:83], v[156:159], v[172:175], v[80:83]
	v_mfma_f32_16x16x32_bf16 v[84:87], v[148:151], v[172:175], v[84:87]
	v_mfma_f32_16x16x32_bf16 v[76:79], v[148:151], v[180:183], v[76:79]
	v_mfma_f32_16x16x32_bf16 v[72:75], v[156:159], v[180:183], v[72:75]
	v_mfma_f32_16x16x32_bf16 v[64:67], v[156:159], v[188:191], v[64:67]
	v_mfma_f32_16x16x32_bf16 v[68:71], v[148:151], v[188:191], v[68:71]
	v_mfma_f32_16x16x32_bf16 v[92:95], v[152:155], v[168:171], v[92:95]
	v_mfma_f32_16x16x32_bf16 v[88:91], v[160:163], v[168:171], v[88:91]
	v_mfma_f32_16x16x32_bf16 v[80:83], v[160:163], v[176:179], v[80:83]
	v_mfma_f32_16x16x32_bf16 v[84:87], v[152:155], v[176:179], v[84:87]
	v_mfma_f32_16x16x32_bf16 v[76:79], v[152:155], v[184:187], v[76:79]
	v_mfma_f32_16x16x32_bf16 v[72:75], v[160:163], v[184:187], v[72:75]
	v_mfma_f32_16x16x32_bf16 v[64:67], v[160:163], v[192:195], v[64:67]
	v_mfma_f32_16x16x32_bf16 v[68:71], v[152:155], v[192:195], v[68:71]
	s_setprio 0
	s_barrier
; #define PG8_STAGE(bufoff, gbase, V0, V1) do { \
;         __builtin_amdgcn_global_load_lds((const unsigned*)((const char*)(gbase) + (V0)), (LAS unsigned*)(lds + (bufoff) + ldsw), 16, 0, 0); \
;         __builtin_amdgcn_global_load_lds((const unsigned*)((const char*)(gbase) + (V1)), (LAS unsigned*)(lds + (bufoff) + ldsw + 8192), 16, 0, 0); } while (0)
; #define PG8_LDA(dst, b, h) do { _Pragma("unroll") for (int m = 0; m < 4; ++m) _Pragma("unroll") for (int k = 0; k < 2; ++k) dst[m][k] = *(const LAS bf16x8*)(lds + PG8_SA(b, h) + aoff + m * 2048 + k * 1024); } while (0)
; #define PG8_MMA(ai, bj, At, Bt) do { __builtin_amdgcn_s_setprio(1); _Pragma("unroll") for (int m = 0; m < 4; ++m) _Pragma("unroll") for (int n = 0; n < 2; ++n) _Pragma("unroll") for (int k = 0; k < 2; ++k) \
;         acc[ai][bj][m][n] = __builtin_amdgcn_mfma_f32_16x16x32_bf16(Bt[n][k], At[m][k], acc[ai][bj][m][n], 0, 0, 0); __builtin_amdgcn_s_setprio(0); } while (0)
; #define PG8_WAIT_V(n) asm volatile("s_waitcnt vmcnt(" #n ")" ::: "memory")
; #define PG8_WAIT_L(n) asm volatile("s_waitcnt lgkmcnt(" #n ")" ::: "memory")
; #define PG8_BAR __builtin_amdgcn_s_barrier()
; #define PG8_SCHED __builtin_amdgcn_sched_barrier(0)
; template <class Epi, class Sched>
; DI void gemm_phase(LAS unsigned char* lds, const int lda2, const int ldb2, const int nt, const Sched& S, const Epi& E) {
;     ...
;             PG8_LDA(At, 1, 1); PG8_STAGE(PG8_SB(1, 0), b3, vB0, vB1); PG8_STAGE(PG8_SB(1, 1), b3 + hstepB, vB0, vB1); PG8_STAGE(PG8_SA(1, 0), a3, vA0, vA1);
;             PG8_WAIT_V(8); PG8_WAIT_L(0); PG8_BAR; PG8_MMA(1, 0, At, B0); PG8_MMA(1, 1, At, B1); PG8_BAR; PG8_SCHED;
;         }
;         if (wr == 0) PG8_BAR;
	s_add_i32 s26, s51, s47
	v_lshl_add_u64 v[98:99], v[214:215], 0, s[86:87]
	s_mov_b32 m0, s26
	ds_read_b128 v[164:167], v239 offset:49152
	ds_read_b128 v[168:171], v239 offset:50176
	ds_read_b128 v[172:175], v239 offset:51200
	ds_read_b128 v[176:179], v239 offset:52224
	ds_read_b128 v[180:183], v239 offset:53248
	ds_read_b128 v[184:187], v239 offset:54272
	ds_read_b128 v[188:191], v239 offset:55296
	ds_read_b128 v[192:195], v239 offset:56320
	global_load_lds_dwordx4 v[98:99], off
	s_add_i32 m0, s26, 0x2000
	s_add_u32 s24, s24, 0x60080
	v_lshl_add_u64 v[98:99], v[216:217], 0, s[86:87]
	s_addc_u32 s25, s25, 0
	s_add_i32 s26, s56, s47
	global_load_lds_dwordx4 v[98:99], off
	v_lshl_add_u64 v[98:99], s[24:25], 0, v[202:203]
	s_mov_b32 m0, s26
	s_nop 0
	global_load_lds_dwordx4 v[98:99], off
	v_lshl_add_u64 v[98:99], s[24:25], 0, v[204:205]
	s_add_i32 m0, s26, 0x2000
	s_nop 0
	global_load_lds_dwordx4 v[98:99], off
	v_lshl_add_u64 v[98:99], v[218:219], 0, s[86:87]
	s_mov_b32 m0, s75
	s_nop 0
	global_load_lds_dwordx4 v[98:99], off
	v_lshl_add_u64 v[98:99], v[220:221], 0, s[86:87]
	s_mov_b32 m0, s76
	s_nop 0
	global_load_lds_dwordx4 v[98:99], off
	s_waitcnt vmcnt(8)
	s_waitcnt lgkmcnt(0)
	s_barrier
	s_setprio 1
	s_waitcnt lgkmcnt(0)
	v_mfma_f32_16x16x32_bf16 v[60:63], v[132:135], v[164:167], v[60:63]
	v_mfma_f32_16x16x32_bf16 v[56:59], v[140:143], v[164:167], v[56:59]
	v_mfma_f32_16x16x32_bf16 v[48:51], v[140:143], v[172:175], v[48:51]
	v_mfma_f32_16x16x32_bf16 v[52:55], v[132:135], v[172:175], v[52:55]
	v_mfma_f32_16x16x32_bf16 v[44:47], v[132:135], v[180:183], v[44:47]
	v_mfma_f32_16x16x32_bf16 v[40:43], v[140:143], v[180:183], v[40:43]
	v_mfma_f32_16x16x32_bf16 v[32:35], v[140:143], v[188:191], v[32:35]
	v_mfma_f32_16x16x32_bf16 v[36:39], v[132:135], v[188:191], v[36:39]
	v_mfma_f32_16x16x32_bf16 v[60:63], v[136:139], v[168:171], v[60:63]
	v_mfma_f32_16x16x32_bf16 v[56:59], v[144:147], v[168:171], v[56:59]
	v_mfma_f32_16x16x32_bf16 v[48:51], v[144:147], v[176:179], v[48:51]
	v_mfma_f32_16x16x32_bf16 v[52:55], v[136:139], v[176:179], v[52:55]
	v_mfma_f32_16x16x32_bf16 v[44:47], v[136:139], v[184:187], v[44:47]
	v_mfma_f32_16x16x32_bf16 v[40:43], v[144:147], v[184:187], v[40:43]
	v_mfma_f32_16x16x32_bf16 v[32:35], v[144:147], v[192:195], v[32:35]
	v_mfma_f32_16x16x32_bf16 v[36:39], v[136:139], v[192:195], v[36:39]
	s_setprio 0
	s_setprio 1
	v_mfma_f32_16x16x32_bf16 v[28:31], v[148:151], v[164:167], v[28:31]
	v_mfma_f32_16x16x32_bf16 v[24:27], v[156:159], v[164:167], v[24:27]
	v_mfma_f32_16x16x32_bf16 v[16:19], v[156:159], v[172:175], v[16:19]
	v_mfma_f32_16x16x32_bf16 v[20:23], v[148:151], v[172:175], v[20:23]
	v_mfma_f32_16x16x32_bf16 v[12:15], v[148:151], v[180:183], v[12:15]
	v_mfma_f32_16x16x32_bf16 v[8:11], v[156:159], v[180:183], v[8:11]
	v_mfma_f32_16x16x32_bf16 v[0:3], v[156:159], v[188:191], v[0:3]
	v_mfma_f32_16x16x32_bf16 v[4:7], v[148:151], v[188:191], v[4:7]
	v_mfma_f32_16x16x32_bf16 v[28:31], v[152:155], v[168:171], v[28:31]
	v_mfma_f32_16x16x32_bf16 v[24:27], v[160:163], v[168:171], v[24:27]
	v_mfma_f32_16x16x32_bf16 v[16:19], v[160:163], v[176:179], v[16:19]
	v_mfma_f32_16x16x32_bf16 v[20:23], v[152:155], v[176:179], v[20:23]
	v_mfma_f32_16x16x32_bf16 v[12:15], v[152:155], v[184:187], v[12:15]
	v_mfma_f32_16x16x32_bf16 v[8:11], v[160:163], v[184:187], v[8:11]
	v_mfma_f32_16x16x32_bf16 v[0:3], v[160:163], v[192:195], v[0:3]
	v_mfma_f32_16x16x32_bf16 v[4:7], v[152:155], v[192:195], v[4:7]
	s_setprio 0
	s_barrier
	s_add_i32 s50, s50, 2
	s_add_u32 s6, s6, 0x100
	s_addc_u32 s7, s7, 0
	s_add_u32 s5, s5, 0x100
	s_addc_u32 s49, s49, 0
	s_cmp_gt_u32 s50, 5
	s_cbranch_scc0 .LBB0_680
	s_and_b64 vcc, exec, s[18:19]
	s_cbranch_vccz .LBB0_683
	s_barrier

; #define PG8_STAGE(bufoff, gbase, V0, V1) do { \
;         __builtin_amdgcn_global_load_lds((const unsigned*)((const char*)(gbase) + (V0)), (LAS unsigned*)(lds + (bufoff) + ldsw), 16, 0, 0); \
;         __builtin_amdgcn_global_load_lds((const unsigned*)((const char*)(gbase) + (V1)), (LAS unsigned*)(lds + (bufoff) + ldsw + 8192), 16, 0, 0); } while (0)
; #define PG8_LDA(dst, b, h) do { _Pragma("unroll") for (int m = 0; m < 4; ++m) _Pragma("unroll") for (int k = 0; k < 2; ++k) dst[m][k] = *(const LAS bf16x8*)(lds + PG8_SA(b, h) + aoff + m * 2048 + k * 1024); } while (0)
; #define PG8_LDB(dst, b, h) do { _Pragma("unroll") for (int n = 0; n < 2; ++n) _Pragma("unroll") for (int k = 0; k < 2; ++k) dst[n][k] = *(const LAS bf16x8*)(lds + PG8_SB(b, h) + boff + n * 2048 + k * 1024); } while (0)
; #define PG8_MMA(ai, bj, At, Bt) do { __builtin_amdgcn_s_setprio(1); _Pragma("unroll") for (int m = 0; m < 4; ++m) _Pragma("unroll") for (int n = 0; n < 2; ++n) _Pragma("unroll") for (int k = 0; k < 2; ++k) \
;         acc[ai][bj][m][n] = __builtin_amdgcn_mfma_f32_16x16x32_bf16(Bt[n][k], At[m][k], acc[ai][bj][m][n], 0, 0, 0); __builtin_amdgcn_s_setprio(0); } while (0)
; #define PG8_WAIT_V(n) asm volatile("s_waitcnt vmcnt(" #n ")" ::: "memory")
; #define PG8_WAIT_L(n) asm volatile("s_waitcnt lgkmcnt(" #n ")" ::: "memory")
; #define PG8_BAR __builtin_amdgcn_s_barrier()
; #define PG8_SCHED __builtin_amdgcn_sched_barrier(0)
; template <class Epi, class Sched>
; DI void gemm_phase(LAS unsigned char* lds, const int lda2, const int ldb2, const int nt, const Sched& S, const Epi& E) {
;     ...
;             PG8_LDB(B0, 0, 0); PG8_LDB(B1, 0, 1); PG8_SCHED; PG8_LDA(At, 0, 0); PG8_STAGE(PG8_SA(1, 1), a1 + hstepA, vA0, vA1);
;             PG8_WAIT_V(8); PG8_WAIT_L(0); PG8_BAR; PG8_MMA(0, 0, At, B0); PG8_MMA(0, 1, At, B1); PG8_BAR; PG8_SCHED;
;             PG8_LDA(At, 0, 1); PG8_STAGE(PG8_SB(0, 0), b2, vB0, vB1); PG8_STAGE(PG8_SB(0, 1), b2 + hstepB, vB0, vB1); PG8_STAGE(PG8_SA(0, 0), a2, vA0, vA1);
;             PG8_WAIT_V(8); PG8_WAIT_L(0); PG8_BAR; PG8_MMA(1, 0, At, B0); PG8_MMA(1, 1, At, B1); PG8_BAR; PG8_SCHED;
.LBB0_905:
	s_add_u32 s26, s26, 0x170080
	s_addc_u32 s27, s27, 0
	s_add_u32 s1, s28, 0x100
	s_addc_u32 s10, s29, 0
	s_mov_b32 s21, -2
	s_waitcnt lgkmcnt(0)
	s_add_u32 s28, s26, 0xffe90080
	s_addc_u32 s29, s27, -1
	s_add_i32 s56, 0, 0x10000
	s_cmp_eq_u32 s21, 12
	s_cselect_b32 s31, s23, s29
	s_cselect_b32 s30, s22, s28
	v_add_u32_e32 v144, s56, v148
	s_cselect_b32 s29, s25, s10
	s_cselect_b32 s28, s24, s1
	s_add_i32 vcc_lo, 0, 0x14000
	v_lshl_add_u64 v[250:251], s[26:27], 0, v[136:137]
	s_add_i32 m0, s74, 0xc000
	s_nop 0
	global_load_lds_dwordx4 v[250:251], off
	v_lshl_add_u64 v[250:251], s[26:27], 0, v[138:139]
	s_add_i32 m0, s74, 0xe000
	s_nop 0
	global_load_lds_dwordx4 v[250:251], off
	ds_read_b128 v[140:143], v144
	ds_read_b128 v[150:153], v144 offset:1024
	ds_read_b128 v[154:157], v144 offset:2048
	ds_read_b128 v[158:161], v144 offset:3072
	v_add_u32_e32 v144, vcc_lo, v148
	ds_read_b128 v[162:165], v144
	ds_read_b128 v[166:169], v144 offset:1024
	ds_read_b128 v[170:173], v144 offset:2048
	ds_read_b128 v[174:177], v144 offset:3072
	ds_read_b128 v[178:181], v149
	ds_read_b128 v[182:185], v149 offset:1024
	ds_read_b128 v[186:189], v149 offset:2048
	ds_read_b128 v[190:193], v149 offset:3072
	ds_read_b128 v[202:205], v149 offset:4096
	ds_read_b128 v[206:209], v149 offset:5120
	ds_read_b128 v[210:213], v149 offset:6144
	ds_read_b128 v[214:217], v149 offset:7168
	s_waitcnt vmcnt(8)
	s_waitcnt lgkmcnt(0)
	s_barrier
	s_setprio 1
	s_waitcnt lgkmcnt(0)
	v_mfma_f32_16x16x32_bf16 v[126:129], v[140:143], v[178:181], 0
	v_mfma_f32_16x16x32_bf16 v[122:125], v[154:157], v[178:181], 0
	v_mfma_f32_16x16x32_bf16 v[106:109], v[154:157], v[186:189], 0
	v_mfma_f32_16x16x32_bf16 v[110:113], v[140:143], v[186:189], 0
	v_mfma_f32_16x16x32_bf16 v[92:95], v[140:143], v[202:205], 0
	v_mfma_f32_16x16x32_bf16 v[88:91], v[154:157], v[202:205], 0
	v_mfma_f32_16x16x32_bf16 v[72:75], v[154:157], v[210:213], 0
	v_mfma_f32_16x16x32_bf16 v[76:79], v[140:143], v[210:213], 0
	v_mfma_f32_16x16x32_bf16 v[126:129], v[150:153], v[182:185], v[126:129]
	v_mfma_f32_16x16x32_bf16 v[122:125], v[158:161], v[182:185], v[122:125]
	v_mfma_f32_16x16x32_bf16 v[106:109], v[158:161], v[190:193], v[106:109]
	v_mfma_f32_16x16x32_bf16 v[110:113], v[150:153], v[190:193], v[110:113]
	v_mfma_f32_16x16x32_bf16 v[92:95], v[150:153], v[206:209], v[92:95]
	v_mfma_f32_16x16x32_bf16 v[88:91], v[158:161], v[206:209], v[88:91]
	v_mfma_f32_16x16x32_bf16 v[72:75], v[158:161], v[214:217], v[72:75]
	v_mfma_f32_16x16x32_bf16 v[76:79], v[150:153], v[214:217], v[76:79]
	s_setprio 0
	s_setprio 1
	v_mfma_f32_16x16x32_bf16 v[118:121], v[162:165], v[178:181], 0
	v_mfma_f32_16x16x32_bf16 v[114:117], v[170:173], v[178:181], 0
	v_mfma_f32_16x16x32_bf16 v[98:101], v[170:173], v[186:189], 0
	v_mfma_f32_16x16x32_bf16 v[102:105], v[162:165], v[186:189], 0
	v_mfma_f32_16x16x32_bf16 v[84:87], v[162:165], v[202:205], 0
	v_mfma_f32_16x16x32_bf16 v[80:83], v[170:173], v[202:205], 0
	v_mfma_f32_16x16x32_bf16 v[64:67], v[170:173], v[210:213], 0
	v_mfma_f32_16x16x32_bf16 v[68:71], v[162:165], v[210:213], 0
	v_mfma_f32_16x16x32_bf16 v[118:121], v[166:169], v[182:185], v[118:121]
	v_mfma_f32_16x16x32_bf16 v[114:117], v[174:177], v[182:185], v[114:117]
	v_mfma_f32_16x16x32_bf16 v[98:101], v[174:177], v[190:193], v[98:101]
	v_mfma_f32_16x16x32_bf16 v[102:105], v[166:169], v[190:193], v[102:105]
	v_mfma_f32_16x16x32_bf16 v[84:87], v[166:169], v[206:209], v[84:87]
	v_mfma_f32_16x16x32_bf16 v[80:83], v[174:177], v[206:209], v[80:83]
	v_mfma_f32_16x16x32_bf16 v[64:67], v[174:177], v[214:217], v[64:67]
	v_mfma_f32_16x16x32_bf16 v[68:71], v[166:169], v[214:217], v[68:71]
	s_setprio 0
	s_barrier
	s_add_i32 s56, s56, s73
	v_lshl_add_u64 v[144:145], s[28:29], 0, v[96:97]
	s_mov_b32 m0, s56
	ds_read_b128 v[178:181], v149 offset:16384
	ds_read_b128 v[182:185], v149 offset:17408
	ds_read_b128 v[186:189], v149 offset:18432
	ds_read_b128 v[190:193], v149 offset:19456
	ds_read_b128 v[202:205], v149 offset:20480
	ds_read_b128 v[206:209], v149 offset:21504
	ds_read_b128 v[210:213], v149 offset:22528
	ds_read_b128 v[214:217], v149 offset:23552
	global_load_lds_dwordx4 v[144:145], off
	s_add_i32 m0, s56, 0x2000
	s_add_u32 s56, s28, 0x40000
	v_lshl_add_u64 v[194:195], s[28:29], 0, v[130:131]
	s_addc_u32 s57, s29, 0
	s_add_i32 vcc_lo, vcc_lo, s73
	global_load_lds_dwordx4 v[194:195], off
	v_lshl_add_u64 v[218:219], s[56:57], 0, v[96:97]
	s_mov_b32 m0, vcc_lo
	v_lshl_add_u64 v[220:221], s[30:31], 0, v[134:135]
	global_load_lds_dwordx4 v[218:219], off
	v_lshl_add_u64 v[218:219], s[56:57], 0, v[130:131]
	s_add_i32 m0, vcc_lo, 0x2000
	s_nop 0
	global_load_lds_dwordx4 v[218:219], off
	v_lshl_add_u64 v[218:219], s[30:31], 0, v[132:133]
	s_mov_b32 m0, s74
	s_nop 0
	global_load_lds_dwordx4 v[218:219], off
	s_mov_b32 m0, s75
	s_nop 0
	global_load_lds_dwordx4 v[220:221], off
	s_waitcnt vmcnt(8)
	s_waitcnt lgkmcnt(0)
	s_barrier
; #define PG8_STAGE(bufoff, gbase, V0, V1) do { \
;         __builtin_amdgcn_global_load_lds((const unsigned*)((const char*)(gbase) + (V0)), (LAS unsigned*)(lds + (bufoff) + ldsw), 16, 0, 0); \
;         __builtin_amdgcn_global_load_lds((const unsigned*)((const char*)(gbase) + (V1)), (LAS unsigned*)(lds + (bufoff) + ldsw + 8192), 16, 0, 0); } while (0)
; #define PG8_LDA(dst, b, h) do { _Pragma("unroll") for (int m = 0; m < 4; ++m) _Pragma("unroll") for (int k = 0; k < 2; ++k) dst[m][k] = *(const LAS bf16x8*)(lds + PG8_SA(b, h) + aoff + m * 2048 + k * 1024); } while (0)
; #define PG8_LDB(dst, b, h) do { _Pragma("unroll") for (int n = 0; n < 2; ++n) _Pragma("unroll") for (int k = 0; k < 2; ++k) dst[n][k] = *(const LAS bf16x8*)(lds + PG8_SB(b, h) + boff + n * 2048 + k * 1024); } while (0)
; #define PG8_MMA(ai, bj, At, Bt) do { __builtin_amdgcn_s_setprio(1); _Pragma("unroll") for (int m = 0; m < 4; ++m) _Pragma("unroll") for (int n = 0; n < 2; ++n) _Pragma("unroll") for (int k = 0; k < 2; ++k) \
;         acc[ai][bj][m][n] = __builtin_amdgcn_mfma_f32_16x16x32_bf16(Bt[n][k], At[m][k], acc[ai][bj][m][n], 0, 0, 0); __builtin_amdgcn_s_setprio(0); } while (0)
; #define PG8_WAIT_V(n) asm volatile("s_waitcnt vmcnt(" #n ")" ::: "memory")
; #define PG8_WAIT_L(n) asm volatile("s_waitcnt lgkmcnt(" #n ")" ::: "memory")
; #define PG8_BAR __builtin_amdgcn_s_barrier()
; #define PG8_SCHED __builtin_amdgcn_sched_barrier(0)
; template <class Epi, class Sched>
; DI void gemm_phase(LAS unsigned char* lds, const int lda2, const int ldb2, const int nt, const Sched& S, const Epi& E) {
;     ...
;             PG8_WAIT_V(8); PG8_WAIT_L(0); PG8_BAR; PG8_MMA(1, 0, At, B0); PG8_MMA(1, 1, At, B1); PG8_BAR; PG8_SCHED;
;             PG8_LDB(B0, 1, 0); PG8_LDB(B1, 1, 1); PG8_SCHED; PG8_LDA(At, 1, 0); PG8_STAGE(PG8_SA(0, 1), a2 + hstepA, vA0, vA1);
;             PG8_WAIT_V(8); PG8_WAIT_L(0); PG8_BAR; PG8_MMA(0, 0, At, B0); PG8_MMA(0, 1, At, B1); PG8_BAR; PG8_SCHED;
	s_setprio 1
	s_waitcnt lgkmcnt(0)
	v_mfma_f32_16x16x32_bf16 v[60:63], v[140:143], v[178:181], 0
	v_mfma_f32_16x16x32_bf16 v[56:59], v[154:157], v[178:181], 0
	v_mfma_f32_16x16x32_bf16 v[40:43], v[154:157], v[186:189], 0
	v_mfma_f32_16x16x32_bf16 v[44:47], v[140:143], v[186:189], 0
	v_mfma_f32_16x16x32_bf16 v[28:31], v[140:143], v[202:205], 0
	v_mfma_f32_16x16x32_bf16 v[24:27], v[154:157], v[202:205], 0
	v_mfma_f32_16x16x32_bf16 v[8:11], v[154:157], v[210:213], 0
	v_mfma_f32_16x16x32_bf16 v[12:15], v[140:143], v[210:213], 0
	v_mfma_f32_16x16x32_bf16 v[60:63], v[150:153], v[182:185], v[60:63]
	v_mfma_f32_16x16x32_bf16 v[56:59], v[158:161], v[182:185], v[56:59]
	v_mfma_f32_16x16x32_bf16 v[40:43], v[158:161], v[190:193], v[40:43]
	v_mfma_f32_16x16x32_bf16 v[44:47], v[150:153], v[190:193], v[44:47]
	v_mfma_f32_16x16x32_bf16 v[28:31], v[150:153], v[206:209], v[28:31]
	v_mfma_f32_16x16x32_bf16 v[24:27], v[158:161], v[206:209], v[24:27]
	v_mfma_f32_16x16x32_bf16 v[8:11], v[158:161], v[214:217], v[8:11]
	v_mfma_f32_16x16x32_bf16 v[12:15], v[150:153], v[214:217], v[12:15]
	s_setprio 0
	s_setprio 1
	v_mfma_f32_16x16x32_bf16 v[52:55], v[162:165], v[178:181], 0
	v_mfma_f32_16x16x32_bf16 v[48:51], v[170:173], v[178:181], 0
	v_mfma_f32_16x16x32_bf16 v[32:35], v[170:173], v[186:189], 0
	v_mfma_f32_16x16x32_bf16 v[36:39], v[162:165], v[186:189], 0
	v_mfma_f32_16x16x32_bf16 v[20:23], v[162:165], v[202:205], 0
	v_mfma_f32_16x16x32_bf16 v[16:19], v[170:173], v[202:205], 0
	v_mfma_f32_16x16x32_bf16 v[0:3], v[170:173], v[210:213], 0
	v_mfma_f32_16x16x32_bf16 v[4:7], v[162:165], v[210:213], 0
	v_mfma_f32_16x16x32_bf16 v[52:55], v[166:169], v[182:185], v[52:55]
	v_mfma_f32_16x16x32_bf16 v[48:51], v[174:177], v[182:185], v[48:51]
	v_mfma_f32_16x16x32_bf16 v[32:35], v[174:177], v[190:193], v[32:35]
	v_mfma_f32_16x16x32_bf16 v[36:39], v[166:169], v[190:193], v[36:39]
	v_mfma_f32_16x16x32_bf16 v[20:23], v[166:169], v[206:209], v[20:23]
	v_mfma_f32_16x16x32_bf16 v[16:19], v[174:177], v[206:209], v[16:19]
	v_mfma_f32_16x16x32_bf16 v[0:3], v[174:177], v[214:217], v[0:3]
	v_mfma_f32_16x16x32_bf16 v[4:7], v[166:169], v[214:217], v[4:7]
	s_setprio 0
	s_barrier
	s_add_i32 s56, 0, 0x18000
	s_add_i32 s57, 0, 0x1c000
	v_add_u32_e32 v158, s56, v148
	v_add_u32_e32 v174, s57, v148
	s_add_u32 s30, s30, 0x170000
	s_addc_u32 s31, s31, 0
	s_mov_b32 m0, s76
	v_lshl_add_u64 v[250:251], s[30:31], 0, v[132:133]
	s_nop 0
	global_load_lds_dwordx4 v[250:251], off
	v_lshl_add_u64 v[250:251], s[30:31], 0, v[134:135]
	s_mov_b32 m0, s77
	s_nop 0
	global_load_lds_dwordx4 v[250:251], off
	ds_read_b128 v[140:143], v158
	ds_read_b128 v[150:153], v158 offset:1024
	ds_read_b128 v[154:157], v158 offset:2048
	ds_read_b128 v[158:161], v158 offset:3072
	ds_read_b128 v[162:165], v174
	ds_read_b128 v[166:169], v174 offset:1024
	ds_read_b128 v[170:173], v174 offset:2048
	ds_read_b128 v[174:177], v174 offset:3072
	ds_read_b128 v[178:181], v149 offset:32768
	ds_read_b128 v[182:185], v149 offset:33792
	ds_read_b128 v[186:189], v149 offset:34816
	ds_read_b128 v[190:193], v149 offset:35840
	ds_read_b128 v[202:205], v149 offset:36864
	ds_read_b128 v[206:209], v149 offset:37888
	ds_read_b128 v[210:213], v149 offset:38912
	ds_read_b128 v[214:217], v149 offset:39936
	s_waitcnt vmcnt(8)
	s_waitcnt lgkmcnt(0)
	s_barrier
	s_setprio 1
	s_waitcnt lgkmcnt(0)
	v_mfma_f32_16x16x32_bf16 v[126:129], v[140:143], v[178:181], v[126:129]
	v_mfma_f32_16x16x32_bf16 v[122:125], v[154:157], v[178:181], v[122:125]
	v_mfma_f32_16x16x32_bf16 v[106:109], v[154:157], v[186:189], v[106:109]
	v_mfma_f32_16x16x32_bf16 v[110:113], v[140:143], v[186:189], v[110:113]
	v_mfma_f32_16x16x32_bf16 v[92:95], v[140:143], v[202:205], v[92:95]
	v_mfma_f32_16x16x32_bf16 v[88:91], v[154:157], v[202:205], v[88:91]
	v_mfma_f32_16x16x32_bf16 v[72:75], v[154:157], v[210:213], v[72:75]
	v_mfma_f32_16x16x32_bf16 v[76:79], v[140:143], v[210:213], v[76:79]
	v_mfma_f32_16x16x32_bf16 v[126:129], v[150:153], v[182:185], v[126:129]
	v_mfma_f32_16x16x32_bf16 v[122:125], v[158:161], v[182:185], v[122:125]
	v_mfma_f32_16x16x32_bf16 v[106:109], v[158:161], v[190:193], v[106:109]
	v_mfma_f32_16x16x32_bf16 v[110:113], v[150:153], v[190:193], v[110:113]
	v_mfma_f32_16x16x32_bf16 v[92:95], v[150:153], v[206:209], v[92:95]
	v_mfma_f32_16x16x32_bf16 v[88:91], v[158:161], v[206:209], v[88:91]
	v_mfma_f32_16x16x32_bf16 v[72:75], v[158:161], v[214:217], v[72:75]
	v_mfma_f32_16x16x32_bf16 v[76:79], v[150:153], v[214:217], v[76:79]
	s_setprio 0
	s_setprio 1
	v_mfma_f32_16x16x32_bf16 v[118:121], v[162:165], v[178:181], v[118:121]
	v_mfma_f32_16x16x32_bf16 v[114:117], v[170:173], v[178:181], v[114:117]
	v_mfma_f32_16x16x32_bf16 v[98:101], v[170:173], v[186:189], v[98:101]
	v_mfma_f32_16x16x32_bf16 v[102:105], v[162:165], v[186:189], v[102:105]
	v_mfma_f32_16x16x32_bf16 v[84:87], v[162:165], v[202:205], v[84:87]
	v_mfma_f32_16x16x32_bf16 v[80:83], v[170:173], v[202:205], v[80:83]
	v_mfma_f32_16x16x32_bf16 v[64:67], v[170:173], v[210:213], v[64:67]
	v_mfma_f32_16x16x32_bf16 v[68:71], v[162:165], v[210:213], v[68:71]
	v_mfma_f32_16x16x32_bf16 v[118:121], v[166:169], v[182:185], v[118:121]
	v_mfma_f32_16x16x32_bf16 v[114:117], v[174:177], v[182:185], v[114:117]
	v_mfma_f32_16x16x32_bf16 v[98:101], v[174:177], v[190:193], v[98:101]
	v_mfma_f32_16x16x32_bf16 v[102:105], v[166:169], v[190:193], v[102:105]
	v_mfma_f32_16x16x32_bf16 v[84:87], v[166:169], v[206:209], v[84:87]
	v_mfma_f32_16x16x32_bf16 v[80:83], v[174:177], v[206:209], v[80:83]
	v_mfma_f32_16x16x32_bf16 v[64:67], v[174:177], v[214:217], v[64:67]
	v_mfma_f32_16x16x32_bf16 v[68:71], v[166:169], v[214:217], v[68:71]
	s_setprio 0
	s_barrier
; #define PG8_STAGE(bufoff, gbase, V0, V1) do { \
;         __builtin_amdgcn_global_load_lds((const unsigned*)((const char*)(gbase) + (V0)), (LAS unsigned*)(lds + (bufoff) + ldsw), 16, 0, 0); \
;         __builtin_amdgcn_global_load_lds((const unsigned*)((const char*)(gbase) + (V1)), (LAS unsigned*)(lds + (bufoff) + ldsw + 8192), 16, 0, 0); } while (0)
; #define PG8_LDA(dst, b, h) do { _Pragma("unroll") for (int m = 0; m < 4; ++m) _Pragma("unroll") for (int k = 0; k < 2; ++k) dst[m][k] = *(const LAS bf16x8*)(lds + PG8_SA(b, h) + aoff + m * 2048 + k * 1024); } while (0)
; #define PG8_LDB(dst, b, h) do { _Pragma("unroll") for (int n = 0; n < 2; ++n) _Pragma("unroll") for (int k = 0; k < 2; ++k) dst[n][k] = *(const LAS bf16x8*)(lds + PG8_SB(b, h) + boff + n * 2048 + k * 1024); } while (0)
; #define PG8_MMA(ai, bj, At, Bt) do { __builtin_amdgcn_s_setprio(1); _Pragma("unroll") for (int m = 0; m < 4; ++m) _Pragma("unroll") for (int n = 0; n < 2; ++n) _Pragma("unroll") for (int k = 0; k < 2; ++k) \
;         acc[ai][bj][m][n] = __builtin_amdgcn_mfma_f32_16x16x32_bf16(Bt[n][k], At[m][k], acc[ai][bj][m][n], 0, 0, 0); __builtin_amdgcn_s_setprio(0); } while (0)
; #define PG8_WAIT_V(n) asm volatile("s_waitcnt vmcnt(" #n ")" ::: "memory")
; #define PG8_WAIT_L(n) asm volatile("s_waitcnt lgkmcnt(" #n ")" ::: "memory")
; #define PG8_BAR __builtin_amdgcn_s_barrier()
; #define PG8_SCHED __builtin_amdgcn_sched_barrier(0)
; template <class Epi, class Sched>
; DI void gemm_phase(LAS unsigned char* lds, const int lda2, const int ldb2, const int nt, const Sched& S, const Epi& E) {
;     ...
;         for (int t = 0; t < nt; t += 2) {
;             const bool last = (t == nt - 2);
;             const char* a1 = cA + (size_t)(t + 1) * kstep;
;             const char* a2 = last ? nA : cA + (size_t)(t + 2) * kstep; const char* b2 = last ? nB : cB + (size_t)(t + 2) * kstep;
;             const char* a3 = a2 + kstep; const char* b3 = b2 + kstep;
;             PG8_LDB(B0, 0, 0); PG8_LDB(B1, 0, 1); PG8_SCHED; PG8_LDA(At, 0, 0); PG8_STAGE(PG8_SA(1, 1), a1 + hstepA, vA0, vA1);
;     ...
;             PG8_LDA(At, 1, 1); PG8_STAGE(PG8_SB(1, 0), b3, vB0, vB1); PG8_STAGE(PG8_SB(1, 1), b3 + hstepB, vB0, vB1); PG8_STAGE(PG8_SA(1, 0), a3, vA0, vA1);
;             PG8_WAIT_V(8); PG8_WAIT_L(0); PG8_BAR; PG8_MMA(1, 0, At, B0); PG8_MMA(1, 1, At, B1); PG8_BAR; PG8_SCHED;
	s_add_i32 s30, s56, s73
	v_lshl_add_u64 v[144:145], v[144:145], 0, s[86:87]
	s_mov_b32 m0, s30
	ds_read_b128 v[178:181], v149 offset:49152
	ds_read_b128 v[182:185], v149 offset:50176
	ds_read_b128 v[186:189], v149 offset:51200
	ds_read_b128 v[190:193], v149 offset:52224
	ds_read_b128 v[202:205], v149 offset:53248
	ds_read_b128 v[206:209], v149 offset:54272
	ds_read_b128 v[210:213], v149 offset:55296
	ds_read_b128 v[214:217], v149 offset:56320
	global_load_lds_dwordx4 v[144:145], off
	s_add_i32 m0, s30, 0x2000
	s_add_u32 s28, s28, 0x40080
	v_lshl_add_u64 v[144:145], v[194:195], 0, s[86:87]
	s_addc_u32 s29, s29, 0
	s_add_i32 s30, s57, s73
	global_load_lds_dwordx4 v[144:145], off
	v_lshl_add_u64 v[144:145], s[28:29], 0, v[96:97]
	s_mov_b32 m0, s30
	s_nop 0
	global_load_lds_dwordx4 v[144:145], off
	v_lshl_add_u64 v[144:145], s[28:29], 0, v[130:131]
	s_add_i32 m0, s30, 0x2000
	s_nop 0
	global_load_lds_dwordx4 v[144:145], off
	v_lshl_add_u64 v[144:145], v[218:219], 0, s[86:87]
	s_mov_b32 m0, s81
	s_nop 0
	global_load_lds_dwordx4 v[144:145], off
	v_lshl_add_u64 v[144:145], v[220:221], 0, s[86:87]
	s_mov_b32 m0, s82
	s_nop 0
	global_load_lds_dwordx4 v[144:145], off
	s_waitcnt vmcnt(8)
	s_waitcnt lgkmcnt(0)
	s_barrier
	s_setprio 1
	s_waitcnt lgkmcnt(0)
	v_mfma_f32_16x16x32_bf16 v[60:63], v[140:143], v[178:181], v[60:63]
	v_mfma_f32_16x16x32_bf16 v[56:59], v[154:157], v[178:181], v[56:59]
	v_mfma_f32_16x16x32_bf16 v[40:43], v[154:157], v[186:189], v[40:43]
	v_mfma_f32_16x16x32_bf16 v[44:47], v[140:143], v[186:189], v[44:47]
	v_mfma_f32_16x16x32_bf16 v[28:31], v[140:143], v[202:205], v[28:31]
	v_mfma_f32_16x16x32_bf16 v[24:27], v[154:157], v[202:205], v[24:27]
	v_mfma_f32_16x16x32_bf16 v[8:11], v[154:157], v[210:213], v[8:11]
	v_mfma_f32_16x16x32_bf16 v[12:15], v[140:143], v[210:213], v[12:15]
	v_mfma_f32_16x16x32_bf16 v[60:63], v[150:153], v[182:185], v[60:63]
	v_mfma_f32_16x16x32_bf16 v[56:59], v[158:161], v[182:185], v[56:59]
	v_mfma_f32_16x16x32_bf16 v[40:43], v[158:161], v[190:193], v[40:43]
	v_mfma_f32_16x16x32_bf16 v[44:47], v[150:153], v[190:193], v[44:47]
	v_mfma_f32_16x16x32_bf16 v[28:31], v[150:153], v[206:209], v[28:31]
	v_mfma_f32_16x16x32_bf16 v[24:27], v[158:161], v[206:209], v[24:27]
	v_mfma_f32_16x16x32_bf16 v[8:11], v[158:161], v[214:217], v[8:11]
	v_mfma_f32_16x16x32_bf16 v[12:15], v[150:153], v[214:217], v[12:15]
	s_setprio 0
	s_setprio 1
	v_mfma_f32_16x16x32_bf16 v[52:55], v[162:165], v[178:181], v[52:55]
	v_mfma_f32_16x16x32_bf16 v[48:51], v[170:173], v[178:181], v[48:51]
	v_mfma_f32_16x16x32_bf16 v[32:35], v[170:173], v[186:189], v[32:35]
	v_mfma_f32_16x16x32_bf16 v[36:39], v[162:165], v[186:189], v[36:39]
	v_mfma_f32_16x16x32_bf16 v[20:23], v[162:165], v[202:205], v[20:23]
	v_mfma_f32_16x16x32_bf16 v[16:19], v[170:173], v[202:205], v[16:19]
	v_mfma_f32_16x16x32_bf16 v[0:3], v[170:173], v[210:213], v[0:3]
	v_mfma_f32_16x16x32_bf16 v[4:7], v[162:165], v[210:213], v[4:7]
	v_mfma_f32_16x16x32_bf16 v[52:55], v[166:169], v[182:185], v[52:55]
	v_mfma_f32_16x16x32_bf16 v[48:51], v[174:177], v[182:185], v[48:51]
	v_mfma_f32_16x16x32_bf16 v[32:35], v[174:177], v[190:193], v[32:35]
	v_mfma_f32_16x16x32_bf16 v[36:39], v[166:169], v[190:193], v[36:39]
	v_mfma_f32_16x16x32_bf16 v[20:23], v[166:169], v[206:209], v[20:23]
	v_mfma_f32_16x16x32_bf16 v[16:19], v[174:177], v[206:209], v[16:19]
	v_mfma_f32_16x16x32_bf16 v[0:3], v[174:177], v[214:217], v[0:3]
	v_mfma_f32_16x16x32_bf16 v[4:7], v[166:169], v[214:217], v[4:7]
	s_setprio 0
	s_barrier
	s_add_i32 s21, s21, 2
	s_add_u32 s26, s26, 0x100
	s_addc_u32 s27, s27, 0
	s_add_u32 s1, s1, 0x100
	s_addc_u32 s10, s10, 0
.LBB0_906:
	s_add_u32 s28, s26, 0xffe90080
	s_addc_u32 s29, s27, -1
	s_add_i32 s56, 0, 0x10000
	s_cmp_eq_u32 s21, 12
	s_cselect_b32 s31, s23, s29
	s_cselect_b32 s30, s22, s28
	v_add_u32_e32 v144, s56, v148
	s_cselect_b32 s29, s25, s10
	s_cselect_b32 s28, s24, s1
	s_add_i32 vcc_lo, 0, 0x14000
	v_lshl_add_u64 v[250:251], s[26:27], 0, v[136:137]
	s_add_i32 m0, s74, 0xc000
	s_nop 0
	global_load_lds_dwordx4 v[250:251], off
	v_lshl_add_u64 v[250:251], s[26:27], 0, v[138:139]
	s_add_i32 m0, s74, 0xe000
	s_nop 0
	global_load_lds_dwordx4 v[250:251], off
	ds_read_b128 v[140:143], v144
	ds_read_b128 v[150:153], v144 offset:1024
	ds_read_b128 v[154:157], v144 offset:2048
	ds_read_b128 v[158:161], v144 offset:3072
	v_add_u32_e32 v144, vcc_lo, v148
	ds_read_b128 v[162:165], v144
	ds_read_b128 v[166:169], v144 offset:1024
	ds_read_b128 v[170:173], v144 offset:2048
	ds_read_b128 v[174:177], v144 offset:3072
	ds_read_b128 v[178:181], v149
	ds_read_b128 v[182:185], v149 offset:1024
	ds_read_b128 v[186:189], v149 offset:2048
	ds_read_b128 v[190:193], v149 offset:3072
	ds_read_b128 v[202:205], v149 offset:4096
	ds_read_b128 v[206:209], v149 offset:5120
	ds_read_b128 v[210:213], v149 offset:6144
	ds_read_b128 v[214:217], v149 offset:7168
	s_waitcnt vmcnt(8)
	s_waitcnt lgkmcnt(0)
	s_barrier
; #define PG8_STAGE(bufoff, gbase, V0, V1) do { \
;         __builtin_amdgcn_global_load_lds((const unsigned*)((const char*)(gbase) + (V0)), (LAS unsigned*)(lds + (bufoff) + ldsw), 16, 0, 0); \
;         __builtin_amdgcn_global_load_lds((const unsigned*)((const char*)(gbase) + (V1)), (LAS unsigned*)(lds + (bufoff) + ldsw + 8192), 16, 0, 0); } while (0)
; #define PG8_LDA(dst, b, h) do { _Pragma("unroll") for (int m = 0; m < 4; ++m) _Pragma("unroll") for (int k = 0; k < 2; ++k) dst[m][k] = *(const LAS bf16x8*)(lds + PG8_SA(b, h) + aoff + m * 2048 + k * 1024); } while (0)
; #define PG8_LDB(dst, b, h) do { _Pragma("unroll") for (int n = 0; n < 2; ++n) _Pragma("unroll") for (int k = 0; k < 2; ++k) dst[n][k] = *(const LAS bf16x8*)(lds + PG8_SB(b, h) + boff + n * 2048 + k * 1024); } while (0)
; #define PG8_MMA(ai, bj, At, Bt) do { __builtin_amdgcn_s_setprio(1); _Pragma("unroll") for (int m = 0; m < 4; ++m) _Pragma("unroll") for (int n = 0; n < 2; ++n) _Pragma("unroll") for (int k = 0; k < 2; ++k) \
;         acc[ai][bj][m][n] = __builtin_amdgcn_mfma_f32_16x16x32_bf16(Bt[n][k], At[m][k], acc[ai][bj][m][n], 0, 0, 0); __builtin_amdgcn_s_setprio(0); } while (0)
; #define PG8_WAIT_V(n) asm volatile("s_waitcnt vmcnt(" #n ")" ::: "memory")
; #define PG8_WAIT_L(n) asm volatile("s_waitcnt lgkmcnt(" #n ")" ::: "memory")
; #define PG8_BAR __builtin_amdgcn_s_barrier()
; #define PG8_SCHED __builtin_amdgcn_sched_barrier(0)
; template <class Epi, class Sched>
; DI void gemm_phase(LAS unsigned char* lds, const int lda2, const int ldb2, const int nt, const Sched& S, const Epi& E) {
;     ...
;             PG8_WAIT_V(8); PG8_WAIT_L(0); PG8_BAR; PG8_MMA(0, 0, At, B0); PG8_MMA(0, 1, At, B1); PG8_BAR; PG8_SCHED;
;             PG8_LDA(At, 0, 1); PG8_STAGE(PG8_SB(0, 0), b2, vB0, vB1); PG8_STAGE(PG8_SB(0, 1), b2 + hstepB, vB0, vB1); PG8_STAGE(PG8_SA(0, 0), a2, vA0, vA1);
;             PG8_WAIT_V(8); PG8_WAIT_L(0); PG8_BAR; PG8_MMA(1, 0, At, B0); PG8_MMA(1, 1, At, B1); PG8_BAR; PG8_SCHED;
;             PG8_LDB(B0, 1, 0); PG8_LDB(B1, 1, 1); PG8_SCHED; PG8_LDA(At, 1, 0); PG8_STAGE(PG8_SA(0, 1), a2 + hstepA, vA0, vA1);
;             PG8_WAIT_V(8); PG8_WAIT_L(0); PG8_BAR; PG8_MMA(0, 0, At, B0); PG8_MMA(0, 1, At, B1); PG8_BAR; PG8_SCHED;
	s_setprio 1
	s_waitcnt lgkmcnt(0)
	v_mfma_f32_16x16x32_bf16 v[126:129], v[140:143], v[178:181], v[126:129]
	v_mfma_f32_16x16x32_bf16 v[122:125], v[154:157], v[178:181], v[122:125]
	v_mfma_f32_16x16x32_bf16 v[106:109], v[154:157], v[186:189], v[106:109]
	v_mfma_f32_16x16x32_bf16 v[110:113], v[140:143], v[186:189], v[110:113]
	v_mfma_f32_16x16x32_bf16 v[92:95], v[140:143], v[202:205], v[92:95]
	v_mfma_f32_16x16x32_bf16 v[88:91], v[154:157], v[202:205], v[88:91]
	v_mfma_f32_16x16x32_bf16 v[72:75], v[154:157], v[210:213], v[72:75]
	v_mfma_f32_16x16x32_bf16 v[76:79], v[140:143], v[210:213], v[76:79]
	v_mfma_f32_16x16x32_bf16 v[126:129], v[150:153], v[182:185], v[126:129]
	v_mfma_f32_16x16x32_bf16 v[122:125], v[158:161], v[182:185], v[122:125]
	v_mfma_f32_16x16x32_bf16 v[106:109], v[158:161], v[190:193], v[106:109]
	v_mfma_f32_16x16x32_bf16 v[110:113], v[150:153], v[190:193], v[110:113]
	v_mfma_f32_16x16x32_bf16 v[92:95], v[150:153], v[206:209], v[92:95]
	v_mfma_f32_16x16x32_bf16 v[88:91], v[158:161], v[206:209], v[88:91]
	v_mfma_f32_16x16x32_bf16 v[72:75], v[158:161], v[214:217], v[72:75]
	v_mfma_f32_16x16x32_bf16 v[76:79], v[150:153], v[214:217], v[76:79]
	s_setprio 0
	s_setprio 1
	v_mfma_f32_16x16x32_bf16 v[118:121], v[162:165], v[178:181], v[118:121]
	v_mfma_f32_16x16x32_bf16 v[114:117], v[170:173], v[178:181], v[114:117]
	v_mfma_f32_16x16x32_bf16 v[98:101], v[170:173], v[186:189], v[98:101]
	v_mfma_f32_16x16x32_bf16 v[102:105], v[162:165], v[186:189], v[102:105]
	v_mfma_f32_16x16x32_bf16 v[84:87], v[162:165], v[202:205], v[84:87]
	v_mfma_f32_16x16x32_bf16 v[80:83], v[170:173], v[202:205], v[80:83]
	v_mfma_f32_16x16x32_bf16 v[64:67], v[170:173], v[210:213], v[64:67]
	v_mfma_f32_16x16x32_bf16 v[68:71], v[162:165], v[210:213], v[68:71]
	v_mfma_f32_16x16x32_bf16 v[118:121], v[166:169], v[182:185], v[118:121]
	v_mfma_f32_16x16x32_bf16 v[114:117], v[174:177], v[182:185], v[114:117]
	v_mfma_f32_16x16x32_bf16 v[98:101], v[174:177], v[190:193], v[98:101]
	v_mfma_f32_16x16x32_bf16 v[102:105], v[166:169], v[190:193], v[102:105]
	v_mfma_f32_16x16x32_bf16 v[84:87], v[166:169], v[206:209], v[84:87]
	v_mfma_f32_16x16x32_bf16 v[80:83], v[174:177], v[206:209], v[80:83]
	v_mfma_f32_16x16x32_bf16 v[64:67], v[174:177], v[214:217], v[64:67]
	v_mfma_f32_16x16x32_bf16 v[68:71], v[166:169], v[214:217], v[68:71]
	s_setprio 0
	s_barrier
	s_add_i32 s56, s56, s73
	v_lshl_add_u64 v[144:145], s[28:29], 0, v[96:97]
	s_mov_b32 m0, s56
	ds_read_b128 v[178:181], v149 offset:16384
	ds_read_b128 v[182:185], v149 offset:17408
	ds_read_b128 v[186:189], v149 offset:18432
	ds_read_b128 v[190:193], v149 offset:19456
	ds_read_b128 v[202:205], v149 offset:20480
	ds_read_b128 v[206:209], v149 offset:21504
	ds_read_b128 v[210:213], v149 offset:22528
	ds_read_b128 v[214:217], v149 offset:23552
	global_load_lds_dwordx4 v[144:145], off
	s_add_i32 m0, s56, 0x2000
	s_add_u32 s56, s28, 0x40000
	v_lshl_add_u64 v[194:195], s[28:29], 0, v[130:131]
	s_addc_u32 s57, s29, 0
	s_add_i32 vcc_lo, vcc_lo, s73
	global_load_lds_dwordx4 v[194:195], off
	v_lshl_add_u64 v[218:219], s[56:57], 0, v[96:97]
	s_mov_b32 m0, vcc_lo
	v_lshl_add_u64 v[220:221], s[30:31], 0, v[134:135]
	global_load_lds_dwordx4 v[218:219], off
	v_lshl_add_u64 v[218:219], s[56:57], 0, v[130:131]
	s_add_i32 m0, vcc_lo, 0x2000
	s_nop 0
	global_load_lds_dwordx4 v[218:219], off
	v_lshl_add_u64 v[218:219], s[30:31], 0, v[132:133]
	s_mov_b32 m0, s74
	s_nop 0
	global_load_lds_dwordx4 v[218:219], off
	s_mov_b32 m0, s75
	s_nop 0
	global_load_lds_dwordx4 v[220:221], off
	s_waitcnt vmcnt(8)
	s_waitcnt lgkmcnt(0)
	s_barrier
	s_setprio 1
	s_waitcnt lgkmcnt(0)
	v_mfma_f32_16x16x32_bf16 v[60:63], v[140:143], v[178:181], v[60:63]
	v_mfma_f32_16x16x32_bf16 v[56:59], v[154:157], v[178:181], v[56:59]
	v_mfma_f32_16x16x32_bf16 v[40:43], v[154:157], v[186:189], v[40:43]
	v_mfma_f32_16x16x32_bf16 v[44:47], v[140:143], v[186:189], v[44:47]
	v_mfma_f32_16x16x32_bf16 v[28:31], v[140:143], v[202:205], v[28:31]
	v_mfma_f32_16x16x32_bf16 v[24:27], v[154:157], v[202:205], v[24:27]
	v_mfma_f32_16x16x32_bf16 v[8:11], v[154:157], v[210:213], v[8:11]
	v_mfma_f32_16x16x32_bf16 v[12:15], v[140:143], v[210:213], v[12:15]
	v_mfma_f32_16x16x32_bf16 v[60:63], v[150:153], v[182:185], v[60:63]
	v_mfma_f32_16x16x32_bf16 v[56:59], v[158:161], v[182:185], v[56:59]
	v_mfma_f32_16x16x32_bf16 v[40:43], v[158:161], v[190:193], v[40:43]
	v_mfma_f32_16x16x32_bf16 v[44:47], v[150:153], v[190:193], v[44:47]
	v_mfma_f32_16x16x32_bf16 v[28:31], v[150:153], v[206:209], v[28:31]
	v_mfma_f32_16x16x32_bf16 v[24:27], v[158:161], v[206:209], v[24:27]
	v_mfma_f32_16x16x32_bf16 v[8:11], v[158:161], v[214:217], v[8:11]
	v_mfma_f32_16x16x32_bf16 v[12:15], v[150:153], v[214:217], v[12:15]
	s_setprio 0
	s_setprio 1
	v_mfma_f32_16x16x32_bf16 v[52:55], v[162:165], v[178:181], v[52:55]
	v_mfma_f32_16x16x32_bf16 v[48:51], v[170:173], v[178:181], v[48:51]
	v_mfma_f32_16x16x32_bf16 v[32:35], v[170:173], v[186:189], v[32:35]
	v_mfma_f32_16x16x32_bf16 v[36:39], v[162:165], v[186:189], v[36:39]
	v_mfma_f32_16x16x32_bf16 v[20:23], v[162:165], v[202:205], v[20:23]
	v_mfma_f32_16x16x32_bf16 v[16:19], v[170:173], v[202:205], v[16:19]
	v_mfma_f32_16x16x32_bf16 v[0:3], v[170:173], v[210:213], v[0:3]
	v_mfma_f32_16x16x32_bf16 v[4:7], v[162:165], v[210:213], v[4:7]
	v_mfma_f32_16x16x32_bf16 v[52:55], v[166:169], v[182:185], v[52:55]
	v_mfma_f32_16x16x32_bf16 v[48:51], v[174:177], v[182:185], v[48:51]
	v_mfma_f32_16x16x32_bf16 v[32:35], v[174:177], v[190:193], v[32:35]
	v_mfma_f32_16x16x32_bf16 v[36:39], v[166:169], v[190:193], v[36:39]
	v_mfma_f32_16x16x32_bf16 v[20:23], v[166:169], v[206:209], v[20:23]
	v_mfma_f32_16x16x32_bf16 v[16:19], v[174:177], v[206:209], v[16:19]
	v_mfma_f32_16x16x32_bf16 v[0:3], v[174:177], v[214:217], v[0:3]
	v_mfma_f32_16x16x32_bf16 v[4:7], v[166:169], v[214:217], v[4:7]
	s_setprio 0
	s_barrier
; #define PG8_STAGE(bufoff, gbase, V0, V1) do { \
;         __builtin_amdgcn_global_load_lds((const unsigned*)((const char*)(gbase) + (V0)), (LAS unsigned*)(lds + (bufoff) + ldsw), 16, 0, 0); \
;         __builtin_amdgcn_global_load_lds((const unsigned*)((const char*)(gbase) + (V1)), (LAS unsigned*)(lds + (bufoff) + ldsw + 8192), 16, 0, 0); } while (0)
; #define PG8_LDA(dst, b, h) do { _Pragma("unroll") for (int m = 0; m < 4; ++m) _Pragma("unroll") for (int k = 0; k < 2; ++k) dst[m][k] = *(const LAS bf16x8*)(lds + PG8_SA(b, h) + aoff + m * 2048 + k * 1024); } while (0)
; #define PG8_LDB(dst, b, h) do { _Pragma("unroll") for (int n = 0; n < 2; ++n) _Pragma("unroll") for (int k = 0; k < 2; ++k) dst[n][k] = *(const LAS bf16x8*)(lds + PG8_SB(b, h) + boff + n * 2048 + k * 1024); } while (0)
; #define PG8_MMA(ai, bj, At, Bt) do { __builtin_amdgcn_s_setprio(1); _Pragma("unroll") for (int m = 0; m < 4; ++m) _Pragma("unroll") for (int n = 0; n < 2; ++n) _Pragma("unroll") for (int k = 0; k < 2; ++k) \
;         acc[ai][bj][m][n] = __builtin_amdgcn_mfma_f32_16x16x32_bf16(Bt[n][k], At[m][k], acc[ai][bj][m][n], 0, 0, 0); __builtin_amdgcn_s_setprio(0); } while (0)
; #define PG8_WAIT_V(n) asm volatile("s_waitcnt vmcnt(" #n ")" ::: "memory")
; #define PG8_WAIT_L(n) asm volatile("s_waitcnt lgkmcnt(" #n ")" ::: "memory")
; #define PG8_BAR __builtin_amdgcn_s_barrier()
; #define PG8_SCHED __builtin_amdgcn_sched_barrier(0)
; template <class Epi, class Sched>
; DI void gemm_phase(LAS unsigned char* lds, const int lda2, const int ldb2, const int nt, const Sched& S, const Epi& E) {
;     ...
;             PG8_LDB(B0, 1, 0); PG8_LDB(B1, 1, 1); PG8_SCHED; PG8_LDA(At, 1, 0); PG8_STAGE(PG8_SA(0, 1), a2 + hstepA, vA0, vA1);
;             PG8_WAIT_V(8); PG8_WAIT_L(0); PG8_BAR; PG8_MMA(0, 0, At, B0); PG8_MMA(0, 1, At, B1); PG8_BAR; PG8_SCHED;
	s_add_i32 s56, 0, 0x18000
	s_add_i32 s57, 0, 0x1c000
	v_add_u32_e32 v158, s56, v148
	v_add_u32_e32 v174, s57, v148
	s_add_u32 s30, s30, 0x170000
	s_addc_u32 s31, s31, 0
	s_mov_b32 m0, s76
	v_lshl_add_u64 v[250:251], s[30:31], 0, v[132:133]
	s_nop 0
	global_load_lds_dwordx4 v[250:251], off
	v_lshl_add_u64 v[250:251], s[30:31], 0, v[134:135]
	s_mov_b32 m0, s77
	s_nop 0
	global_load_lds_dwordx4 v[250:251], off
	ds_read_b128 v[140:143], v158
	ds_read_b128 v[150:153], v158 offset:1024
	ds_read_b128 v[154:157], v158 offset:2048
	ds_read_b128 v[158:161], v158 offset:3072
	ds_read_b128 v[162:165], v174
	ds_read_b128 v[166:169], v174 offset:1024
	ds_read_b128 v[170:173], v174 offset:2048
	ds_read_b128 v[174:177], v174 offset:3072
	ds_read_b128 v[178:181], v149 offset:32768
	ds_read_b128 v[182:185], v149 offset:33792
	ds_read_b128 v[186:189], v149 offset:34816
	ds_read_b128 v[190:193], v149 offset:35840
	ds_read_b128 v[202:205], v149 offset:36864
	ds_read_b128 v[206:209], v149 offset:37888
	ds_read_b128 v[210:213], v149 offset:38912
	ds_read_b128 v[214:217], v149 offset:39936
	s_waitcnt vmcnt(8)
	s_waitcnt lgkmcnt(0)
	s_barrier
	s_setprio 1
	s_waitcnt lgkmcnt(0)
	v_mfma_f32_16x16x32_bf16 v[126:129], v[140:143], v[178:181], v[126:129]
	v_mfma_f32_16x16x32_bf16 v[122:125], v[154:157], v[178:181], v[122:125]
	v_mfma_f32_16x16x32_bf16 v[106:109], v[154:157], v[186:189], v[106:109]
	v_mfma_f32_16x16x32_bf16 v[110:113], v[140:143], v[186:189], v[110:113]
	v_mfma_f32_16x16x32_bf16 v[92:95], v[140:143], v[202:205], v[92:95]
	v_mfma_f32_16x16x32_bf16 v[88:91], v[154:157], v[202:205], v[88:91]
	v_mfma_f32_16x16x32_bf16 v[72:75], v[154:157], v[210:213], v[72:75]
	v_mfma_f32_16x16x32_bf16 v[76:79], v[140:143], v[210:213], v[76:79]
	v_mfma_f32_16x16x32_bf16 v[126:129], v[150:153], v[182:185], v[126:129]
	v_mfma_f32_16x16x32_bf16 v[122:125], v[158:161], v[182:185], v[122:125]
	v_mfma_f32_16x16x32_bf16 v[106:109], v[158:161], v[190:193], v[106:109]
	v_mfma_f32_16x16x32_bf16 v[110:113], v[150:153], v[190:193], v[110:113]
	v_mfma_f32_16x16x32_bf16 v[92:95], v[150:153], v[206:209], v[92:95]
	v_mfma_f32_16x16x32_bf16 v[88:91], v[158:161], v[206:209], v[88:91]
	v_mfma_f32_16x16x32_bf16 v[72:75], v[158:161], v[214:217], v[72:75]
	v_mfma_f32_16x16x32_bf16 v[76:79], v[150:153], v[214:217], v[76:79]
	s_setprio 0
	s_setprio 1
	v_mfma_f32_16x16x32_bf16 v[118:121], v[162:165], v[178:181], v[118:121]
	v_mfma_f32_16x16x32_bf16 v[114:117], v[170:173], v[178:181], v[114:117]
	v_mfma_f32_16x16x32_bf16 v[98:101], v[170:173], v[186:189], v[98:101]
	v_mfma_f32_16x16x32_bf16 v[102:105], v[162:165], v[186:189], v[102:105]
	v_mfma_f32_16x16x32_bf16 v[84:87], v[162:165], v[202:205], v[84:87]
	v_mfma_f32_16x16x32_bf16 v[80:83], v[170:173], v[202:205], v[80:83]
	v_mfma_f32_16x16x32_bf16 v[64:67], v[170:173], v[210:213], v[64:67]
	v_mfma_f32_16x16x32_bf16 v[68:71], v[162:165], v[210:213], v[68:71]
	v_mfma_f32_16x16x32_bf16 v[118:121], v[166:169], v[182:185], v[118:121]
	v_mfma_f32_16x16x32_bf16 v[114:117], v[174:177], v[182:185], v[114:117]
	v_mfma_f32_16x16x32_bf16 v[98:101], v[174:177], v[190:193], v[98:101]
	v_mfma_f32_16x16x32_bf16 v[102:105], v[166:169], v[190:193], v[102:105]
	v_mfma_f32_16x16x32_bf16 v[84:87], v[166:169], v[206:209], v[84:87]
	v_mfma_f32_16x16x32_bf16 v[80:83], v[174:177], v[206:209], v[80:83]
	v_mfma_f32_16x16x32_bf16 v[64:67], v[174:177], v[214:217], v[64:67]
	v_mfma_f32_16x16x32_bf16 v[68:71], v[166:169], v[214:217], v[68:71]
	s_setprio 0
	s_barrier
; #define PG8_STAGE(bufoff, gbase, V0, V1) do { \
;         __builtin_amdgcn_global_load_lds((const unsigned*)((const char*)(gbase) + (V0)), (LAS unsigned*)(lds + (bufoff) + ldsw), 16, 0, 0); \
;         __builtin_amdgcn_global_load_lds((const unsigned*)((const char*)(gbase) + (V1)), (LAS unsigned*)(lds + (bufoff) + ldsw + 8192), 16, 0, 0); } while (0)
; #define PG8_LDA(dst, b, h) do { _Pragma("unroll") for (int m = 0; m < 4; ++m) _Pragma("unroll") for (int k = 0; k < 2; ++k) dst[m][k] = *(const LAS bf16x8*)(lds + PG8_SA(b, h) + aoff + m * 2048 + k * 1024); } while (0)
; #define PG8_MMA(ai, bj, At, Bt) do { __builtin_amdgcn_s_setprio(1); _Pragma("unroll") for (int m = 0; m < 4; ++m) _Pragma("unroll") for (int n = 0; n < 2; ++n) _Pragma("unroll") for (int k = 0; k < 2; ++k) \
;         acc[ai][bj][m][n] = __builtin_amdgcn_mfma_f32_16x16x32_bf16(Bt[n][k], At[m][k], acc[ai][bj][m][n], 0, 0, 0); __builtin_amdgcn_s_setprio(0); } while (0)
; #define PG8_WAIT_V(n) asm volatile("s_waitcnt vmcnt(" #n ")" ::: "memory")
; #define PG8_WAIT_L(n) asm volatile("s_waitcnt lgkmcnt(" #n ")" ::: "memory")
; #define PG8_BAR __builtin_amdgcn_s_barrier()
; #define PG8_SCHED __builtin_amdgcn_sched_barrier(0)
; template <class Epi, class Sched>
; DI void gemm_phase(LAS unsigned char* lds, const int lda2, const int ldb2, const int nt, const Sched& S, const Epi& E) {
;     ...
;             PG8_LDA(At, 1, 1); PG8_STAGE(PG8_SB(1, 0), b3, vB0, vB1); PG8_STAGE(PG8_SB(1, 1), b3 + hstepB, vB0, vB1); PG8_STAGE(PG8_SA(1, 0), a3, vA0, vA1);
;             PG8_WAIT_V(8); PG8_WAIT_L(0); PG8_BAR; PG8_MMA(1, 0, At, B0); PG8_MMA(1, 1, At, B1); PG8_BAR; PG8_SCHED;
;         }
;         if (wr == 0) PG8_BAR;
	s_add_i32 s30, s56, s73
	v_lshl_add_u64 v[144:145], v[144:145], 0, s[86:87]
	s_mov_b32 m0, s30
	ds_read_b128 v[178:181], v149 offset:49152
	ds_read_b128 v[182:185], v149 offset:50176
	ds_read_b128 v[186:189], v149 offset:51200
	ds_read_b128 v[190:193], v149 offset:52224
	ds_read_b128 v[202:205], v149 offset:53248
	ds_read_b128 v[206:209], v149 offset:54272
	ds_read_b128 v[210:213], v149 offset:55296
	ds_read_b128 v[214:217], v149 offset:56320
	global_load_lds_dwordx4 v[144:145], off
	s_add_i32 m0, s30, 0x2000
	s_add_u32 s28, s28, 0x40080
	v_lshl_add_u64 v[144:145], v[194:195], 0, s[86:87]
	s_addc_u32 s29, s29, 0
	s_add_i32 s30, s57, s73
	global_load_lds_dwordx4 v[144:145], off
	v_lshl_add_u64 v[144:145], s[28:29], 0, v[96:97]
	s_mov_b32 m0, s30
	s_nop 0
	global_load_lds_dwordx4 v[144:145], off
	v_lshl_add_u64 v[144:145], s[28:29], 0, v[130:131]
	s_add_i32 m0, s30, 0x2000
	s_nop 0
	global_load_lds_dwordx4 v[144:145], off
	v_lshl_add_u64 v[144:145], v[218:219], 0, s[86:87]
	s_mov_b32 m0, s81
	s_nop 0
	global_load_lds_dwordx4 v[144:145], off
	v_lshl_add_u64 v[144:145], v[220:221], 0, s[86:87]
	s_mov_b32 m0, s82
	s_nop 0
	global_load_lds_dwordx4 v[144:145], off
	s_waitcnt vmcnt(8)
	s_waitcnt lgkmcnt(0)
	s_barrier
	s_setprio 1
	s_waitcnt lgkmcnt(0)
	v_mfma_f32_16x16x32_bf16 v[60:63], v[140:143], v[178:181], v[60:63]
	v_mfma_f32_16x16x32_bf16 v[56:59], v[154:157], v[178:181], v[56:59]
	v_mfma_f32_16x16x32_bf16 v[40:43], v[154:157], v[186:189], v[40:43]
	v_mfma_f32_16x16x32_bf16 v[44:47], v[140:143], v[186:189], v[44:47]
	v_mfma_f32_16x16x32_bf16 v[28:31], v[140:143], v[202:205], v[28:31]
	v_mfma_f32_16x16x32_bf16 v[24:27], v[154:157], v[202:205], v[24:27]
	v_mfma_f32_16x16x32_bf16 v[8:11], v[154:157], v[210:213], v[8:11]
	v_mfma_f32_16x16x32_bf16 v[12:15], v[140:143], v[210:213], v[12:15]
	v_mfma_f32_16x16x32_bf16 v[60:63], v[150:153], v[182:185], v[60:63]
	v_mfma_f32_16x16x32_bf16 v[56:59], v[158:161], v[182:185], v[56:59]
	v_mfma_f32_16x16x32_bf16 v[40:43], v[158:161], v[190:193], v[40:43]
	v_mfma_f32_16x16x32_bf16 v[44:47], v[150:153], v[190:193], v[44:47]
	v_mfma_f32_16x16x32_bf16 v[28:31], v[150:153], v[206:209], v[28:31]
	v_mfma_f32_16x16x32_bf16 v[24:27], v[158:161], v[206:209], v[24:27]
	v_mfma_f32_16x16x32_bf16 v[8:11], v[158:161], v[214:217], v[8:11]
	v_mfma_f32_16x16x32_bf16 v[12:15], v[150:153], v[214:217], v[12:15]
	s_setprio 0
	s_setprio 1
	v_mfma_f32_16x16x32_bf16 v[52:55], v[162:165], v[178:181], v[52:55]
	v_mfma_f32_16x16x32_bf16 v[48:51], v[170:173], v[178:181], v[48:51]
	v_mfma_f32_16x16x32_bf16 v[32:35], v[170:173], v[186:189], v[32:35]
	v_mfma_f32_16x16x32_bf16 v[36:39], v[162:165], v[186:189], v[36:39]
	v_mfma_f32_16x16x32_bf16 v[20:23], v[162:165], v[202:205], v[20:23]
	v_mfma_f32_16x16x32_bf16 v[16:19], v[170:173], v[202:205], v[16:19]
	v_mfma_f32_16x16x32_bf16 v[0:3], v[170:173], v[210:213], v[0:3]
	v_mfma_f32_16x16x32_bf16 v[4:7], v[162:165], v[210:213], v[4:7]
	v_mfma_f32_16x16x32_bf16 v[52:55], v[166:169], v[182:185], v[52:55]
	v_mfma_f32_16x16x32_bf16 v[48:51], v[174:177], v[182:185], v[48:51]
	v_mfma_f32_16x16x32_bf16 v[32:35], v[174:177], v[190:193], v[32:35]
	v_mfma_f32_16x16x32_bf16 v[36:39], v[166:169], v[190:193], v[36:39]
	v_mfma_f32_16x16x32_bf16 v[20:23], v[166:169], v[206:209], v[20:23]
	v_mfma_f32_16x16x32_bf16 v[16:19], v[174:177], v[206:209], v[16:19]
	v_mfma_f32_16x16x32_bf16 v[0:3], v[174:177], v[214:217], v[0:3]
	v_mfma_f32_16x16x32_bf16 v[4:7], v[166:169], v[214:217], v[4:7]
	s_setprio 0
	s_barrier
	s_add_i32 s21, s21, 2
	s_add_u32 s26, s26, 0x100
	s_addc_u32 s27, s27, 0
	s_add_u32 s1, s1, 0x100
	s_addc_u32 s10, s10, 0
	s_cmp_gt_u32 s21, 13
	s_cbranch_scc0 .LBB0_906
	s_and_b64 vcc, exec, s[18:19]
	s_cbranch_vccz .LBB0_909
	s_barrier

; #define PG8_STAGE(bufoff, gbase, V0, V1) do { \
;         __builtin_amdgcn_global_load_lds((const unsigned*)((const char*)(gbase) + (V0)), (LAS unsigned*)(lds + (bufoff) + ldsw), 16, 0, 0); \
;         __builtin_amdgcn_global_load_lds((const unsigned*)((const char*)(gbase) + (V1)), (LAS unsigned*)(lds + (bufoff) + ldsw + 8192), 16, 0, 0); } while (0)
; #define PG8_LDA(dst, b, h) do { _Pragma("unroll") for (int m = 0; m < 4; ++m) _Pragma("unroll") for (int k = 0; k < 2; ++k) dst[m][k] = *(const LAS bf16x8*)(lds + PG8_SA(b, h) + aoff + m * 2048 + k * 1024); } while (0)
; #define PG8_LDB(dst, b, h) do { _Pragma("unroll") for (int n = 0; n < 2; ++n) _Pragma("unroll") for (int k = 0; k < 2; ++k) dst[n][k] = *(const LAS bf16x8*)(lds + PG8_SB(b, h) + boff + n * 2048 + k * 1024); } while (0)
; #define PG8_MMA(ai, bj, At, Bt) do { __builtin_amdgcn_s_setprio(1); _Pragma("unroll") for (int m = 0; m < 4; ++m) _Pragma("unroll") for (int n = 0; n < 2; ++n) _Pragma("unroll") for (int k = 0; k < 2; ++k) \
;         acc[ai][bj][m][n] = __builtin_amdgcn_mfma_f32_16x16x32_bf16(Bt[n][k], At[m][k], acc[ai][bj][m][n], 0, 0, 0); __builtin_amdgcn_s_setprio(0); } while (0)
; #define PG8_WAIT_V(n) asm volatile("s_waitcnt vmcnt(" #n ")" ::: "memory")
; #define PG8_WAIT_L(n) asm volatile("s_waitcnt lgkmcnt(" #n ")" ::: "memory")
; #define PG8_BAR __builtin_amdgcn_s_barrier()
; #define PG8_SCHED __builtin_amdgcn_sched_barrier(0)
; template <class Epi, class Sched>
; DI void gemm_phase(LAS unsigned char* lds, const int lda2, const int ldb2, const int nt, const Sched& S, const Epi& E) {
;     ...
;             PG8_LDB(B0, 0, 0); PG8_LDB(B1, 0, 1); PG8_SCHED; PG8_LDA(At, 0, 0); PG8_STAGE(PG8_SA(1, 1), a1 + hstepA, vA0, vA1);
;             PG8_WAIT_V(8); PG8_WAIT_L(0); PG8_BAR; PG8_MMA(0, 0, At, B0); PG8_MMA(0, 1, At, B1); PG8_BAR; PG8_SCHED;
;             PG8_LDA(At, 0, 1); PG8_STAGE(PG8_SB(0, 0), b2, vB0, vB1); PG8_STAGE(PG8_SB(0, 1), b2 + hstepB, vB0, vB1); PG8_STAGE(PG8_SA(0, 0), a2, vA0, vA1);
;             PG8_WAIT_V(8); PG8_WAIT_L(0); PG8_BAR; PG8_MMA(1, 0, At, B0); PG8_MMA(1, 1, At, B1); PG8_BAR; PG8_SCHED;
.LBB0_1052:
	s_add_u32 s28, s28, 0x40080
	s_addc_u32 s29, s29, 0
	s_add_u32 s19, s30, 0x100
	s_addc_u32 s21, s31, 0
	s_mov_b32 s27, -2
	s_add_u32 s30, s28, 0xfffc0080
	s_addc_u32 s31, s29, -1
	s_add_i32 s50, 0, 0x10000
	s_cmp_eq_u32 s27, 12
	s_cselect_b32 s53, s23, s31
	s_cselect_b32 s52, s22, s30
	v_add_u32_e32 v140, s50, v144
	s_cselect_b32 s31, s25, s21
	s_cselect_b32 s30, s24, s19
	s_add_i32 s56, 0, 0x14000
	v_lshl_add_u64 v[250:251], s[28:29], 0, v[136:137]
	s_add_i32 m0, s79, 0xc000
	s_nop 0
	global_load_lds_dwordx4 v[250:251], off
	v_lshl_add_u64 v[250:251], s[28:29], 0, v[138:139]
	s_add_i32 m0, s79, 0xe000
	s_nop 0
	global_load_lds_dwordx4 v[250:251], off
	ds_read_b128 v[146:149], v140
	ds_read_b128 v[150:153], v140 offset:1024
	ds_read_b128 v[154:157], v140 offset:2048
	ds_read_b128 v[158:161], v140 offset:3072
	v_add_u32_e32 v140, s56, v144
	ds_read_b128 v[162:165], v140
	ds_read_b128 v[166:169], v140 offset:1024
	ds_read_b128 v[170:173], v140 offset:2048
	ds_read_b128 v[174:177], v140 offset:3072
	ds_read_b128 v[178:181], v145
	ds_read_b128 v[182:185], v145 offset:1024
	ds_read_b128 v[186:189], v145 offset:2048
	ds_read_b128 v[190:193], v145 offset:3072
	ds_read_b128 v[202:205], v145 offset:4096
	ds_read_b128 v[206:209], v145 offset:5120
	ds_read_b128 v[210:213], v145 offset:6144
	ds_read_b128 v[214:217], v145 offset:7168
	s_waitcnt vmcnt(8)
	s_waitcnt lgkmcnt(0)
	s_barrier
	s_setprio 1
	s_waitcnt lgkmcnt(0)
	v_mfma_f32_16x16x32_bf16 v[126:129], v[146:149], v[178:181], 0
	v_mfma_f32_16x16x32_bf16 v[118:121], v[154:157], v[178:181], 0
	v_mfma_f32_16x16x32_bf16 v[102:105], v[154:157], v[186:189], 0
	v_mfma_f32_16x16x32_bf16 v[110:113], v[146:149], v[186:189], 0
	v_mfma_f32_16x16x32_bf16 v[92:95], v[146:149], v[202:205], 0
	v_mfma_f32_16x16x32_bf16 v[84:87], v[154:157], v[202:205], 0
	v_mfma_f32_16x16x32_bf16 v[68:71], v[154:157], v[210:213], 0
	v_mfma_f32_16x16x32_bf16 v[76:79], v[146:149], v[210:213], 0
	v_mfma_f32_16x16x32_bf16 v[126:129], v[150:153], v[182:185], v[126:129]
	v_mfma_f32_16x16x32_bf16 v[118:121], v[158:161], v[182:185], v[118:121]
	v_mfma_f32_16x16x32_bf16 v[102:105], v[158:161], v[190:193], v[102:105]
	v_mfma_f32_16x16x32_bf16 v[110:113], v[150:153], v[190:193], v[110:113]
	v_mfma_f32_16x16x32_bf16 v[92:95], v[150:153], v[206:209], v[92:95]
	v_mfma_f32_16x16x32_bf16 v[84:87], v[158:161], v[206:209], v[84:87]
	v_mfma_f32_16x16x32_bf16 v[68:71], v[158:161], v[214:217], v[68:71]
	v_mfma_f32_16x16x32_bf16 v[76:79], v[150:153], v[214:217], v[76:79]
	s_setprio 0
	s_setprio 1
	v_mfma_f32_16x16x32_bf16 v[122:125], v[162:165], v[178:181], 0
	v_mfma_f32_16x16x32_bf16 v[114:117], v[170:173], v[178:181], 0
	v_mfma_f32_16x16x32_bf16 v[98:101], v[170:173], v[186:189], 0
	v_mfma_f32_16x16x32_bf16 v[106:109], v[162:165], v[186:189], 0
	v_mfma_f32_16x16x32_bf16 v[88:91], v[162:165], v[202:205], 0
	v_mfma_f32_16x16x32_bf16 v[80:83], v[170:173], v[202:205], 0
	v_mfma_f32_16x16x32_bf16 v[64:67], v[170:173], v[210:213], 0
	v_mfma_f32_16x16x32_bf16 v[72:75], v[162:165], v[210:213], 0
	v_mfma_f32_16x16x32_bf16 v[122:125], v[166:169], v[182:185], v[122:125]
	v_mfma_f32_16x16x32_bf16 v[114:117], v[174:177], v[182:185], v[114:117]
	v_mfma_f32_16x16x32_bf16 v[98:101], v[174:177], v[190:193], v[98:101]
	v_mfma_f32_16x16x32_bf16 v[106:109], v[166:169], v[190:193], v[106:109]
	v_mfma_f32_16x16x32_bf16 v[88:91], v[166:169], v[206:209], v[88:91]
	v_mfma_f32_16x16x32_bf16 v[80:83], v[174:177], v[206:209], v[80:83]
	v_mfma_f32_16x16x32_bf16 v[64:67], v[174:177], v[214:217], v[64:67]
	v_mfma_f32_16x16x32_bf16 v[72:75], v[166:169], v[214:217], v[72:75]
	s_setprio 0
	s_barrier
	s_add_i32 s50, s50, s75
	v_lshl_add_u64 v[140:141], s[30:31], 0, v[96:97]
	s_mov_b32 m0, s50
	ds_read_b128 v[178:181], v145 offset:16384
	ds_read_b128 v[182:185], v145 offset:17408
	ds_read_b128 v[186:189], v145 offset:18432
	ds_read_b128 v[190:193], v145 offset:19456
	ds_read_b128 v[202:205], v145 offset:20480
	ds_read_b128 v[206:209], v145 offset:21504
	ds_read_b128 v[210:213], v145 offset:22528
	ds_read_b128 v[214:217], v145 offset:23552
	global_load_lds_dwordx4 v[140:141], off
	s_add_i32 m0, s50, 0x2000
	s_add_u32 s50, s30, 0x40000
	v_lshl_add_u64 v[194:195], s[30:31], 0, v[130:131]
	s_addc_u32 s51, s31, 0
	s_add_i32 s56, s56, s75
	global_load_lds_dwordx4 v[194:195], off
	v_lshl_add_u64 v[218:219], s[50:51], 0, v[96:97]
	s_mov_b32 m0, s56
	v_lshl_add_u64 v[220:221], s[52:53], 0, v[134:135]
	global_load_lds_dwordx4 v[218:219], off
	v_lshl_add_u64 v[218:219], s[50:51], 0, v[130:131]
	s_add_i32 m0, s56, 0x2000
	s_nop 0
	global_load_lds_dwordx4 v[218:219], off
	v_lshl_add_u64 v[218:219], s[52:53], 0, v[132:133]
	s_mov_b32 m0, s79
	s_nop 0
	global_load_lds_dwordx4 v[218:219], off
	s_mov_b32 m0, s80
	s_nop 0
	global_load_lds_dwordx4 v[220:221], off
	s_waitcnt vmcnt(8)
	s_waitcnt lgkmcnt(0)
	s_barrier
; #define PG8_STAGE(bufoff, gbase, V0, V1) do { \
;         __builtin_amdgcn_global_load_lds((const unsigned*)((const char*)(gbase) + (V0)), (LAS unsigned*)(lds + (bufoff) + ldsw), 16, 0, 0); \
;         __builtin_amdgcn_global_load_lds((const unsigned*)((const char*)(gbase) + (V1)), (LAS unsigned*)(lds + (bufoff) + ldsw + 8192), 16, 0, 0); } while (0)
; #define PG8_LDA(dst, b, h) do { _Pragma("unroll") for (int m = 0; m < 4; ++m) _Pragma("unroll") for (int k = 0; k < 2; ++k) dst[m][k] = *(const LAS bf16x8*)(lds + PG8_SA(b, h) + aoff + m * 2048 + k * 1024); } while (0)
; #define PG8_LDB(dst, b, h) do { _Pragma("unroll") for (int n = 0; n < 2; ++n) _Pragma("unroll") for (int k = 0; k < 2; ++k) dst[n][k] = *(const LAS bf16x8*)(lds + PG8_SB(b, h) + boff + n * 2048 + k * 1024); } while (0)
; #define PG8_MMA(ai, bj, At, Bt) do { __builtin_amdgcn_s_setprio(1); _Pragma("unroll") for (int m = 0; m < 4; ++m) _Pragma("unroll") for (int n = 0; n < 2; ++n) _Pragma("unroll") for (int k = 0; k < 2; ++k) \
;         acc[ai][bj][m][n] = __builtin_amdgcn_mfma_f32_16x16x32_bf16(Bt[n][k], At[m][k], acc[ai][bj][m][n], 0, 0, 0); __builtin_amdgcn_s_setprio(0); } while (0)
; #define PG8_WAIT_V(n) asm volatile("s_waitcnt vmcnt(" #n ")" ::: "memory")
; #define PG8_WAIT_L(n) asm volatile("s_waitcnt lgkmcnt(" #n ")" ::: "memory")
; #define PG8_BAR __builtin_amdgcn_s_barrier()
; #define PG8_SCHED __builtin_amdgcn_sched_barrier(0)
; template <class Epi, class Sched>
; DI void gemm_phase(LAS unsigned char* lds, const int lda2, const int ldb2, const int nt, const Sched& S, const Epi& E) {
;     ...
;             PG8_LDB(B0, 0, 0); PG8_LDB(B1, 0, 1); PG8_SCHED; PG8_LDA(At, 0, 0); PG8_STAGE(PG8_SA(1, 1), a1 + hstepA, vA0, vA1);
;             PG8_WAIT_V(8); PG8_WAIT_L(0); PG8_BAR; PG8_MMA(0, 0, At, B0); PG8_MMA(0, 1, At, B1); PG8_BAR; PG8_SCHED;
;             PG8_LDA(At, 0, 1); PG8_STAGE(PG8_SB(0, 0), b2, vB0, vB1); PG8_STAGE(PG8_SB(0, 1), b2 + hstepB, vB0, vB1); PG8_STAGE(PG8_SA(0, 0), a2, vA0, vA1);
;             PG8_WAIT_V(8); PG8_WAIT_L(0); PG8_BAR; PG8_MMA(1, 0, At, B0); PG8_MMA(1, 1, At, B1); PG8_BAR; PG8_SCHED;
;             PG8_LDB(B0, 1, 0); PG8_LDB(B1, 1, 1); PG8_SCHED; PG8_LDA(At, 1, 0); PG8_STAGE(PG8_SA(0, 1), a2 + hstepA, vA0, vA1);
;             PG8_WAIT_V(8); PG8_WAIT_L(0); PG8_BAR; PG8_MMA(0, 0, At, B0); PG8_MMA(0, 1, At, B1); PG8_BAR; PG8_SCHED;
	s_setprio 1
	s_waitcnt lgkmcnt(0)
	v_mfma_f32_16x16x32_bf16 v[60:63], v[146:149], v[178:181], 0
	v_mfma_f32_16x16x32_bf16 v[52:55], v[154:157], v[178:181], 0
	v_mfma_f32_16x16x32_bf16 v[36:39], v[154:157], v[186:189], 0
	v_mfma_f32_16x16x32_bf16 v[44:47], v[146:149], v[186:189], 0
	v_mfma_f32_16x16x32_bf16 v[28:31], v[146:149], v[202:205], 0
	v_mfma_f32_16x16x32_bf16 v[20:23], v[154:157], v[202:205], 0
	v_mfma_f32_16x16x32_bf16 v[4:7], v[154:157], v[210:213], 0
	v_mfma_f32_16x16x32_bf16 v[12:15], v[146:149], v[210:213], 0
	v_mfma_f32_16x16x32_bf16 v[60:63], v[150:153], v[182:185], v[60:63]
	v_mfma_f32_16x16x32_bf16 v[52:55], v[158:161], v[182:185], v[52:55]
	v_mfma_f32_16x16x32_bf16 v[36:39], v[158:161], v[190:193], v[36:39]
	v_mfma_f32_16x16x32_bf16 v[44:47], v[150:153], v[190:193], v[44:47]
	v_mfma_f32_16x16x32_bf16 v[28:31], v[150:153], v[206:209], v[28:31]
	v_mfma_f32_16x16x32_bf16 v[20:23], v[158:161], v[206:209], v[20:23]
	v_mfma_f32_16x16x32_bf16 v[4:7], v[158:161], v[214:217], v[4:7]
	v_mfma_f32_16x16x32_bf16 v[12:15], v[150:153], v[214:217], v[12:15]
	s_setprio 0
	s_setprio 1
	v_mfma_f32_16x16x32_bf16 v[56:59], v[162:165], v[178:181], 0
	v_mfma_f32_16x16x32_bf16 v[48:51], v[170:173], v[178:181], 0
	v_mfma_f32_16x16x32_bf16 v[32:35], v[170:173], v[186:189], 0
	v_mfma_f32_16x16x32_bf16 v[40:43], v[162:165], v[186:189], 0
	v_mfma_f32_16x16x32_bf16 v[24:27], v[162:165], v[202:205], 0
	v_mfma_f32_16x16x32_bf16 v[16:19], v[170:173], v[202:205], 0
	v_mfma_f32_16x16x32_bf16 v[0:3], v[170:173], v[210:213], 0
	v_mfma_f32_16x16x32_bf16 v[8:11], v[162:165], v[210:213], 0
	v_mfma_f32_16x16x32_bf16 v[56:59], v[166:169], v[182:185], v[56:59]
	v_mfma_f32_16x16x32_bf16 v[48:51], v[174:177], v[182:185], v[48:51]
	v_mfma_f32_16x16x32_bf16 v[32:35], v[174:177], v[190:193], v[32:35]
	v_mfma_f32_16x16x32_bf16 v[40:43], v[166:169], v[190:193], v[40:43]
	v_mfma_f32_16x16x32_bf16 v[24:27], v[166:169], v[206:209], v[24:27]
	v_mfma_f32_16x16x32_bf16 v[16:19], v[174:177], v[206:209], v[16:19]
	v_mfma_f32_16x16x32_bf16 v[0:3], v[174:177], v[214:217], v[0:3]
	v_mfma_f32_16x16x32_bf16 v[8:11], v[166:169], v[214:217], v[8:11]
	s_setprio 0
	s_barrier
	s_add_i32 s56, 0, 0x18000
	s_add_i32 s57, 0, 0x1c000
	v_add_u32_e32 v158, s56, v144
	v_add_u32_e32 v174, s57, v144
	s_add_u32 s50, s52, 0x40000
	s_addc_u32 s51, s53, 0
	s_mov_b32 m0, s81
	v_lshl_add_u64 v[250:251], s[50:51], 0, v[132:133]
	s_nop 0
	global_load_lds_dwordx4 v[250:251], off
	v_lshl_add_u64 v[250:251], s[50:51], 0, v[134:135]
	s_mov_b32 m0, s82
	s_nop 0
	global_load_lds_dwordx4 v[250:251], off
	ds_read_b128 v[146:149], v158
	ds_read_b128 v[150:153], v158 offset:1024
	ds_read_b128 v[154:157], v158 offset:2048
	ds_read_b128 v[158:161], v158 offset:3072
	ds_read_b128 v[162:165], v174
	ds_read_b128 v[166:169], v174 offset:1024
	ds_read_b128 v[170:173], v174 offset:2048
	ds_read_b128 v[174:177], v174 offset:3072
	ds_read_b128 v[178:181], v145 offset:32768
	ds_read_b128 v[182:185], v145 offset:33792
	ds_read_b128 v[186:189], v145 offset:34816
	ds_read_b128 v[190:193], v145 offset:35840
	ds_read_b128 v[202:205], v145 offset:36864
	ds_read_b128 v[206:209], v145 offset:37888
	ds_read_b128 v[210:213], v145 offset:38912
	ds_read_b128 v[214:217], v145 offset:39936
	s_waitcnt vmcnt(8)
	s_waitcnt lgkmcnt(0)
	s_barrier
	s_setprio 1
	s_waitcnt lgkmcnt(0)
	v_mfma_f32_16x16x32_bf16 v[126:129], v[146:149], v[178:181], v[126:129]
	v_mfma_f32_16x16x32_bf16 v[118:121], v[154:157], v[178:181], v[118:121]
	v_mfma_f32_16x16x32_bf16 v[102:105], v[154:157], v[186:189], v[102:105]
	v_mfma_f32_16x16x32_bf16 v[110:113], v[146:149], v[186:189], v[110:113]
	v_mfma_f32_16x16x32_bf16 v[92:95], v[146:149], v[202:205], v[92:95]
	v_mfma_f32_16x16x32_bf16 v[84:87], v[154:157], v[202:205], v[84:87]
	v_mfma_f32_16x16x32_bf16 v[68:71], v[154:157], v[210:213], v[68:71]
	v_mfma_f32_16x16x32_bf16 v[76:79], v[146:149], v[210:213], v[76:79]
	v_mfma_f32_16x16x32_bf16 v[126:129], v[150:153], v[182:185], v[126:129]
	v_mfma_f32_16x16x32_bf16 v[118:121], v[158:161], v[182:185], v[118:121]
	v_mfma_f32_16x16x32_bf16 v[102:105], v[158:161], v[190:193], v[102:105]
	v_mfma_f32_16x16x32_bf16 v[110:113], v[150:153], v[190:193], v[110:113]
	v_mfma_f32_16x16x32_bf16 v[92:95], v[150:153], v[206:209], v[92:95]
	v_mfma_f32_16x16x32_bf16 v[84:87], v[158:161], v[206:209], v[84:87]
	v_mfma_f32_16x16x32_bf16 v[68:71], v[158:161], v[214:217], v[68:71]
	v_mfma_f32_16x16x32_bf16 v[76:79], v[150:153], v[214:217], v[76:79]
	s_setprio 0
	s_setprio 1
	v_mfma_f32_16x16x32_bf16 v[122:125], v[162:165], v[178:181], v[122:125]
	v_mfma_f32_16x16x32_bf16 v[114:117], v[170:173], v[178:181], v[114:117]
	v_mfma_f32_16x16x32_bf16 v[98:101], v[170:173], v[186:189], v[98:101]
	v_mfma_f32_16x16x32_bf16 v[106:109], v[162:165], v[186:189], v[106:109]
	v_mfma_f32_16x16x32_bf16 v[88:91], v[162:165], v[202:205], v[88:91]
	v_mfma_f32_16x16x32_bf16 v[80:83], v[170:173], v[202:205], v[80:83]
	v_mfma_f32_16x16x32_bf16 v[64:67], v[170:173], v[210:213], v[64:67]
	v_mfma_f32_16x16x32_bf16 v[72:75], v[162:165], v[210:213], v[72:75]
	v_mfma_f32_16x16x32_bf16 v[122:125], v[166:169], v[182:185], v[122:125]
	v_mfma_f32_16x16x32_bf16 v[114:117], v[174:177], v[182:185], v[114:117]
	v_mfma_f32_16x16x32_bf16 v[98:101], v[174:177], v[190:193], v[98:101]
	v_mfma_f32_16x16x32_bf16 v[106:109], v[166:169], v[190:193], v[106:109]
	v_mfma_f32_16x16x32_bf16 v[88:91], v[166:169], v[206:209], v[88:91]
	v_mfma_f32_16x16x32_bf16 v[80:83], v[174:177], v[206:209], v[80:83]
	v_mfma_f32_16x16x32_bf16 v[64:67], v[174:177], v[214:217], v[64:67]
	v_mfma_f32_16x16x32_bf16 v[72:75], v[166:169], v[214:217], v[72:75]
	s_setprio 0
	s_barrier
; #define PG8_STAGE(bufoff, gbase, V0, V1) do { \
;         __builtin_amdgcn_global_load_lds((const unsigned*)((const char*)(gbase) + (V0)), (LAS unsigned*)(lds + (bufoff) + ldsw), 16, 0, 0); \
;         __builtin_amdgcn_global_load_lds((const unsigned*)((const char*)(gbase) + (V1)), (LAS unsigned*)(lds + (bufoff) + ldsw + 8192), 16, 0, 0); } while (0)
; #define PG8_LDA(dst, b, h) do { _Pragma("unroll") for (int m = 0; m < 4; ++m) _Pragma("unroll") for (int k = 0; k < 2; ++k) dst[m][k] = *(const LAS bf16x8*)(lds + PG8_SA(b, h) + aoff + m * 2048 + k * 1024); } while (0)
; #define PG8_WAIT_V(n) asm volatile("s_waitcnt vmcnt(" #n ")" ::: "memory")
; template <class Epi, class Sched>
; DI void gemm_phase(LAS unsigned char* lds, const int lda2, const int ldb2, const int nt, const Sched& S, const Epi& E) {
;     ...
;         const bool has_next = S.next(ui + 1, nxt);
;         const char* nA = has_next ? nxt.A : cA; const char* nB = has_next ? nxt.B : cB;
;         for (int t = 0; t < nt; t += 2) {
;             const bool last = (t == nt - 2);
;             const char* a1 = cA + (size_t)(t + 1) * kstep;
;             const char* a2 = last ? nA : cA + (size_t)(t + 2) * kstep; const char* b2 = last ? nB : cB + (size_t)(t + 2) * kstep;
;             const char* a3 = a2 + kstep; const char* b3 = b2 + kstep;
;             PG8_LDB(B0, 0, 0); PG8_LDB(B1, 0, 1); PG8_SCHED; PG8_LDA(At, 0, 0); PG8_STAGE(PG8_SA(1, 1), a1 + hstepA, vA0, vA1);
;             PG8_WAIT_V(8); PG8_WAIT_L(0); PG8_BAR; PG8_MMA(0, 0, At, B0); PG8_MMA(0, 1, At, B1); PG8_BAR; PG8_SCHED;
;             PG8_LDA(At, 0, 1); PG8_STAGE(PG8_SB(0, 0), b2, vB0, vB1); PG8_STAGE(PG8_SB(0, 1), b2 + hstepB, vB0, vB1); PG8_STAGE(PG8_SA(0, 0), a2, vA0, vA1);
;             PG8_WAIT_V(8); PG8_WAIT_L(0); PG8_BAR; PG8_MMA(1, 0, At, B0); PG8_MMA(1, 1, At, B1); PG8_BAR; PG8_SCHED;
;             PG8_LDB(B0, 1, 0); PG8_LDB(B1, 1, 1); PG8_SCHED; PG8_LDA(At, 1, 0); PG8_STAGE(PG8_SA(0, 1), a2 + hstepA, vA0, vA1);
;             PG8_WAIT_V(8); PG8_WAIT_L(0); PG8_BAR; PG8_MMA(0, 0, At, B0); PG8_MMA(0, 1, At, B1); PG8_BAR; PG8_SCHED;
;             PG8_LDA(At, 1, 1); PG8_STAGE(PG8_SB(1, 0), b3, vB0, vB1); PG8_STAGE(PG8_SB(1, 1), b3 + hstepB, vB0, vB1); PG8_STAGE(PG8_SA(1, 0), a3, vA0, vA1);
;             PG8_WAIT_V(8); PG8_WAIT_L(0); PG8_BAR; PG8_MMA(1, 0, At, B0); PG8_MMA(1, 1, At, B1); PG8_BAR; PG8_SCHED;
	s_add_i32 s50, s56, s75
	v_lshl_add_u64 v[140:141], v[140:141], 0, s[86:87]
	s_mov_b32 m0, s50
	ds_read_b128 v[178:181], v145 offset:49152
	ds_read_b128 v[182:185], v145 offset:50176
	ds_read_b128 v[186:189], v145 offset:51200
	ds_read_b128 v[190:193], v145 offset:52224
	ds_read_b128 v[202:205], v145 offset:53248
	ds_read_b128 v[206:209], v145 offset:54272
	ds_read_b128 v[210:213], v145 offset:55296
	ds_read_b128 v[214:217], v145 offset:56320
	global_load_lds_dwordx4 v[140:141], off
	s_add_i32 m0, s50, 0x2000
	s_add_u32 s30, s30, 0x40080
	v_lshl_add_u64 v[140:141], v[194:195], 0, s[86:87]
	s_addc_u32 s31, s31, 0
	s_add_i32 s50, s57, s75
	global_load_lds_dwordx4 v[140:141], off
	v_lshl_add_u64 v[140:141], s[30:31], 0, v[96:97]
	s_mov_b32 m0, s50
	s_nop 0
	global_load_lds_dwordx4 v[140:141], off
	v_lshl_add_u64 v[140:141], s[30:31], 0, v[130:131]
	s_add_i32 m0, s50, 0x2000
	s_nop 0
	global_load_lds_dwordx4 v[140:141], off
	v_lshl_add_u64 v[140:141], v[218:219], 0, s[86:87]
	s_mov_b32 m0, s85
	s_nop 0
	global_load_lds_dwordx4 v[140:141], off
	v_lshl_add_u64 v[140:141], v[220:221], 0, s[86:87]
	s_mov_b32 m0, s14
	s_nop 0
	global_load_lds_dwordx4 v[140:141], off
	s_waitcnt vmcnt(8)
	s_waitcnt lgkmcnt(0)
	s_barrier
	s_setprio 1
	s_waitcnt lgkmcnt(0)
	v_mfma_f32_16x16x32_bf16 v[60:63], v[146:149], v[178:181], v[60:63]
	v_mfma_f32_16x16x32_bf16 v[52:55], v[154:157], v[178:181], v[52:55]
	v_mfma_f32_16x16x32_bf16 v[36:39], v[154:157], v[186:189], v[36:39]
	v_mfma_f32_16x16x32_bf16 v[44:47], v[146:149], v[186:189], v[44:47]
	v_mfma_f32_16x16x32_bf16 v[28:31], v[146:149], v[202:205], v[28:31]
	v_mfma_f32_16x16x32_bf16 v[20:23], v[154:157], v[202:205], v[20:23]
	v_mfma_f32_16x16x32_bf16 v[4:7], v[154:157], v[210:213], v[4:7]
	v_mfma_f32_16x16x32_bf16 v[12:15], v[146:149], v[210:213], v[12:15]
	v_mfma_f32_16x16x32_bf16 v[60:63], v[150:153], v[182:185], v[60:63]
	v_mfma_f32_16x16x32_bf16 v[52:55], v[158:161], v[182:185], v[52:55]
	v_mfma_f32_16x16x32_bf16 v[36:39], v[158:161], v[190:193], v[36:39]
	v_mfma_f32_16x16x32_bf16 v[44:47], v[150:153], v[190:193], v[44:47]
	v_mfma_f32_16x16x32_bf16 v[28:31], v[150:153], v[206:209], v[28:31]
	v_mfma_f32_16x16x32_bf16 v[20:23], v[158:161], v[206:209], v[20:23]
	v_mfma_f32_16x16x32_bf16 v[4:7], v[158:161], v[214:217], v[4:7]
	v_mfma_f32_16x16x32_bf16 v[12:15], v[150:153], v[214:217], v[12:15]
	s_setprio 0
	s_setprio 1
	v_mfma_f32_16x16x32_bf16 v[56:59], v[162:165], v[178:181], v[56:59]
	v_mfma_f32_16x16x32_bf16 v[48:51], v[170:173], v[178:181], v[48:51]
	v_mfma_f32_16x16x32_bf16 v[32:35], v[170:173], v[186:189], v[32:35]
	v_mfma_f32_16x16x32_bf16 v[40:43], v[162:165], v[186:189], v[40:43]
	v_mfma_f32_16x16x32_bf16 v[24:27], v[162:165], v[202:205], v[24:27]
	v_mfma_f32_16x16x32_bf16 v[16:19], v[170:173], v[202:205], v[16:19]
	v_mfma_f32_16x16x32_bf16 v[0:3], v[170:173], v[210:213], v[0:3]
	v_mfma_f32_16x16x32_bf16 v[8:11], v[162:165], v[210:213], v[8:11]
	v_mfma_f32_16x16x32_bf16 v[56:59], v[166:169], v[182:185], v[56:59]
	v_mfma_f32_16x16x32_bf16 v[48:51], v[174:177], v[182:185], v[48:51]
	v_mfma_f32_16x16x32_bf16 v[32:35], v[174:177], v[190:193], v[32:35]
	v_mfma_f32_16x16x32_bf16 v[40:43], v[166:169], v[190:193], v[40:43]
	v_mfma_f32_16x16x32_bf16 v[24:27], v[166:169], v[206:209], v[24:27]
	v_mfma_f32_16x16x32_bf16 v[16:19], v[174:177], v[206:209], v[16:19]
	v_mfma_f32_16x16x32_bf16 v[0:3], v[174:177], v[214:217], v[0:3]
	v_mfma_f32_16x16x32_bf16 v[8:11], v[166:169], v[214:217], v[8:11]
	s_setprio 0
	s_barrier
	s_add_i32 s27, s27, 2
	s_add_u32 s28, s28, 0x100
	s_addc_u32 s29, s29, 0
	s_add_u32 s19, s19, 0x100
	s_addc_u32 s21, s21, 0
.LBB0_1053:
	s_add_u32 s30, s28, 0xfffc0080
	s_addc_u32 s31, s29, -1
	s_add_i32 s50, 0, 0x10000
	s_cmp_eq_u32 s27, 12
	s_cselect_b32 s53, s23, s31
	s_cselect_b32 s52, s22, s30
	v_add_u32_e32 v140, s50, v144
	s_cselect_b32 s31, s25, s21
	s_cselect_b32 s30, s24, s19
	s_add_i32 s56, 0, 0x14000
	v_lshl_add_u64 v[250:251], s[28:29], 0, v[136:137]
	s_add_i32 m0, s79, 0xc000
	s_nop 0
	global_load_lds_dwordx4 v[250:251], off
	v_lshl_add_u64 v[250:251], s[28:29], 0, v[138:139]
	s_add_i32 m0, s79, 0xe000
	s_nop 0
	global_load_lds_dwordx4 v[250:251], off
	ds_read_b128 v[146:149], v140
	ds_read_b128 v[150:153], v140 offset:1024
	ds_read_b128 v[154:157], v140 offset:2048
	ds_read_b128 v[158:161], v140 offset:3072
	v_add_u32_e32 v140, s56, v144
	ds_read_b128 v[162:165], v140
	ds_read_b128 v[166:169], v140 offset:1024
	ds_read_b128 v[170:173], v140 offset:2048
	ds_read_b128 v[174:177], v140 offset:3072
	ds_read_b128 v[178:181], v145
	ds_read_b128 v[182:185], v145 offset:1024
	ds_read_b128 v[186:189], v145 offset:2048
	ds_read_b128 v[190:193], v145 offset:3072
	ds_read_b128 v[202:205], v145 offset:4096
	ds_read_b128 v[206:209], v145 offset:5120
	ds_read_b128 v[210:213], v145 offset:6144
	ds_read_b128 v[214:217], v145 offset:7168
	s_waitcnt vmcnt(8)
	s_waitcnt lgkmcnt(0)
	s_barrier
; #define PG8_STAGE(bufoff, gbase, V0, V1) do { \
;         __builtin_amdgcn_global_load_lds((const unsigned*)((const char*)(gbase) + (V0)), (LAS unsigned*)(lds + (bufoff) + ldsw), 16, 0, 0); \
;         __builtin_amdgcn_global_load_lds((const unsigned*)((const char*)(gbase) + (V1)), (LAS unsigned*)(lds + (bufoff) + ldsw + 8192), 16, 0, 0); } while (0)
; #define PG8_LDA(dst, b, h) do { _Pragma("unroll") for (int m = 0; m < 4; ++m) _Pragma("unroll") for (int k = 0; k < 2; ++k) dst[m][k] = *(const LAS bf16x8*)(lds + PG8_SA(b, h) + aoff + m * 2048 + k * 1024); } while (0)
; #define PG8_LDB(dst, b, h) do { _Pragma("unroll") for (int n = 0; n < 2; ++n) _Pragma("unroll") for (int k = 0; k < 2; ++k) dst[n][k] = *(const LAS bf16x8*)(lds + PG8_SB(b, h) + boff + n * 2048 + k * 1024); } while (0)
; #define PG8_MMA(ai, bj, At, Bt) do { __builtin_amdgcn_s_setprio(1); _Pragma("unroll") for (int m = 0; m < 4; ++m) _Pragma("unroll") for (int n = 0; n < 2; ++n) _Pragma("unroll") for (int k = 0; k < 2; ++k) \
;         acc[ai][bj][m][n] = __builtin_amdgcn_mfma_f32_16x16x32_bf16(Bt[n][k], At[m][k], acc[ai][bj][m][n], 0, 0, 0); __builtin_amdgcn_s_setprio(0); } while (0)
; #define PG8_WAIT_V(n) asm volatile("s_waitcnt vmcnt(" #n ")" ::: "memory")
; #define PG8_WAIT_L(n) asm volatile("s_waitcnt lgkmcnt(" #n ")" ::: "memory")
; #define PG8_BAR __builtin_amdgcn_s_barrier()
; #define PG8_SCHED __builtin_amdgcn_sched_barrier(0)
; template <class Epi, class Sched>
; DI void gemm_phase(LAS unsigned char* lds, const int lda2, const int ldb2, const int nt, const Sched& S, const Epi& E) {
;     ...
;             PG8_LDB(B0, 0, 0); PG8_LDB(B1, 0, 1); PG8_SCHED; PG8_LDA(At, 0, 0); PG8_STAGE(PG8_SA(1, 1), a1 + hstepA, vA0, vA1);
;             PG8_WAIT_V(8); PG8_WAIT_L(0); PG8_BAR; PG8_MMA(0, 0, At, B0); PG8_MMA(0, 1, At, B1); PG8_BAR; PG8_SCHED;
;             PG8_LDA(At, 0, 1); PG8_STAGE(PG8_SB(0, 0), b2, vB0, vB1); PG8_STAGE(PG8_SB(0, 1), b2 + hstepB, vB0, vB1); PG8_STAGE(PG8_SA(0, 0), a2, vA0, vA1);
;             PG8_WAIT_V(8); PG8_WAIT_L(0); PG8_BAR; PG8_MMA(1, 0, At, B0); PG8_MMA(1, 1, At, B1); PG8_BAR; PG8_SCHED;
	s_setprio 1
	s_waitcnt lgkmcnt(0)
	v_mfma_f32_16x16x32_bf16 v[126:129], v[146:149], v[178:181], v[126:129]
	v_mfma_f32_16x16x32_bf16 v[118:121], v[154:157], v[178:181], v[118:121]
	v_mfma_f32_16x16x32_bf16 v[102:105], v[154:157], v[186:189], v[102:105]
	v_mfma_f32_16x16x32_bf16 v[110:113], v[146:149], v[186:189], v[110:113]
	v_mfma_f32_16x16x32_bf16 v[92:95], v[146:149], v[202:205], v[92:95]
	v_mfma_f32_16x16x32_bf16 v[84:87], v[154:157], v[202:205], v[84:87]
	v_mfma_f32_16x16x32_bf16 v[68:71], v[154:157], v[210:213], v[68:71]
	v_mfma_f32_16x16x32_bf16 v[76:79], v[146:149], v[210:213], v[76:79]
	v_mfma_f32_16x16x32_bf16 v[126:129], v[150:153], v[182:185], v[126:129]
	v_mfma_f32_16x16x32_bf16 v[118:121], v[158:161], v[182:185], v[118:121]
	v_mfma_f32_16x16x32_bf16 v[102:105], v[158:161], v[190:193], v[102:105]
	v_mfma_f32_16x16x32_bf16 v[110:113], v[150:153], v[190:193], v[110:113]
	v_mfma_f32_16x16x32_bf16 v[92:95], v[150:153], v[206:209], v[92:95]
	v_mfma_f32_16x16x32_bf16 v[84:87], v[158:161], v[206:209], v[84:87]
	v_mfma_f32_16x16x32_bf16 v[68:71], v[158:161], v[214:217], v[68:71]
	v_mfma_f32_16x16x32_bf16 v[76:79], v[150:153], v[214:217], v[76:79]
	s_setprio 0
	s_setprio 1
	v_mfma_f32_16x16x32_bf16 v[122:125], v[162:165], v[178:181], v[122:125]
	v_mfma_f32_16x16x32_bf16 v[114:117], v[170:173], v[178:181], v[114:117]
	v_mfma_f32_16x16x32_bf16 v[98:101], v[170:173], v[186:189], v[98:101]
	v_mfma_f32_16x16x32_bf16 v[106:109], v[162:165], v[186:189], v[106:109]
	v_mfma_f32_16x16x32_bf16 v[88:91], v[162:165], v[202:205], v[88:91]
	v_mfma_f32_16x16x32_bf16 v[80:83], v[170:173], v[202:205], v[80:83]
	v_mfma_f32_16x16x32_bf16 v[64:67], v[170:173], v[210:213], v[64:67]
	v_mfma_f32_16x16x32_bf16 v[72:75], v[162:165], v[210:213], v[72:75]
	v_mfma_f32_16x16x32_bf16 v[122:125], v[166:169], v[182:185], v[122:125]
	v_mfma_f32_16x16x32_bf16 v[114:117], v[174:177], v[182:185], v[114:117]
	v_mfma_f32_16x16x32_bf16 v[98:101], v[174:177], v[190:193], v[98:101]
	v_mfma_f32_16x16x32_bf16 v[106:109], v[166:169], v[190:193], v[106:109]
	v_mfma_f32_16x16x32_bf16 v[88:91], v[166:169], v[206:209], v[88:91]
	v_mfma_f32_16x16x32_bf16 v[80:83], v[174:177], v[206:209], v[80:83]
	v_mfma_f32_16x16x32_bf16 v[64:67], v[174:177], v[214:217], v[64:67]
	v_mfma_f32_16x16x32_bf16 v[72:75], v[166:169], v[214:217], v[72:75]
	s_setprio 0
	s_barrier
	s_add_i32 s50, s50, s75
	v_lshl_add_u64 v[140:141], s[30:31], 0, v[96:97]
	s_mov_b32 m0, s50
	ds_read_b128 v[178:181], v145 offset:16384
	ds_read_b128 v[182:185], v145 offset:17408
	ds_read_b128 v[186:189], v145 offset:18432
	ds_read_b128 v[190:193], v145 offset:19456
	ds_read_b128 v[202:205], v145 offset:20480
	ds_read_b128 v[206:209], v145 offset:21504
	ds_read_b128 v[210:213], v145 offset:22528
	ds_read_b128 v[214:217], v145 offset:23552
	global_load_lds_dwordx4 v[140:141], off
	s_add_i32 m0, s50, 0x2000
	s_add_u32 s50, s30, 0x40000
	v_lshl_add_u64 v[194:195], s[30:31], 0, v[130:131]
	s_addc_u32 s51, s31, 0
	s_add_i32 s56, s56, s75
	global_load_lds_dwordx4 v[194:195], off
	v_lshl_add_u64 v[218:219], s[50:51], 0, v[96:97]
	s_mov_b32 m0, s56
	v_lshl_add_u64 v[220:221], s[52:53], 0, v[134:135]
	global_load_lds_dwordx4 v[218:219], off
	v_lshl_add_u64 v[218:219], s[50:51], 0, v[130:131]
	s_add_i32 m0, s56, 0x2000
	s_nop 0
	global_load_lds_dwordx4 v[218:219], off
	v_lshl_add_u64 v[218:219], s[52:53], 0, v[132:133]
	s_mov_b32 m0, s79
	s_nop 0
	global_load_lds_dwordx4 v[218:219], off
	s_mov_b32 m0, s80
	s_nop 0
	global_load_lds_dwordx4 v[220:221], off
	s_waitcnt vmcnt(8)
	s_waitcnt lgkmcnt(0)
	s_barrier
	s_setprio 1
	s_waitcnt lgkmcnt(0)
	v_mfma_f32_16x16x32_bf16 v[60:63], v[146:149], v[178:181], v[60:63]
	v_mfma_f32_16x16x32_bf16 v[52:55], v[154:157], v[178:181], v[52:55]
	v_mfma_f32_16x16x32_bf16 v[36:39], v[154:157], v[186:189], v[36:39]
	v_mfma_f32_16x16x32_bf16 v[44:47], v[146:149], v[186:189], v[44:47]
	v_mfma_f32_16x16x32_bf16 v[28:31], v[146:149], v[202:205], v[28:31]
	v_mfma_f32_16x16x32_bf16 v[20:23], v[154:157], v[202:205], v[20:23]
	v_mfma_f32_16x16x32_bf16 v[4:7], v[154:157], v[210:213], v[4:7]
	v_mfma_f32_16x16x32_bf16 v[12:15], v[146:149], v[210:213], v[12:15]
	v_mfma_f32_16x16x32_bf16 v[60:63], v[150:153], v[182:185], v[60:63]
	v_mfma_f32_16x16x32_bf16 v[52:55], v[158:161], v[182:185], v[52:55]
	v_mfma_f32_16x16x32_bf16 v[36:39], v[158:161], v[190:193], v[36:39]
	v_mfma_f32_16x16x32_bf16 v[44:47], v[150:153], v[190:193], v[44:47]
	v_mfma_f32_16x16x32_bf16 v[28:31], v[150:153], v[206:209], v[28:31]
	v_mfma_f32_16x16x32_bf16 v[20:23], v[158:161], v[206:209], v[20:23]
	v_mfma_f32_16x16x32_bf16 v[4:7], v[158:161], v[214:217], v[4:7]
	v_mfma_f32_16x16x32_bf16 v[12:15], v[150:153], v[214:217], v[12:15]
	s_setprio 0
	s_setprio 1
	v_mfma_f32_16x16x32_bf16 v[56:59], v[162:165], v[178:181], v[56:59]
	v_mfma_f32_16x16x32_bf16 v[48:51], v[170:173], v[178:181], v[48:51]
	v_mfma_f32_16x16x32_bf16 v[32:35], v[170:173], v[186:189], v[32:35]
	v_mfma_f32_16x16x32_bf16 v[40:43], v[162:165], v[186:189], v[40:43]
	v_mfma_f32_16x16x32_bf16 v[24:27], v[162:165], v[202:205], v[24:27]
	v_mfma_f32_16x16x32_bf16 v[16:19], v[170:173], v[202:205], v[16:19]
	v_mfma_f32_16x16x32_bf16 v[0:3], v[170:173], v[210:213], v[0:3]
	v_mfma_f32_16x16x32_bf16 v[8:11], v[162:165], v[210:213], v[8:11]
	v_mfma_f32_16x16x32_bf16 v[56:59], v[166:169], v[182:185], v[56:59]
	v_mfma_f32_16x16x32_bf16 v[48:51], v[174:177], v[182:185], v[48:51]
	v_mfma_f32_16x16x32_bf16 v[32:35], v[174:177], v[190:193], v[32:35]
	v_mfma_f32_16x16x32_bf16 v[40:43], v[166:169], v[190:193], v[40:43]
	v_mfma_f32_16x16x32_bf16 v[24:27], v[166:169], v[206:209], v[24:27]
	v_mfma_f32_16x16x32_bf16 v[16:19], v[174:177], v[206:209], v[16:19]
	v_mfma_f32_16x16x32_bf16 v[0:3], v[174:177], v[214:217], v[0:3]
	v_mfma_f32_16x16x32_bf16 v[8:11], v[166:169], v[214:217], v[8:11]
	s_setprio 0
	s_barrier
; #define PG8_STAGE(bufoff, gbase, V0, V1) do { \
;         __builtin_amdgcn_global_load_lds((const unsigned*)((const char*)(gbase) + (V0)), (LAS unsigned*)(lds + (bufoff) + ldsw), 16, 0, 0); \
;         __builtin_amdgcn_global_load_lds((const unsigned*)((const char*)(gbase) + (V1)), (LAS unsigned*)(lds + (bufoff) + ldsw + 8192), 16, 0, 0); } while (0)
; #define PG8_LDA(dst, b, h) do { _Pragma("unroll") for (int m = 0; m < 4; ++m) _Pragma("unroll") for (int k = 0; k < 2; ++k) dst[m][k] = *(const LAS bf16x8*)(lds + PG8_SA(b, h) + aoff + m * 2048 + k * 1024); } while (0)
; #define PG8_LDB(dst, b, h) do { _Pragma("unroll") for (int n = 0; n < 2; ++n) _Pragma("unroll") for (int k = 0; k < 2; ++k) dst[n][k] = *(const LAS bf16x8*)(lds + PG8_SB(b, h) + boff + n * 2048 + k * 1024); } while (0)
; #define PG8_MMA(ai, bj, At, Bt) do { __builtin_amdgcn_s_setprio(1); _Pragma("unroll") for (int m = 0; m < 4; ++m) _Pragma("unroll") for (int n = 0; n < 2; ++n) _Pragma("unroll") for (int k = 0; k < 2; ++k) \
;         acc[ai][bj][m][n] = __builtin_amdgcn_mfma_f32_16x16x32_bf16(Bt[n][k], At[m][k], acc[ai][bj][m][n], 0, 0, 0); __builtin_amdgcn_s_setprio(0); } while (0)
; #define PG8_WAIT_V(n) asm volatile("s_waitcnt vmcnt(" #n ")" ::: "memory")
; #define PG8_WAIT_L(n) asm volatile("s_waitcnt lgkmcnt(" #n ")" ::: "memory")
; #define PG8_BAR __builtin_amdgcn_s_barrier()
; #define PG8_SCHED __builtin_amdgcn_sched_barrier(0)
; template <class Epi, class Sched>
; DI void gemm_phase(LAS unsigned char* lds, const int lda2, const int ldb2, const int nt, const Sched& S, const Epi& E) {
;     ...
;             PG8_LDB(B0, 1, 0); PG8_LDB(B1, 1, 1); PG8_SCHED; PG8_LDA(At, 1, 0); PG8_STAGE(PG8_SA(0, 1), a2 + hstepA, vA0, vA1);
;             PG8_WAIT_V(8); PG8_WAIT_L(0); PG8_BAR; PG8_MMA(0, 0, At, B0); PG8_MMA(0, 1, At, B1); PG8_BAR; PG8_SCHED;
	s_add_i32 s56, 0, 0x18000
	s_add_i32 s57, 0, 0x1c000
	v_add_u32_e32 v158, s56, v144
	v_add_u32_e32 v174, s57, v144
	s_add_u32 s50, s52, 0x40000
	s_addc_u32 s51, s53, 0
	s_mov_b32 m0, s81
	v_lshl_add_u64 v[250:251], s[50:51], 0, v[132:133]
	s_nop 0
	global_load_lds_dwordx4 v[250:251], off
	v_lshl_add_u64 v[250:251], s[50:51], 0, v[134:135]
	s_mov_b32 m0, s82
	s_nop 0
	global_load_lds_dwordx4 v[250:251], off
	ds_read_b128 v[146:149], v158
	ds_read_b128 v[150:153], v158 offset:1024
	ds_read_b128 v[154:157], v158 offset:2048
	ds_read_b128 v[158:161], v158 offset:3072
	ds_read_b128 v[162:165], v174
	ds_read_b128 v[166:169], v174 offset:1024
	ds_read_b128 v[170:173], v174 offset:2048
	ds_read_b128 v[174:177], v174 offset:3072
	ds_read_b128 v[178:181], v145 offset:32768
	ds_read_b128 v[182:185], v145 offset:33792
	ds_read_b128 v[186:189], v145 offset:34816
	ds_read_b128 v[190:193], v145 offset:35840
	ds_read_b128 v[202:205], v145 offset:36864
	ds_read_b128 v[206:209], v145 offset:37888
	ds_read_b128 v[210:213], v145 offset:38912
	ds_read_b128 v[214:217], v145 offset:39936
	s_waitcnt vmcnt(8)
	s_waitcnt lgkmcnt(0)
	s_barrier
	s_setprio 1
	s_waitcnt lgkmcnt(0)
	v_mfma_f32_16x16x32_bf16 v[126:129], v[146:149], v[178:181], v[126:129]
	v_mfma_f32_16x16x32_bf16 v[118:121], v[154:157], v[178:181], v[118:121]
	v_mfma_f32_16x16x32_bf16 v[102:105], v[154:157], v[186:189], v[102:105]
	v_mfma_f32_16x16x32_bf16 v[110:113], v[146:149], v[186:189], v[110:113]
	v_mfma_f32_16x16x32_bf16 v[92:95], v[146:149], v[202:205], v[92:95]
	v_mfma_f32_16x16x32_bf16 v[84:87], v[154:157], v[202:205], v[84:87]
	v_mfma_f32_16x16x32_bf16 v[68:71], v[154:157], v[210:213], v[68:71]
	v_mfma_f32_16x16x32_bf16 v[76:79], v[146:149], v[210:213], v[76:79]
	v_mfma_f32_16x16x32_bf16 v[126:129], v[150:153], v[182:185], v[126:129]
	v_mfma_f32_16x16x32_bf16 v[118:121], v[158:161], v[182:185], v[118:121]
	v_mfma_f32_16x16x32_bf16 v[102:105], v[158:161], v[190:193], v[102:105]
	v_mfma_f32_16x16x32_bf16 v[110:113], v[150:153], v[190:193], v[110:113]
	v_mfma_f32_16x16x32_bf16 v[92:95], v[150:153], v[206:209], v[92:95]
	v_mfma_f32_16x16x32_bf16 v[84:87], v[158:161], v[206:209], v[84:87]
	v_mfma_f32_16x16x32_bf16 v[68:71], v[158:161], v[214:217], v[68:71]
	v_mfma_f32_16x16x32_bf16 v[76:79], v[150:153], v[214:217], v[76:79]
	s_setprio 0
	s_setprio 1
	v_mfma_f32_16x16x32_bf16 v[122:125], v[162:165], v[178:181], v[122:125]
	v_mfma_f32_16x16x32_bf16 v[114:117], v[170:173], v[178:181], v[114:117]
	v_mfma_f32_16x16x32_bf16 v[98:101], v[170:173], v[186:189], v[98:101]
	v_mfma_f32_16x16x32_bf16 v[106:109], v[162:165], v[186:189], v[106:109]
	v_mfma_f32_16x16x32_bf16 v[88:91], v[162:165], v[202:205], v[88:91]
	v_mfma_f32_16x16x32_bf16 v[80:83], v[170:173], v[202:205], v[80:83]
	v_mfma_f32_16x16x32_bf16 v[64:67], v[170:173], v[210:213], v[64:67]
	v_mfma_f32_16x16x32_bf16 v[72:75], v[162:165], v[210:213], v[72:75]
	v_mfma_f32_16x16x32_bf16 v[122:125], v[166:169], v[182:185], v[122:125]
	v_mfma_f32_16x16x32_bf16 v[114:117], v[174:177], v[182:185], v[114:117]
	v_mfma_f32_16x16x32_bf16 v[98:101], v[174:177], v[190:193], v[98:101]
	v_mfma_f32_16x16x32_bf16 v[106:109], v[166:169], v[190:193], v[106:109]
	v_mfma_f32_16x16x32_bf16 v[88:91], v[166:169], v[206:209], v[88:91]
	v_mfma_f32_16x16x32_bf16 v[80:83], v[174:177], v[206:209], v[80:83]
	v_mfma_f32_16x16x32_bf16 v[64:67], v[174:177], v[214:217], v[64:67]
	v_mfma_f32_16x16x32_bf16 v[72:75], v[166:169], v[214:217], v[72:75]
	s_setprio 0
	s_barrier
; #define PG8_STAGE(bufoff, gbase, V0, V1) do { \
;         __builtin_amdgcn_global_load_lds((const unsigned*)((const char*)(gbase) + (V0)), (LAS unsigned*)(lds + (bufoff) + ldsw), 16, 0, 0); \
;         __builtin_amdgcn_global_load_lds((const unsigned*)((const char*)(gbase) + (V1)), (LAS unsigned*)(lds + (bufoff) + ldsw + 8192), 16, 0, 0); } while (0)
; #define PG8_LDA(dst, b, h) do { _Pragma("unroll") for (int m = 0; m < 4; ++m) _Pragma("unroll") for (int k = 0; k < 2; ++k) dst[m][k] = *(const LAS bf16x8*)(lds + PG8_SA(b, h) + aoff + m * 2048 + k * 1024); } while (0)
; #define PG8_MMA(ai, bj, At, Bt) do { __builtin_amdgcn_s_setprio(1); _Pragma("unroll") for (int m = 0; m < 4; ++m) _Pragma("unroll") for (int n = 0; n < 2; ++n) _Pragma("unroll") for (int k = 0; k < 2; ++k) \
;         acc[ai][bj][m][n] = __builtin_amdgcn_mfma_f32_16x16x32_bf16(Bt[n][k], At[m][k], acc[ai][bj][m][n], 0, 0, 0); __builtin_amdgcn_s_setprio(0); } while (0)
; #define PG8_WAIT_V(n) asm volatile("s_waitcnt vmcnt(" #n ")" ::: "memory")
; #define PG8_WAIT_L(n) asm volatile("s_waitcnt lgkmcnt(" #n ")" ::: "memory")
; #define PG8_BAR __builtin_amdgcn_s_barrier()
; #define PG8_SCHED __builtin_amdgcn_sched_barrier(0)
; template <class Epi, class Sched>
; DI void gemm_phase(LAS unsigned char* lds, const int lda2, const int ldb2, const int nt, const Sched& S, const Epi& E) {
;     ...
;             PG8_LDA(At, 1, 1); PG8_STAGE(PG8_SB(1, 0), b3, vB0, vB1); PG8_STAGE(PG8_SB(1, 1), b3 + hstepB, vB0, vB1); PG8_STAGE(PG8_SA(1, 0), a3, vA0, vA1);
;             PG8_WAIT_V(8); PG8_WAIT_L(0); PG8_BAR; PG8_MMA(1, 0, At, B0); PG8_MMA(1, 1, At, B1); PG8_BAR; PG8_SCHED;
;         }
;         if (wr == 0) PG8_BAR;
	s_add_i32 s50, s56, s75
	v_lshl_add_u64 v[140:141], v[140:141], 0, s[86:87]
	s_mov_b32 m0, s50
	ds_read_b128 v[178:181], v145 offset:49152
	ds_read_b128 v[182:185], v145 offset:50176
	ds_read_b128 v[186:189], v145 offset:51200
	ds_read_b128 v[190:193], v145 offset:52224
	ds_read_b128 v[202:205], v145 offset:53248
	ds_read_b128 v[206:209], v145 offset:54272
	ds_read_b128 v[210:213], v145 offset:55296
	ds_read_b128 v[214:217], v145 offset:56320
	global_load_lds_dwordx4 v[140:141], off
	s_add_i32 m0, s50, 0x2000
	s_add_u32 s30, s30, 0x40080
	v_lshl_add_u64 v[140:141], v[194:195], 0, s[86:87]
	s_addc_u32 s31, s31, 0
	s_add_i32 s50, s57, s75
	global_load_lds_dwordx4 v[140:141], off
	v_lshl_add_u64 v[140:141], s[30:31], 0, v[96:97]
	s_mov_b32 m0, s50
	s_nop 0
	global_load_lds_dwordx4 v[140:141], off
	v_lshl_add_u64 v[140:141], s[30:31], 0, v[130:131]
	s_add_i32 m0, s50, 0x2000
	s_nop 0
	global_load_lds_dwordx4 v[140:141], off
	v_lshl_add_u64 v[140:141], v[218:219], 0, s[86:87]
	s_mov_b32 m0, s85
	s_nop 0
	global_load_lds_dwordx4 v[140:141], off
	v_lshl_add_u64 v[140:141], v[220:221], 0, s[86:87]
	s_mov_b32 m0, s14
	s_nop 0
	global_load_lds_dwordx4 v[140:141], off
	s_waitcnt vmcnt(8)
	s_waitcnt lgkmcnt(0)
	s_barrier
	s_setprio 1
	s_waitcnt lgkmcnt(0)
	v_mfma_f32_16x16x32_bf16 v[60:63], v[146:149], v[178:181], v[60:63]
	v_mfma_f32_16x16x32_bf16 v[52:55], v[154:157], v[178:181], v[52:55]
	v_mfma_f32_16x16x32_bf16 v[36:39], v[154:157], v[186:189], v[36:39]
	v_mfma_f32_16x16x32_bf16 v[44:47], v[146:149], v[186:189], v[44:47]
	v_mfma_f32_16x16x32_bf16 v[28:31], v[146:149], v[202:205], v[28:31]
	v_mfma_f32_16x16x32_bf16 v[20:23], v[154:157], v[202:205], v[20:23]
	v_mfma_f32_16x16x32_bf16 v[4:7], v[154:157], v[210:213], v[4:7]
	v_mfma_f32_16x16x32_bf16 v[12:15], v[146:149], v[210:213], v[12:15]
	v_mfma_f32_16x16x32_bf16 v[60:63], v[150:153], v[182:185], v[60:63]
	v_mfma_f32_16x16x32_bf16 v[52:55], v[158:161], v[182:185], v[52:55]
	v_mfma_f32_16x16x32_bf16 v[36:39], v[158:161], v[190:193], v[36:39]
	v_mfma_f32_16x16x32_bf16 v[44:47], v[150:153], v[190:193], v[44:47]
	v_mfma_f32_16x16x32_bf16 v[28:31], v[150:153], v[206:209], v[28:31]
	v_mfma_f32_16x16x32_bf16 v[20:23], v[158:161], v[206:209], v[20:23]
	v_mfma_f32_16x16x32_bf16 v[4:7], v[158:161], v[214:217], v[4:7]
	v_mfma_f32_16x16x32_bf16 v[12:15], v[150:153], v[214:217], v[12:15]
	s_setprio 0
	s_setprio 1
	v_mfma_f32_16x16x32_bf16 v[56:59], v[162:165], v[178:181], v[56:59]
	v_mfma_f32_16x16x32_bf16 v[48:51], v[170:173], v[178:181], v[48:51]
	v_mfma_f32_16x16x32_bf16 v[32:35], v[170:173], v[186:189], v[32:35]
	v_mfma_f32_16x16x32_bf16 v[40:43], v[162:165], v[186:189], v[40:43]
	v_mfma_f32_16x16x32_bf16 v[24:27], v[162:165], v[202:205], v[24:27]
	v_mfma_f32_16x16x32_bf16 v[16:19], v[170:173], v[202:205], v[16:19]
	v_mfma_f32_16x16x32_bf16 v[0:3], v[170:173], v[210:213], v[0:3]
	v_mfma_f32_16x16x32_bf16 v[8:11], v[162:165], v[210:213], v[8:11]
	v_mfma_f32_16x16x32_bf16 v[56:59], v[166:169], v[182:185], v[56:59]
	v_mfma_f32_16x16x32_bf16 v[48:51], v[174:177], v[182:185], v[48:51]
	v_mfma_f32_16x16x32_bf16 v[32:35], v[174:177], v[190:193], v[32:35]
	v_mfma_f32_16x16x32_bf16 v[40:43], v[166:169], v[190:193], v[40:43]
	v_mfma_f32_16x16x32_bf16 v[24:27], v[166:169], v[206:209], v[24:27]
	v_mfma_f32_16x16x32_bf16 v[16:19], v[174:177], v[206:209], v[16:19]
	v_mfma_f32_16x16x32_bf16 v[0:3], v[174:177], v[214:217], v[0:3]
	v_mfma_f32_16x16x32_bf16 v[8:11], v[166:169], v[214:217], v[8:11]
	s_setprio 0
	s_barrier
	s_add_i32 s27, s27, 2
	s_add_u32 s28, s28, 0x100
	s_addc_u32 s29, s29, 0
	s_add_u32 s19, s19, 0x100
	s_addc_u32 s21, s21, 0
	s_cmp_gt_u32 s27, 13
	s_cbranch_scc0 .LBB0_1053
	s_and_b64 vcc, exec, s[16:17]
	s_cbranch_vccz .LBB0_1056
	s_barrier

; #define PG8_STAGE(bufoff, gbase, V0, V1) do { \
;         __builtin_amdgcn_global_load_lds((const unsigned*)((const char*)(gbase) + (V0)), (LAS unsigned*)(lds + (bufoff) + ldsw), 16, 0, 0); \
;         __builtin_amdgcn_global_load_lds((const unsigned*)((const char*)(gbase) + (V1)), (LAS unsigned*)(lds + (bufoff) + ldsw + 8192), 16, 0, 0); } while (0)
; #define PG8_LDA(dst, b, h) do { _Pragma("unroll") for (int m = 0; m < 4; ++m) _Pragma("unroll") for (int k = 0; k < 2; ++k) dst[m][k] = *(const LAS bf16x8*)(lds + PG8_SA(b, h) + aoff + m * 2048 + k * 1024); } while (0)
; #define PG8_LDB(dst, b, h) do { _Pragma("unroll") for (int n = 0; n < 2; ++n) _Pragma("unroll") for (int k = 0; k < 2; ++k) dst[n][k] = *(const LAS bf16x8*)(lds + PG8_SB(b, h) + boff + n * 2048 + k * 1024); } while (0)
; #define PG8_MMA(ai, bj, At, Bt) do { __builtin_amdgcn_s_setprio(1); _Pragma("unroll") for (int m = 0; m < 4; ++m) _Pragma("unroll") for (int n = 0; n < 2; ++n) _Pragma("unroll") for (int k = 0; k < 2; ++k) \
;         acc[ai][bj][m][n] = __builtin_amdgcn_mfma_f32_16x16x32_bf16(Bt[n][k], At[m][k], acc[ai][bj][m][n], 0, 0, 0); __builtin_amdgcn_s_setprio(0); } while (0)
; template <class Epi, class Sched>
; DI void gemm_phase(LAS unsigned char* lds, const int lda2, const int ldb2, const int nt, const Sched& S, const Epi& E) {
;     ...
;     for (;;) {
;         const bool has_next = S.next(ui + 1, nxt);
;         const char* nA = has_next ? nxt.A : cA; const char* nB = has_next ? nxt.B : cB;
;         for (int t = 0; t < nt; t += 2) {
;             const bool last = (t == nt - 2);
;             const char* a1 = cA + (size_t)(t + 1) * kstep;
;             const char* a2 = last ? nA : cA + (size_t)(t + 2) * kstep; const char* b2 = last ? nB : cB + (size_t)(t + 2) * kstep;
;             const char* a3 = a2 + kstep; const char* b3 = b2 + kstep;
;             PG8_LDB(B0, 0, 0); PG8_LDB(B1, 0, 1); PG8_SCHED; PG8_LDA(At, 0, 0); PG8_STAGE(PG8_SA(1, 1), a1 + hstepA, vA0, vA1);
;             PG8_WAIT_V(8); PG8_WAIT_L(0); PG8_BAR; PG8_MMA(0, 0, At, B0); PG8_MMA(0, 1, At, B1); PG8_BAR; PG8_SCHED;
;             PG8_LDA(At, 0, 1); PG8_STAGE(PG8_SB(0, 0), b2, vB0, vB1); PG8_STAGE(PG8_SB(0, 1), b2 + hstepB, vB0, vB1); PG8_STAGE(PG8_SA(0, 0), a2, vA0, vA1);
;             PG8_WAIT_V(8); PG8_WAIT_L(0); PG8_BAR; PG8_MMA(1, 0, At, B0); PG8_MMA(1, 1, At, B1); PG8_BAR; PG8_SCHED;
.LBB0_1123:
	s_add_u32 s28, s28, 0xb0080
	s_addc_u32 s29, s29, 0
	s_add_u32 s1, s30, 0x100
	s_addc_u32 s10, s31, 0
	s_mov_b32 s57, -2
	s_waitcnt lgkmcnt(0)
	s_add_u32 s30, s28, 0xfff50080
	s_addc_u32 s31, s29, -1
	s_add_i32 vcc_lo, 0, 0x10000
	s_cmp_eq_u32 s57, 40
	s_cselect_b32 s53, s25, s31
	s_cselect_b32 s52, s24, s30
	v_add_u32_e32 v144, vcc_lo, v148
	s_cselect_b32 s31, s27, s10
	s_cselect_b32 s30, s26, s1
	s_add_i32 s58, 0, 0x14000
	v_lshl_add_u64 v[250:251], s[28:29], 0, v[136:137]
	s_add_i32 m0, s74, 0xc000
	s_nop 0
	global_load_lds_dwordx4 v[250:251], off
	v_lshl_add_u64 v[250:251], s[28:29], 0, v[138:139]
	s_add_i32 m0, s74, 0xe000
	s_nop 0
	global_load_lds_dwordx4 v[250:251], off
	ds_read_b128 v[140:143], v144
	ds_read_b128 v[150:153], v144 offset:1024
	ds_read_b128 v[154:157], v144 offset:2048
	ds_read_b128 v[158:161], v144 offset:3072
	v_add_u32_e32 v144, s58, v148
	ds_read_b128 v[162:165], v144
	ds_read_b128 v[166:169], v144 offset:1024
	ds_read_b128 v[170:173], v144 offset:2048
	ds_read_b128 v[174:177], v144 offset:3072
	ds_read_b128 v[178:181], v149
	ds_read_b128 v[182:185], v149 offset:1024
	ds_read_b128 v[186:189], v149 offset:2048
	ds_read_b128 v[190:193], v149 offset:3072
	ds_read_b128 v[202:205], v149 offset:4096
	ds_read_b128 v[206:209], v149 offset:5120
	ds_read_b128 v[210:213], v149 offset:6144
	ds_read_b128 v[214:217], v149 offset:7168
	s_waitcnt vmcnt(8)
	s_waitcnt lgkmcnt(0)
	s_barrier
	s_setprio 1
	s_waitcnt lgkmcnt(0)
	v_mfma_f32_16x16x32_bf16 v[126:129], v[140:143], v[178:181], 0
	v_mfma_f32_16x16x32_bf16 v[122:125], v[154:157], v[178:181], 0
	v_mfma_f32_16x16x32_bf16 v[106:109], v[154:157], v[186:189], 0
	v_mfma_f32_16x16x32_bf16 v[110:113], v[140:143], v[186:189], 0
	v_mfma_f32_16x16x32_bf16 v[92:95], v[140:143], v[202:205], 0
	v_mfma_f32_16x16x32_bf16 v[88:91], v[154:157], v[202:205], 0
	v_mfma_f32_16x16x32_bf16 v[72:75], v[154:157], v[210:213], 0
	v_mfma_f32_16x16x32_bf16 v[76:79], v[140:143], v[210:213], 0
	v_mfma_f32_16x16x32_bf16 v[126:129], v[150:153], v[182:185], v[126:129]
	v_mfma_f32_16x16x32_bf16 v[122:125], v[158:161], v[182:185], v[122:125]
	v_mfma_f32_16x16x32_bf16 v[106:109], v[158:161], v[190:193], v[106:109]
	v_mfma_f32_16x16x32_bf16 v[110:113], v[150:153], v[190:193], v[110:113]
	v_mfma_f32_16x16x32_bf16 v[92:95], v[150:153], v[206:209], v[92:95]
	v_mfma_f32_16x16x32_bf16 v[88:91], v[158:161], v[206:209], v[88:91]
	v_mfma_f32_16x16x32_bf16 v[72:75], v[158:161], v[214:217], v[72:75]
	v_mfma_f32_16x16x32_bf16 v[76:79], v[150:153], v[214:217], v[76:79]
	s_setprio 0
	s_setprio 1
	v_mfma_f32_16x16x32_bf16 v[118:121], v[162:165], v[178:181], 0
	v_mfma_f32_16x16x32_bf16 v[114:117], v[170:173], v[178:181], 0
	v_mfma_f32_16x16x32_bf16 v[98:101], v[170:173], v[186:189], 0
	v_mfma_f32_16x16x32_bf16 v[102:105], v[162:165], v[186:189], 0
	v_mfma_f32_16x16x32_bf16 v[84:87], v[162:165], v[202:205], 0
	v_mfma_f32_16x16x32_bf16 v[80:83], v[170:173], v[202:205], 0
	v_mfma_f32_16x16x32_bf16 v[64:67], v[170:173], v[210:213], 0
	v_mfma_f32_16x16x32_bf16 v[68:71], v[162:165], v[210:213], 0
	v_mfma_f32_16x16x32_bf16 v[118:121], v[166:169], v[182:185], v[118:121]
	v_mfma_f32_16x16x32_bf16 v[114:117], v[174:177], v[182:185], v[114:117]
	v_mfma_f32_16x16x32_bf16 v[98:101], v[174:177], v[190:193], v[98:101]
	v_mfma_f32_16x16x32_bf16 v[102:105], v[166:169], v[190:193], v[102:105]
	v_mfma_f32_16x16x32_bf16 v[84:87], v[166:169], v[206:209], v[84:87]
	v_mfma_f32_16x16x32_bf16 v[80:83], v[174:177], v[206:209], v[80:83]
	v_mfma_f32_16x16x32_bf16 v[64:67], v[174:177], v[214:217], v[64:67]
	v_mfma_f32_16x16x32_bf16 v[68:71], v[166:169], v[214:217], v[68:71]
	s_setprio 0
	s_barrier
	s_add_i32 s59, vcc_lo, s73
	v_lshl_add_u64 v[144:145], s[30:31], 0, v[96:97]
	s_mov_b32 m0, s59
	ds_read_b128 v[178:181], v149 offset:16384
	ds_read_b128 v[182:185], v149 offset:17408
	ds_read_b128 v[186:189], v149 offset:18432
	ds_read_b128 v[190:193], v149 offset:19456
	ds_read_b128 v[202:205], v149 offset:20480
	ds_read_b128 v[206:209], v149 offset:21504
	ds_read_b128 v[210:213], v149 offset:22528
	ds_read_b128 v[214:217], v149 offset:23552
	global_load_lds_dwordx4 v[144:145], off
	s_add_i32 m0, s59, 0x2000
	s_add_u32 vcc_lo, s30, 0xb0000
	v_lshl_add_u64 v[194:195], s[30:31], 0, v[130:131]
	s_addc_u32 vcc_hi, s31, 0
	s_add_i32 s58, s58, s73
	global_load_lds_dwordx4 v[194:195], off
	v_lshl_add_u64 v[218:219], vcc, 0, v[96:97]
	s_mov_b32 m0, s58
	v_lshl_add_u64 v[220:221], s[52:53], 0, v[134:135]
	global_load_lds_dwordx4 v[218:219], off
	v_lshl_add_u64 v[218:219], vcc, 0, v[130:131]
	s_add_i32 m0, s58, 0x2000
	s_nop 0
	global_load_lds_dwordx4 v[218:219], off
	v_lshl_add_u64 v[218:219], s[52:53], 0, v[132:133]
	s_mov_b32 m0, s74
	s_nop 0
	global_load_lds_dwordx4 v[218:219], off
	s_mov_b32 m0, s75
	s_nop 0
	global_load_lds_dwordx4 v[220:221], off
	s_waitcnt vmcnt(8)
	s_waitcnt lgkmcnt(0)
	s_barrier
; #define PG8_STAGE(bufoff, gbase, V0, V1) do { \
;         __builtin_amdgcn_global_load_lds((const unsigned*)((const char*)(gbase) + (V0)), (LAS unsigned*)(lds + (bufoff) + ldsw), 16, 0, 0); \
;         __builtin_amdgcn_global_load_lds((const unsigned*)((const char*)(gbase) + (V1)), (LAS unsigned*)(lds + (bufoff) + ldsw + 8192), 16, 0, 0); } while (0)
; #define PG8_LDA(dst, b, h) do { _Pragma("unroll") for (int m = 0; m < 4; ++m) _Pragma("unroll") for (int k = 0; k < 2; ++k) dst[m][k] = *(const LAS bf16x8*)(lds + PG8_SA(b, h) + aoff + m * 2048 + k * 1024); } while (0)
; #define PG8_LDB(dst, b, h) do { _Pragma("unroll") for (int n = 0; n < 2; ++n) _Pragma("unroll") for (int k = 0; k < 2; ++k) dst[n][k] = *(const LAS bf16x8*)(lds + PG8_SB(b, h) + boff + n * 2048 + k * 1024); } while (0)
; #define PG8_MMA(ai, bj, At, Bt) do { __builtin_amdgcn_s_setprio(1); _Pragma("unroll") for (int m = 0; m < 4; ++m) _Pragma("unroll") for (int n = 0; n < 2; ++n) _Pragma("unroll") for (int k = 0; k < 2; ++k) \
;         acc[ai][bj][m][n] = __builtin_amdgcn_mfma_f32_16x16x32_bf16(Bt[n][k], At[m][k], acc[ai][bj][m][n], 0, 0, 0); __builtin_amdgcn_s_setprio(0); } while (0)
; #define PG8_WAIT_V(n) asm volatile("s_waitcnt vmcnt(" #n ")" ::: "memory")
; #define PG8_WAIT_L(n) asm volatile("s_waitcnt lgkmcnt(" #n ")" ::: "memory")
; #define PG8_BAR __builtin_amdgcn_s_barrier()
; #define PG8_SCHED __builtin_amdgcn_sched_barrier(0)
; template <class Epi, class Sched>
; DI void gemm_phase(LAS unsigned char* lds, const int lda2, const int ldb2, const int nt, const Sched& S, const Epi& E) {
;     ...
;             PG8_WAIT_V(8); PG8_WAIT_L(0); PG8_BAR; PG8_MMA(0, 0, At, B0); PG8_MMA(0, 1, At, B1); PG8_BAR; PG8_SCHED;
;             PG8_LDA(At, 0, 1); PG8_STAGE(PG8_SB(0, 0), b2, vB0, vB1); PG8_STAGE(PG8_SB(0, 1), b2 + hstepB, vB0, vB1); PG8_STAGE(PG8_SA(0, 0), a2, vA0, vA1);
;             PG8_WAIT_V(8); PG8_WAIT_L(0); PG8_BAR; PG8_MMA(1, 0, At, B0); PG8_MMA(1, 1, At, B1); PG8_BAR; PG8_SCHED;
;             PG8_LDB(B0, 1, 0); PG8_LDB(B1, 1, 1); PG8_SCHED; PG8_LDA(At, 1, 0); PG8_STAGE(PG8_SA(0, 1), a2 + hstepA, vA0, vA1);
;             PG8_WAIT_V(8); PG8_WAIT_L(0); PG8_BAR; PG8_MMA(0, 0, At, B0); PG8_MMA(0, 1, At, B1); PG8_BAR; PG8_SCHED;
	s_setprio 1
	s_waitcnt lgkmcnt(0)
	v_mfma_f32_16x16x32_bf16 v[60:63], v[140:143], v[178:181], 0
	v_mfma_f32_16x16x32_bf16 v[56:59], v[154:157], v[178:181], 0
	v_mfma_f32_16x16x32_bf16 v[40:43], v[154:157], v[186:189], 0
	v_mfma_f32_16x16x32_bf16 v[44:47], v[140:143], v[186:189], 0
	v_mfma_f32_16x16x32_bf16 v[28:31], v[140:143], v[202:205], 0
	v_mfma_f32_16x16x32_bf16 v[24:27], v[154:157], v[202:205], 0
	v_mfma_f32_16x16x32_bf16 v[8:11], v[154:157], v[210:213], 0
	v_mfma_f32_16x16x32_bf16 v[12:15], v[140:143], v[210:213], 0
	v_mfma_f32_16x16x32_bf16 v[60:63], v[150:153], v[182:185], v[60:63]
	v_mfma_f32_16x16x32_bf16 v[56:59], v[158:161], v[182:185], v[56:59]
	v_mfma_f32_16x16x32_bf16 v[40:43], v[158:161], v[190:193], v[40:43]
	v_mfma_f32_16x16x32_bf16 v[44:47], v[150:153], v[190:193], v[44:47]
	v_mfma_f32_16x16x32_bf16 v[28:31], v[150:153], v[206:209], v[28:31]
	v_mfma_f32_16x16x32_bf16 v[24:27], v[158:161], v[206:209], v[24:27]
	v_mfma_f32_16x16x32_bf16 v[8:11], v[158:161], v[214:217], v[8:11]
	v_mfma_f32_16x16x32_bf16 v[12:15], v[150:153], v[214:217], v[12:15]
	s_setprio 0
	s_setprio 1
	v_mfma_f32_16x16x32_bf16 v[52:55], v[162:165], v[178:181], 0
	v_mfma_f32_16x16x32_bf16 v[48:51], v[170:173], v[178:181], 0
	v_mfma_f32_16x16x32_bf16 v[32:35], v[170:173], v[186:189], 0
	v_mfma_f32_16x16x32_bf16 v[36:39], v[162:165], v[186:189], 0
	v_mfma_f32_16x16x32_bf16 v[20:23], v[162:165], v[202:205], 0
	v_mfma_f32_16x16x32_bf16 v[16:19], v[170:173], v[202:205], 0
	v_mfma_f32_16x16x32_bf16 v[0:3], v[170:173], v[210:213], 0
	v_mfma_f32_16x16x32_bf16 v[4:7], v[162:165], v[210:213], 0
	v_mfma_f32_16x16x32_bf16 v[52:55], v[166:169], v[182:185], v[52:55]
	v_mfma_f32_16x16x32_bf16 v[48:51], v[174:177], v[182:185], v[48:51]
	v_mfma_f32_16x16x32_bf16 v[32:35], v[174:177], v[190:193], v[32:35]
	v_mfma_f32_16x16x32_bf16 v[36:39], v[166:169], v[190:193], v[36:39]
	v_mfma_f32_16x16x32_bf16 v[20:23], v[166:169], v[206:209], v[20:23]
	v_mfma_f32_16x16x32_bf16 v[16:19], v[174:177], v[206:209], v[16:19]
	v_mfma_f32_16x16x32_bf16 v[0:3], v[174:177], v[214:217], v[0:3]
	v_mfma_f32_16x16x32_bf16 v[4:7], v[166:169], v[214:217], v[4:7]
	s_setprio 0
	s_barrier
	s_add_i32 s58, 0, 0x18000
	s_add_i32 s59, 0, 0x1c000
	v_add_u32_e32 v158, s58, v148
	v_add_u32_e32 v174, s59, v148
	s_add_u32 s52, s52, 0xb0000
	s_addc_u32 s53, s53, 0
	s_mov_b32 m0, s76
	v_lshl_add_u64 v[250:251], s[52:53], 0, v[132:133]
	s_nop 0
	global_load_lds_dwordx4 v[250:251], off
	v_lshl_add_u64 v[250:251], s[52:53], 0, v[134:135]
	s_mov_b32 m0, s77
	s_nop 0
	global_load_lds_dwordx4 v[250:251], off
	ds_read_b128 v[140:143], v158
	ds_read_b128 v[150:153], v158 offset:1024
	ds_read_b128 v[154:157], v158 offset:2048
	ds_read_b128 v[158:161], v158 offset:3072
	ds_read_b128 v[162:165], v174
	ds_read_b128 v[166:169], v174 offset:1024
	ds_read_b128 v[170:173], v174 offset:2048
	ds_read_b128 v[174:177], v174 offset:3072
	ds_read_b128 v[178:181], v149 offset:32768
	ds_read_b128 v[182:185], v149 offset:33792
	ds_read_b128 v[186:189], v149 offset:34816
	ds_read_b128 v[190:193], v149 offset:35840
	ds_read_b128 v[202:205], v149 offset:36864
	ds_read_b128 v[206:209], v149 offset:37888
	ds_read_b128 v[210:213], v149 offset:38912
	ds_read_b128 v[214:217], v149 offset:39936
	s_waitcnt vmcnt(8)
	s_waitcnt lgkmcnt(0)
	s_barrier
	s_setprio 1
	s_waitcnt lgkmcnt(0)
	v_mfma_f32_16x16x32_bf16 v[126:129], v[140:143], v[178:181], v[126:129]
	v_mfma_f32_16x16x32_bf16 v[122:125], v[154:157], v[178:181], v[122:125]
	v_mfma_f32_16x16x32_bf16 v[106:109], v[154:157], v[186:189], v[106:109]
	v_mfma_f32_16x16x32_bf16 v[110:113], v[140:143], v[186:189], v[110:113]
	v_mfma_f32_16x16x32_bf16 v[92:95], v[140:143], v[202:205], v[92:95]
	v_mfma_f32_16x16x32_bf16 v[88:91], v[154:157], v[202:205], v[88:91]
	v_mfma_f32_16x16x32_bf16 v[72:75], v[154:157], v[210:213], v[72:75]
	v_mfma_f32_16x16x32_bf16 v[76:79], v[140:143], v[210:213], v[76:79]
	v_mfma_f32_16x16x32_bf16 v[126:129], v[150:153], v[182:185], v[126:129]
	v_mfma_f32_16x16x32_bf16 v[122:125], v[158:161], v[182:185], v[122:125]
	v_mfma_f32_16x16x32_bf16 v[106:109], v[158:161], v[190:193], v[106:109]
	v_mfma_f32_16x16x32_bf16 v[110:113], v[150:153], v[190:193], v[110:113]
	v_mfma_f32_16x16x32_bf16 v[92:95], v[150:153], v[206:209], v[92:95]
	v_mfma_f32_16x16x32_bf16 v[88:91], v[158:161], v[206:209], v[88:91]
	v_mfma_f32_16x16x32_bf16 v[72:75], v[158:161], v[214:217], v[72:75]
	v_mfma_f32_16x16x32_bf16 v[76:79], v[150:153], v[214:217], v[76:79]
	s_setprio 0
	s_setprio 1
	v_mfma_f32_16x16x32_bf16 v[118:121], v[162:165], v[178:181], v[118:121]
	v_mfma_f32_16x16x32_bf16 v[114:117], v[170:173], v[178:181], v[114:117]
	v_mfma_f32_16x16x32_bf16 v[98:101], v[170:173], v[186:189], v[98:101]
	v_mfma_f32_16x16x32_bf16 v[102:105], v[162:165], v[186:189], v[102:105]
	v_mfma_f32_16x16x32_bf16 v[84:87], v[162:165], v[202:205], v[84:87]
	v_mfma_f32_16x16x32_bf16 v[80:83], v[170:173], v[202:205], v[80:83]
	v_mfma_f32_16x16x32_bf16 v[64:67], v[170:173], v[210:213], v[64:67]
	v_mfma_f32_16x16x32_bf16 v[68:71], v[162:165], v[210:213], v[68:71]
	v_mfma_f32_16x16x32_bf16 v[118:121], v[166:169], v[182:185], v[118:121]
	v_mfma_f32_16x16x32_bf16 v[114:117], v[174:177], v[182:185], v[114:117]
	v_mfma_f32_16x16x32_bf16 v[98:101], v[174:177], v[190:193], v[98:101]
	v_mfma_f32_16x16x32_bf16 v[102:105], v[166:169], v[190:193], v[102:105]
	v_mfma_f32_16x16x32_bf16 v[84:87], v[166:169], v[206:209], v[84:87]
	v_mfma_f32_16x16x32_bf16 v[80:83], v[174:177], v[206:209], v[80:83]
	v_mfma_f32_16x16x32_bf16 v[64:67], v[174:177], v[214:217], v[64:67]
	v_mfma_f32_16x16x32_bf16 v[68:71], v[166:169], v[214:217], v[68:71]
	s_setprio 0
	s_barrier
; #define PG8_STAGE(bufoff, gbase, V0, V1) do { \
;         __builtin_amdgcn_global_load_lds((const unsigned*)((const char*)(gbase) + (V0)), (LAS unsigned*)(lds + (bufoff) + ldsw), 16, 0, 0); \
;         __builtin_amdgcn_global_load_lds((const unsigned*)((const char*)(gbase) + (V1)), (LAS unsigned*)(lds + (bufoff) + ldsw + 8192), 16, 0, 0); } while (0)
; #define PG8_LDA(dst, b, h) do { _Pragma("unroll") for (int m = 0; m < 4; ++m) _Pragma("unroll") for (int k = 0; k < 2; ++k) dst[m][k] = *(const LAS bf16x8*)(lds + PG8_SA(b, h) + aoff + m * 2048 + k * 1024); } while (0)
; #define PG8_WAIT_V(n) asm volatile("s_waitcnt vmcnt(" #n ")" ::: "memory")
; template <class Epi, class Sched>
; DI void gemm_phase(LAS unsigned char* lds, const int lda2, const int ldb2, const int nt, const Sched& S, const Epi& E) {
;     ...
;         const bool has_next = S.next(ui + 1, nxt);
;         const char* nA = has_next ? nxt.A : cA; const char* nB = has_next ? nxt.B : cB;
;         for (int t = 0; t < nt; t += 2) {
;             const bool last = (t == nt - 2);
;             const char* a1 = cA + (size_t)(t + 1) * kstep;
;             const char* a2 = last ? nA : cA + (size_t)(t + 2) * kstep; const char* b2 = last ? nB : cB + (size_t)(t + 2) * kstep;
;             const char* a3 = a2 + kstep; const char* b3 = b2 + kstep;
;             PG8_LDB(B0, 0, 0); PG8_LDB(B1, 0, 1); PG8_SCHED; PG8_LDA(At, 0, 0); PG8_STAGE(PG8_SA(1, 1), a1 + hstepA, vA0, vA1);
;             PG8_WAIT_V(8); PG8_WAIT_L(0); PG8_BAR; PG8_MMA(0, 0, At, B0); PG8_MMA(0, 1, At, B1); PG8_BAR; PG8_SCHED;
;             PG8_LDA(At, 0, 1); PG8_STAGE(PG8_SB(0, 0), b2, vB0, vB1); PG8_STAGE(PG8_SB(0, 1), b2 + hstepB, vB0, vB1); PG8_STAGE(PG8_SA(0, 0), a2, vA0, vA1);
;             PG8_WAIT_V(8); PG8_WAIT_L(0); PG8_BAR; PG8_MMA(1, 0, At, B0); PG8_MMA(1, 1, At, B1); PG8_BAR; PG8_SCHED;
;             PG8_LDB(B0, 1, 0); PG8_LDB(B1, 1, 1); PG8_SCHED; PG8_LDA(At, 1, 0); PG8_STAGE(PG8_SA(0, 1), a2 + hstepA, vA0, vA1);
;             PG8_WAIT_V(8); PG8_WAIT_L(0); PG8_BAR; PG8_MMA(0, 0, At, B0); PG8_MMA(0, 1, At, B1); PG8_BAR; PG8_SCHED;
;             PG8_LDA(At, 1, 1); PG8_STAGE(PG8_SB(1, 0), b3, vB0, vB1); PG8_STAGE(PG8_SB(1, 1), b3 + hstepB, vB0, vB1); PG8_STAGE(PG8_SA(1, 0), a3, vA0, vA1);
;             PG8_WAIT_V(8); PG8_WAIT_L(0); PG8_BAR; PG8_MMA(1, 0, At, B0); PG8_MMA(1, 1, At, B1); PG8_BAR; PG8_SCHED;
	s_add_i32 s52, s58, s73
	v_lshl_add_u64 v[144:145], v[144:145], 0, s[86:87]
	s_mov_b32 m0, s52
	ds_read_b128 v[178:181], v149 offset:49152
	ds_read_b128 v[182:185], v149 offset:50176
	ds_read_b128 v[186:189], v149 offset:51200
	ds_read_b128 v[190:193], v149 offset:52224
	ds_read_b128 v[202:205], v149 offset:53248
	ds_read_b128 v[206:209], v149 offset:54272
	ds_read_b128 v[210:213], v149 offset:55296
	ds_read_b128 v[214:217], v149 offset:56320
	global_load_lds_dwordx4 v[144:145], off
	s_add_i32 m0, s52, 0x2000
	s_add_u32 s30, s30, 0xb0080
	v_lshl_add_u64 v[144:145], v[194:195], 0, s[86:87]
	s_addc_u32 s31, s31, 0
	s_add_i32 s52, s59, s73
	global_load_lds_dwordx4 v[144:145], off
	v_lshl_add_u64 v[144:145], s[30:31], 0, v[96:97]
	s_mov_b32 m0, s52
	s_nop 0
	global_load_lds_dwordx4 v[144:145], off
	v_lshl_add_u64 v[144:145], s[30:31], 0, v[130:131]
	s_add_i32 m0, s52, 0x2000
	s_nop 0
	global_load_lds_dwordx4 v[144:145], off
	v_lshl_add_u64 v[144:145], v[218:219], 0, s[86:87]
	s_mov_b32 m0, s81
	s_nop 0
	global_load_lds_dwordx4 v[144:145], off
	v_lshl_add_u64 v[144:145], v[220:221], 0, s[86:87]
	s_mov_b32 m0, s82
	s_nop 0
	global_load_lds_dwordx4 v[144:145], off
	s_waitcnt vmcnt(8)
	s_waitcnt lgkmcnt(0)
	s_barrier
	s_setprio 1
	s_waitcnt lgkmcnt(0)
	v_mfma_f32_16x16x32_bf16 v[60:63], v[140:143], v[178:181], v[60:63]
	v_mfma_f32_16x16x32_bf16 v[56:59], v[154:157], v[178:181], v[56:59]
	v_mfma_f32_16x16x32_bf16 v[40:43], v[154:157], v[186:189], v[40:43]
	v_mfma_f32_16x16x32_bf16 v[44:47], v[140:143], v[186:189], v[44:47]
	v_mfma_f32_16x16x32_bf16 v[28:31], v[140:143], v[202:205], v[28:31]
	v_mfma_f32_16x16x32_bf16 v[24:27], v[154:157], v[202:205], v[24:27]
	v_mfma_f32_16x16x32_bf16 v[8:11], v[154:157], v[210:213], v[8:11]
	v_mfma_f32_16x16x32_bf16 v[12:15], v[140:143], v[210:213], v[12:15]
	v_mfma_f32_16x16x32_bf16 v[60:63], v[150:153], v[182:185], v[60:63]
	v_mfma_f32_16x16x32_bf16 v[56:59], v[158:161], v[182:185], v[56:59]
	v_mfma_f32_16x16x32_bf16 v[40:43], v[158:161], v[190:193], v[40:43]
	v_mfma_f32_16x16x32_bf16 v[44:47], v[150:153], v[190:193], v[44:47]
	v_mfma_f32_16x16x32_bf16 v[28:31], v[150:153], v[206:209], v[28:31]
	v_mfma_f32_16x16x32_bf16 v[24:27], v[158:161], v[206:209], v[24:27]
	v_mfma_f32_16x16x32_bf16 v[8:11], v[158:161], v[214:217], v[8:11]
	v_mfma_f32_16x16x32_bf16 v[12:15], v[150:153], v[214:217], v[12:15]
	s_setprio 0
	s_setprio 1
	v_mfma_f32_16x16x32_bf16 v[52:55], v[162:165], v[178:181], v[52:55]
	v_mfma_f32_16x16x32_bf16 v[48:51], v[170:173], v[178:181], v[48:51]
	v_mfma_f32_16x16x32_bf16 v[32:35], v[170:173], v[186:189], v[32:35]
	v_mfma_f32_16x16x32_bf16 v[36:39], v[162:165], v[186:189], v[36:39]
	v_mfma_f32_16x16x32_bf16 v[20:23], v[162:165], v[202:205], v[20:23]
	v_mfma_f32_16x16x32_bf16 v[16:19], v[170:173], v[202:205], v[16:19]
	v_mfma_f32_16x16x32_bf16 v[0:3], v[170:173], v[210:213], v[0:3]
	v_mfma_f32_16x16x32_bf16 v[4:7], v[162:165], v[210:213], v[4:7]
	v_mfma_f32_16x16x32_bf16 v[52:55], v[166:169], v[182:185], v[52:55]
	v_mfma_f32_16x16x32_bf16 v[48:51], v[174:177], v[182:185], v[48:51]
	v_mfma_f32_16x16x32_bf16 v[32:35], v[174:177], v[190:193], v[32:35]
	v_mfma_f32_16x16x32_bf16 v[36:39], v[166:169], v[190:193], v[36:39]
	v_mfma_f32_16x16x32_bf16 v[20:23], v[166:169], v[206:209], v[20:23]
	v_mfma_f32_16x16x32_bf16 v[16:19], v[174:177], v[206:209], v[16:19]
	v_mfma_f32_16x16x32_bf16 v[0:3], v[174:177], v[214:217], v[0:3]
	v_mfma_f32_16x16x32_bf16 v[4:7], v[166:169], v[214:217], v[4:7]
	s_setprio 0
	s_barrier
	s_add_i32 s57, s57, 2
	s_add_u32 s28, s28, 0x100
	s_addc_u32 s29, s29, 0
	s_add_u32 s1, s1, 0x100
	s_addc_u32 s10, s10, 0
.LBB0_1124:
	s_add_u32 s30, s28, 0xfff50080
	s_addc_u32 s31, s29, -1
	s_add_i32 vcc_lo, 0, 0x10000
	s_cmp_eq_u32 s57, 40
	s_cselect_b32 s53, s25, s31
	s_cselect_b32 s52, s24, s30
	v_add_u32_e32 v144, vcc_lo, v148
	s_cselect_b32 s31, s27, s10
	s_cselect_b32 s30, s26, s1
	s_add_i32 s58, 0, 0x14000
	v_lshl_add_u64 v[250:251], s[28:29], 0, v[136:137]
	s_add_i32 m0, s74, 0xc000
	s_nop 0
	global_load_lds_dwordx4 v[250:251], off
	v_lshl_add_u64 v[250:251], s[28:29], 0, v[138:139]
	s_add_i32 m0, s74, 0xe000
	s_nop 0
	global_load_lds_dwordx4 v[250:251], off
	ds_read_b128 v[140:143], v144
	ds_read_b128 v[150:153], v144 offset:1024
	ds_read_b128 v[154:157], v144 offset:2048
	ds_read_b128 v[158:161], v144 offset:3072
	v_add_u32_e32 v144, s58, v148
	ds_read_b128 v[162:165], v144
	ds_read_b128 v[166:169], v144 offset:1024
	ds_read_b128 v[170:173], v144 offset:2048
	ds_read_b128 v[174:177], v144 offset:3072
	ds_read_b128 v[178:181], v149
	ds_read_b128 v[182:185], v149 offset:1024
	ds_read_b128 v[186:189], v149 offset:2048
	ds_read_b128 v[190:193], v149 offset:3072
	ds_read_b128 v[202:205], v149 offset:4096
	ds_read_b128 v[206:209], v149 offset:5120
	ds_read_b128 v[210:213], v149 offset:6144
	ds_read_b128 v[214:217], v149 offset:7168
	s_waitcnt vmcnt(8)
	s_waitcnt lgkmcnt(0)
	s_barrier
; #define PG8_STAGE(bufoff, gbase, V0, V1) do { \
;         __builtin_amdgcn_global_load_lds((const unsigned*)((const char*)(gbase) + (V0)), (LAS unsigned*)(lds + (bufoff) + ldsw), 16, 0, 0); \
;         __builtin_amdgcn_global_load_lds((const unsigned*)((const char*)(gbase) + (V1)), (LAS unsigned*)(lds + (bufoff) + ldsw + 8192), 16, 0, 0); } while (0)
; #define PG8_LDA(dst, b, h) do { _Pragma("unroll") for (int m = 0; m < 4; ++m) _Pragma("unroll") for (int k = 0; k < 2; ++k) dst[m][k] = *(const LAS bf16x8*)(lds + PG8_SA(b, h) + aoff + m * 2048 + k * 1024); } while (0)
; #define PG8_LDB(dst, b, h) do { _Pragma("unroll") for (int n = 0; n < 2; ++n) _Pragma("unroll") for (int k = 0; k < 2; ++k) dst[n][k] = *(const LAS bf16x8*)(lds + PG8_SB(b, h) + boff + n * 2048 + k * 1024); } while (0)
; #define PG8_MMA(ai, bj, At, Bt) do { __builtin_amdgcn_s_setprio(1); _Pragma("unroll") for (int m = 0; m < 4; ++m) _Pragma("unroll") for (int n = 0; n < 2; ++n) _Pragma("unroll") for (int k = 0; k < 2; ++k) \
;         acc[ai][bj][m][n] = __builtin_amdgcn_mfma_f32_16x16x32_bf16(Bt[n][k], At[m][k], acc[ai][bj][m][n], 0, 0, 0); __builtin_amdgcn_s_setprio(0); } while (0)
; #define PG8_WAIT_V(n) asm volatile("s_waitcnt vmcnt(" #n ")" ::: "memory")
; #define PG8_WAIT_L(n) asm volatile("s_waitcnt lgkmcnt(" #n ")" ::: "memory")
; #define PG8_BAR __builtin_amdgcn_s_barrier()
; #define PG8_SCHED __builtin_amdgcn_sched_barrier(0)
; template <class Epi, class Sched>
; DI void gemm_phase(LAS unsigned char* lds, const int lda2, const int ldb2, const int nt, const Sched& S, const Epi& E) {
;     ...
;             PG8_LDB(B0, 0, 0); PG8_LDB(B1, 0, 1); PG8_SCHED; PG8_LDA(At, 0, 0); PG8_STAGE(PG8_SA(1, 1), a1 + hstepA, vA0, vA1);
;             PG8_WAIT_V(8); PG8_WAIT_L(0); PG8_BAR; PG8_MMA(0, 0, At, B0); PG8_MMA(0, 1, At, B1); PG8_BAR; PG8_SCHED;
;             PG8_LDA(At, 0, 1); PG8_STAGE(PG8_SB(0, 0), b2, vB0, vB1); PG8_STAGE(PG8_SB(0, 1), b2 + hstepB, vB0, vB1); PG8_STAGE(PG8_SA(0, 0), a2, vA0, vA1);
;             PG8_WAIT_V(8); PG8_WAIT_L(0); PG8_BAR; PG8_MMA(1, 0, At, B0); PG8_MMA(1, 1, At, B1); PG8_BAR; PG8_SCHED;
	s_setprio 1
	s_waitcnt lgkmcnt(0)
	v_mfma_f32_16x16x32_bf16 v[126:129], v[140:143], v[178:181], v[126:129]
	v_mfma_f32_16x16x32_bf16 v[122:125], v[154:157], v[178:181], v[122:125]
	v_mfma_f32_16x16x32_bf16 v[106:109], v[154:157], v[186:189], v[106:109]
	v_mfma_f32_16x16x32_bf16 v[110:113], v[140:143], v[186:189], v[110:113]
	v_mfma_f32_16x16x32_bf16 v[92:95], v[140:143], v[202:205], v[92:95]
	v_mfma_f32_16x16x32_bf16 v[88:91], v[154:157], v[202:205], v[88:91]
	v_mfma_f32_16x16x32_bf16 v[72:75], v[154:157], v[210:213], v[72:75]
	v_mfma_f32_16x16x32_bf16 v[76:79], v[140:143], v[210:213], v[76:79]
	v_mfma_f32_16x16x32_bf16 v[126:129], v[150:153], v[182:185], v[126:129]
	v_mfma_f32_16x16x32_bf16 v[122:125], v[158:161], v[182:185], v[122:125]
	v_mfma_f32_16x16x32_bf16 v[106:109], v[158:161], v[190:193], v[106:109]
	v_mfma_f32_16x16x32_bf16 v[110:113], v[150:153], v[190:193], v[110:113]
	v_mfma_f32_16x16x32_bf16 v[92:95], v[150:153], v[206:209], v[92:95]
	v_mfma_f32_16x16x32_bf16 v[88:91], v[158:161], v[206:209], v[88:91]
	v_mfma_f32_16x16x32_bf16 v[72:75], v[158:161], v[214:217], v[72:75]
	v_mfma_f32_16x16x32_bf16 v[76:79], v[150:153], v[214:217], v[76:79]
	s_setprio 0
	s_setprio 1
	v_mfma_f32_16x16x32_bf16 v[118:121], v[162:165], v[178:181], v[118:121]
	v_mfma_f32_16x16x32_bf16 v[114:117], v[170:173], v[178:181], v[114:117]
	v_mfma_f32_16x16x32_bf16 v[98:101], v[170:173], v[186:189], v[98:101]
	v_mfma_f32_16x16x32_bf16 v[102:105], v[162:165], v[186:189], v[102:105]
	v_mfma_f32_16x16x32_bf16 v[84:87], v[162:165], v[202:205], v[84:87]
	v_mfma_f32_16x16x32_bf16 v[80:83], v[170:173], v[202:205], v[80:83]
	v_mfma_f32_16x16x32_bf16 v[64:67], v[170:173], v[210:213], v[64:67]
	v_mfma_f32_16x16x32_bf16 v[68:71], v[162:165], v[210:213], v[68:71]
	v_mfma_f32_16x16x32_bf16 v[118:121], v[166:169], v[182:185], v[118:121]
	v_mfma_f32_16x16x32_bf16 v[114:117], v[174:177], v[182:185], v[114:117]
	v_mfma_f32_16x16x32_bf16 v[98:101], v[174:177], v[190:193], v[98:101]
	v_mfma_f32_16x16x32_bf16 v[102:105], v[166:169], v[190:193], v[102:105]
	v_mfma_f32_16x16x32_bf16 v[84:87], v[166:169], v[206:209], v[84:87]
	v_mfma_f32_16x16x32_bf16 v[80:83], v[174:177], v[206:209], v[80:83]
	v_mfma_f32_16x16x32_bf16 v[64:67], v[174:177], v[214:217], v[64:67]
	v_mfma_f32_16x16x32_bf16 v[68:71], v[166:169], v[214:217], v[68:71]
	s_setprio 0
	s_barrier
	s_add_i32 s59, vcc_lo, s73
	v_lshl_add_u64 v[144:145], s[30:31], 0, v[96:97]
	s_mov_b32 m0, s59
	ds_read_b128 v[178:181], v149 offset:16384
	ds_read_b128 v[182:185], v149 offset:17408
	ds_read_b128 v[186:189], v149 offset:18432
	ds_read_b128 v[190:193], v149 offset:19456
	ds_read_b128 v[202:205], v149 offset:20480
	ds_read_b128 v[206:209], v149 offset:21504
	ds_read_b128 v[210:213], v149 offset:22528
	ds_read_b128 v[214:217], v149 offset:23552
	global_load_lds_dwordx4 v[144:145], off
	s_add_i32 m0, s59, 0x2000
	s_add_u32 vcc_lo, s30, 0xb0000
	v_lshl_add_u64 v[194:195], s[30:31], 0, v[130:131]
	s_addc_u32 vcc_hi, s31, 0
	s_add_i32 s58, s58, s73
	global_load_lds_dwordx4 v[194:195], off
	v_lshl_add_u64 v[218:219], vcc, 0, v[96:97]
	s_mov_b32 m0, s58
	v_lshl_add_u64 v[220:221], s[52:53], 0, v[134:135]
	global_load_lds_dwordx4 v[218:219], off
	v_lshl_add_u64 v[218:219], vcc, 0, v[130:131]
	s_add_i32 m0, s58, 0x2000
	s_nop 0
	global_load_lds_dwordx4 v[218:219], off
	v_lshl_add_u64 v[218:219], s[52:53], 0, v[132:133]
	s_mov_b32 m0, s74
	s_nop 0
	global_load_lds_dwordx4 v[218:219], off
	s_mov_b32 m0, s75
	s_nop 0
	global_load_lds_dwordx4 v[220:221], off
	s_waitcnt vmcnt(8)
	s_waitcnt lgkmcnt(0)
	s_barrier
	s_setprio 1
	s_waitcnt lgkmcnt(0)
	v_mfma_f32_16x16x32_bf16 v[60:63], v[140:143], v[178:181], v[60:63]
	v_mfma_f32_16x16x32_bf16 v[56:59], v[154:157], v[178:181], v[56:59]
	v_mfma_f32_16x16x32_bf16 v[40:43], v[154:157], v[186:189], v[40:43]
	v_mfma_f32_16x16x32_bf16 v[44:47], v[140:143], v[186:189], v[44:47]
	v_mfma_f32_16x16x32_bf16 v[28:31], v[140:143], v[202:205], v[28:31]
	v_mfma_f32_16x16x32_bf16 v[24:27], v[154:157], v[202:205], v[24:27]
	v_mfma_f32_16x16x32_bf16 v[8:11], v[154:157], v[210:213], v[8:11]
	v_mfma_f32_16x16x32_bf16 v[12:15], v[140:143], v[210:213], v[12:15]
	v_mfma_f32_16x16x32_bf16 v[60:63], v[150:153], v[182:185], v[60:63]
	v_mfma_f32_16x16x32_bf16 v[56:59], v[158:161], v[182:185], v[56:59]
	v_mfma_f32_16x16x32_bf16 v[40:43], v[158:161], v[190:193], v[40:43]
	v_mfma_f32_16x16x32_bf16 v[44:47], v[150:153], v[190:193], v[44:47]
	v_mfma_f32_16x16x32_bf16 v[28:31], v[150:153], v[206:209], v[28:31]
	v_mfma_f32_16x16x32_bf16 v[24:27], v[158:161], v[206:209], v[24:27]
	v_mfma_f32_16x16x32_bf16 v[8:11], v[158:161], v[214:217], v[8:11]
	v_mfma_f32_16x16x32_bf16 v[12:15], v[150:153], v[214:217], v[12:15]
	s_setprio 0
	s_setprio 1
	v_mfma_f32_16x16x32_bf16 v[52:55], v[162:165], v[178:181], v[52:55]
	v_mfma_f32_16x16x32_bf16 v[48:51], v[170:173], v[178:181], v[48:51]
	v_mfma_f32_16x16x32_bf16 v[32:35], v[170:173], v[186:189], v[32:35]
	v_mfma_f32_16x16x32_bf16 v[36:39], v[162:165], v[186:189], v[36:39]
	v_mfma_f32_16x16x32_bf16 v[20:23], v[162:165], v[202:205], v[20:23]
	v_mfma_f32_16x16x32_bf16 v[16:19], v[170:173], v[202:205], v[16:19]
	v_mfma_f32_16x16x32_bf16 v[0:3], v[170:173], v[210:213], v[0:3]
	v_mfma_f32_16x16x32_bf16 v[4:7], v[162:165], v[210:213], v[4:7]
	v_mfma_f32_16x16x32_bf16 v[52:55], v[166:169], v[182:185], v[52:55]
	v_mfma_f32_16x16x32_bf16 v[48:51], v[174:177], v[182:185], v[48:51]
	v_mfma_f32_16x16x32_bf16 v[32:35], v[174:177], v[190:193], v[32:35]
	v_mfma_f32_16x16x32_bf16 v[36:39], v[166:169], v[190:193], v[36:39]
	v_mfma_f32_16x16x32_bf16 v[20:23], v[166:169], v[206:209], v[20:23]
	v_mfma_f32_16x16x32_bf16 v[16:19], v[174:177], v[206:209], v[16:19]
	v_mfma_f32_16x16x32_bf16 v[0:3], v[174:177], v[214:217], v[0:3]
	v_mfma_f32_16x16x32_bf16 v[4:7], v[166:169], v[214:217], v[4:7]
	s_setprio 0
	s_barrier
; #define PG8_STAGE(bufoff, gbase, V0, V1) do { \
;         __builtin_amdgcn_global_load_lds((const unsigned*)((const char*)(gbase) + (V0)), (LAS unsigned*)(lds + (bufoff) + ldsw), 16, 0, 0); \
;         __builtin_amdgcn_global_load_lds((const unsigned*)((const char*)(gbase) + (V1)), (LAS unsigned*)(lds + (bufoff) + ldsw + 8192), 16, 0, 0); } while (0)
; #define PG8_LDA(dst, b, h) do { _Pragma("unroll") for (int m = 0; m < 4; ++m) _Pragma("unroll") for (int k = 0; k < 2; ++k) dst[m][k] = *(const LAS bf16x8*)(lds + PG8_SA(b, h) + aoff + m * 2048 + k * 1024); } while (0)
; #define PG8_LDB(dst, b, h) do { _Pragma("unroll") for (int n = 0; n < 2; ++n) _Pragma("unroll") for (int k = 0; k < 2; ++k) dst[n][k] = *(const LAS bf16x8*)(lds + PG8_SB(b, h) + boff + n * 2048 + k * 1024); } while (0)
; #define PG8_MMA(ai, bj, At, Bt) do { __builtin_amdgcn_s_setprio(1); _Pragma("unroll") for (int m = 0; m < 4; ++m) _Pragma("unroll") for (int n = 0; n < 2; ++n) _Pragma("unroll") for (int k = 0; k < 2; ++k) \
;         acc[ai][bj][m][n] = __builtin_amdgcn_mfma_f32_16x16x32_bf16(Bt[n][k], At[m][k], acc[ai][bj][m][n], 0, 0, 0); __builtin_amdgcn_s_setprio(0); } while (0)
; #define PG8_WAIT_V(n) asm volatile("s_waitcnt vmcnt(" #n ")" ::: "memory")
; #define PG8_WAIT_L(n) asm volatile("s_waitcnt lgkmcnt(" #n ")" ::: "memory")
; #define PG8_BAR __builtin_amdgcn_s_barrier()
; #define PG8_SCHED __builtin_amdgcn_sched_barrier(0)
; template <class Epi, class Sched>
; DI void gemm_phase(LAS unsigned char* lds, const int lda2, const int ldb2, const int nt, const Sched& S, const Epi& E) {
;     ...
;             PG8_LDB(B0, 1, 0); PG8_LDB(B1, 1, 1); PG8_SCHED; PG8_LDA(At, 1, 0); PG8_STAGE(PG8_SA(0, 1), a2 + hstepA, vA0, vA1);
;             PG8_WAIT_V(8); PG8_WAIT_L(0); PG8_BAR; PG8_MMA(0, 0, At, B0); PG8_MMA(0, 1, At, B1); PG8_BAR; PG8_SCHED;
	s_add_i32 s58, 0, 0x18000
	s_add_i32 s59, 0, 0x1c000
	v_add_u32_e32 v158, s58, v148
	v_add_u32_e32 v174, s59, v148
	s_add_u32 s52, s52, 0xb0000
	s_addc_u32 s53, s53, 0
	s_mov_b32 m0, s76
	v_lshl_add_u64 v[250:251], s[52:53], 0, v[132:133]
	s_nop 0
	global_load_lds_dwordx4 v[250:251], off
	v_lshl_add_u64 v[250:251], s[52:53], 0, v[134:135]
	s_mov_b32 m0, s77
	s_nop 0
	global_load_lds_dwordx4 v[250:251], off
	ds_read_b128 v[140:143], v158
	ds_read_b128 v[150:153], v158 offset:1024
	ds_read_b128 v[154:157], v158 offset:2048
	ds_read_b128 v[158:161], v158 offset:3072
	ds_read_b128 v[162:165], v174
	ds_read_b128 v[166:169], v174 offset:1024
	ds_read_b128 v[170:173], v174 offset:2048
	ds_read_b128 v[174:177], v174 offset:3072
	ds_read_b128 v[178:181], v149 offset:32768
	ds_read_b128 v[182:185], v149 offset:33792
	ds_read_b128 v[186:189], v149 offset:34816
	ds_read_b128 v[190:193], v149 offset:35840
	ds_read_b128 v[202:205], v149 offset:36864
	ds_read_b128 v[206:209], v149 offset:37888
	ds_read_b128 v[210:213], v149 offset:38912
	ds_read_b128 v[214:217], v149 offset:39936
	s_waitcnt vmcnt(8)
	s_waitcnt lgkmcnt(0)
	s_barrier
	s_setprio 1
	s_waitcnt lgkmcnt(0)
	v_mfma_f32_16x16x32_bf16 v[126:129], v[140:143], v[178:181], v[126:129]
	v_mfma_f32_16x16x32_bf16 v[122:125], v[154:157], v[178:181], v[122:125]
	v_mfma_f32_16x16x32_bf16 v[106:109], v[154:157], v[186:189], v[106:109]
	v_mfma_f32_16x16x32_bf16 v[110:113], v[140:143], v[186:189], v[110:113]
	v_mfma_f32_16x16x32_bf16 v[92:95], v[140:143], v[202:205], v[92:95]
	v_mfma_f32_16x16x32_bf16 v[88:91], v[154:157], v[202:205], v[88:91]
	v_mfma_f32_16x16x32_bf16 v[72:75], v[154:157], v[210:213], v[72:75]
	v_mfma_f32_16x16x32_bf16 v[76:79], v[140:143], v[210:213], v[76:79]
	v_mfma_f32_16x16x32_bf16 v[126:129], v[150:153], v[182:185], v[126:129]
	v_mfma_f32_16x16x32_bf16 v[122:125], v[158:161], v[182:185], v[122:125]
	v_mfma_f32_16x16x32_bf16 v[106:109], v[158:161], v[190:193], v[106:109]
	v_mfma_f32_16x16x32_bf16 v[110:113], v[150:153], v[190:193], v[110:113]
	v_mfma_f32_16x16x32_bf16 v[92:95], v[150:153], v[206:209], v[92:95]
	v_mfma_f32_16x16x32_bf16 v[88:91], v[158:161], v[206:209], v[88:91]
	v_mfma_f32_16x16x32_bf16 v[72:75], v[158:161], v[214:217], v[72:75]
	v_mfma_f32_16x16x32_bf16 v[76:79], v[150:153], v[214:217], v[76:79]
	s_setprio 0
	s_setprio 1
	v_mfma_f32_16x16x32_bf16 v[118:121], v[162:165], v[178:181], v[118:121]
	v_mfma_f32_16x16x32_bf16 v[114:117], v[170:173], v[178:181], v[114:117]
	v_mfma_f32_16x16x32_bf16 v[98:101], v[170:173], v[186:189], v[98:101]
	v_mfma_f32_16x16x32_bf16 v[102:105], v[162:165], v[186:189], v[102:105]
	v_mfma_f32_16x16x32_bf16 v[84:87], v[162:165], v[202:205], v[84:87]
	v_mfma_f32_16x16x32_bf16 v[80:83], v[170:173], v[202:205], v[80:83]
	v_mfma_f32_16x16x32_bf16 v[64:67], v[170:173], v[210:213], v[64:67]
	v_mfma_f32_16x16x32_bf16 v[68:71], v[162:165], v[210:213], v[68:71]
	v_mfma_f32_16x16x32_bf16 v[118:121], v[166:169], v[182:185], v[118:121]
	v_mfma_f32_16x16x32_bf16 v[114:117], v[174:177], v[182:185], v[114:117]
	v_mfma_f32_16x16x32_bf16 v[98:101], v[174:177], v[190:193], v[98:101]
	v_mfma_f32_16x16x32_bf16 v[102:105], v[166:169], v[190:193], v[102:105]
	v_mfma_f32_16x16x32_bf16 v[84:87], v[166:169], v[206:209], v[84:87]
	v_mfma_f32_16x16x32_bf16 v[80:83], v[174:177], v[206:209], v[80:83]
	v_mfma_f32_16x16x32_bf16 v[64:67], v[174:177], v[214:217], v[64:67]
	v_mfma_f32_16x16x32_bf16 v[68:71], v[166:169], v[214:217], v[68:71]
	s_setprio 0
	s_barrier
; #define PG8_STAGE(bufoff, gbase, V0, V1) do { \
;         __builtin_amdgcn_global_load_lds((const unsigned*)((const char*)(gbase) + (V0)), (LAS unsigned*)(lds + (bufoff) + ldsw), 16, 0, 0); \
;         __builtin_amdgcn_global_load_lds((const unsigned*)((const char*)(gbase) + (V1)), (LAS unsigned*)(lds + (bufoff) + ldsw + 8192), 16, 0, 0); } while (0)
; #define PG8_LDA(dst, b, h) do { _Pragma("unroll") for (int m = 0; m < 4; ++m) _Pragma("unroll") for (int k = 0; k < 2; ++k) dst[m][k] = *(const LAS bf16x8*)(lds + PG8_SA(b, h) + aoff + m * 2048 + k * 1024); } while (0)
; #define PG8_MMA(ai, bj, At, Bt) do { __builtin_amdgcn_s_setprio(1); _Pragma("unroll") for (int m = 0; m < 4; ++m) _Pragma("unroll") for (int n = 0; n < 2; ++n) _Pragma("unroll") for (int k = 0; k < 2; ++k) \
;         acc[ai][bj][m][n] = __builtin_amdgcn_mfma_f32_16x16x32_bf16(Bt[n][k], At[m][k], acc[ai][bj][m][n], 0, 0, 0); __builtin_amdgcn_s_setprio(0); } while (0)
; #define PG8_WAIT_V(n) asm volatile("s_waitcnt vmcnt(" #n ")" ::: "memory")
; #define PG8_WAIT_L(n) asm volatile("s_waitcnt lgkmcnt(" #n ")" ::: "memory")
; #define PG8_BAR __builtin_amdgcn_s_barrier()
; #define PG8_SCHED __builtin_amdgcn_sched_barrier(0)
; template <class Epi, class Sched>
; DI void gemm_phase(LAS unsigned char* lds, const int lda2, const int ldb2, const int nt, const Sched& S, const Epi& E) {
;     ...
;             PG8_LDA(At, 1, 1); PG8_STAGE(PG8_SB(1, 0), b3, vB0, vB1); PG8_STAGE(PG8_SB(1, 1), b3 + hstepB, vB0, vB1); PG8_STAGE(PG8_SA(1, 0), a3, vA0, vA1);
;             PG8_WAIT_V(8); PG8_WAIT_L(0); PG8_BAR; PG8_MMA(1, 0, At, B0); PG8_MMA(1, 1, At, B1); PG8_BAR; PG8_SCHED;
;         }
;         if (wr == 0) PG8_BAR;
	s_add_i32 s52, s58, s73
	v_lshl_add_u64 v[144:145], v[144:145], 0, s[86:87]
	s_mov_b32 m0, s52
	ds_read_b128 v[178:181], v149 offset:49152
	ds_read_b128 v[182:185], v149 offset:50176
	ds_read_b128 v[186:189], v149 offset:51200
	ds_read_b128 v[190:193], v149 offset:52224
	ds_read_b128 v[202:205], v149 offset:53248
	ds_read_b128 v[206:209], v149 offset:54272
	ds_read_b128 v[210:213], v149 offset:55296
	ds_read_b128 v[214:217], v149 offset:56320
	global_load_lds_dwordx4 v[144:145], off
	s_add_i32 m0, s52, 0x2000
	s_add_u32 s30, s30, 0xb0080
	v_lshl_add_u64 v[144:145], v[194:195], 0, s[86:87]
	s_addc_u32 s31, s31, 0
	s_add_i32 s52, s59, s73
	global_load_lds_dwordx4 v[144:145], off
	v_lshl_add_u64 v[144:145], s[30:31], 0, v[96:97]
	s_mov_b32 m0, s52
	s_nop 0
	global_load_lds_dwordx4 v[144:145], off
	v_lshl_add_u64 v[144:145], s[30:31], 0, v[130:131]
	s_add_i32 m0, s52, 0x2000
	s_nop 0
	global_load_lds_dwordx4 v[144:145], off
	v_lshl_add_u64 v[144:145], v[218:219], 0, s[86:87]
	s_mov_b32 m0, s81
	s_nop 0
	global_load_lds_dwordx4 v[144:145], off
	v_lshl_add_u64 v[144:145], v[220:221], 0, s[86:87]
	s_mov_b32 m0, s82
	s_nop 0
	global_load_lds_dwordx4 v[144:145], off
	s_waitcnt vmcnt(8)
	s_waitcnt lgkmcnt(0)
	s_barrier
	s_setprio 1
	s_waitcnt lgkmcnt(0)
	v_mfma_f32_16x16x32_bf16 v[60:63], v[140:143], v[178:181], v[60:63]
	v_mfma_f32_16x16x32_bf16 v[56:59], v[154:157], v[178:181], v[56:59]
	v_mfma_f32_16x16x32_bf16 v[40:43], v[154:157], v[186:189], v[40:43]
	v_mfma_f32_16x16x32_bf16 v[44:47], v[140:143], v[186:189], v[44:47]
	v_mfma_f32_16x16x32_bf16 v[28:31], v[140:143], v[202:205], v[28:31]
	v_mfma_f32_16x16x32_bf16 v[24:27], v[154:157], v[202:205], v[24:27]
	v_mfma_f32_16x16x32_bf16 v[8:11], v[154:157], v[210:213], v[8:11]
	v_mfma_f32_16x16x32_bf16 v[12:15], v[140:143], v[210:213], v[12:15]
	v_mfma_f32_16x16x32_bf16 v[60:63], v[150:153], v[182:185], v[60:63]
	v_mfma_f32_16x16x32_bf16 v[56:59], v[158:161], v[182:185], v[56:59]
	v_mfma_f32_16x16x32_bf16 v[40:43], v[158:161], v[190:193], v[40:43]
	v_mfma_f32_16x16x32_bf16 v[44:47], v[150:153], v[190:193], v[44:47]
	v_mfma_f32_16x16x32_bf16 v[28:31], v[150:153], v[206:209], v[28:31]
	v_mfma_f32_16x16x32_bf16 v[24:27], v[158:161], v[206:209], v[24:27]
	v_mfma_f32_16x16x32_bf16 v[8:11], v[158:161], v[214:217], v[8:11]
	v_mfma_f32_16x16x32_bf16 v[12:15], v[150:153], v[214:217], v[12:15]
	s_setprio 0
	s_setprio 1
	v_mfma_f32_16x16x32_bf16 v[52:55], v[162:165], v[178:181], v[52:55]
	v_mfma_f32_16x16x32_bf16 v[48:51], v[170:173], v[178:181], v[48:51]
	v_mfma_f32_16x16x32_bf16 v[32:35], v[170:173], v[186:189], v[32:35]
	v_mfma_f32_16x16x32_bf16 v[36:39], v[162:165], v[186:189], v[36:39]
	v_mfma_f32_16x16x32_bf16 v[20:23], v[162:165], v[202:205], v[20:23]
	v_mfma_f32_16x16x32_bf16 v[16:19], v[170:173], v[202:205], v[16:19]
	v_mfma_f32_16x16x32_bf16 v[0:3], v[170:173], v[210:213], v[0:3]
	v_mfma_f32_16x16x32_bf16 v[4:7], v[162:165], v[210:213], v[4:7]
	v_mfma_f32_16x16x32_bf16 v[52:55], v[166:169], v[182:185], v[52:55]
	v_mfma_f32_16x16x32_bf16 v[48:51], v[174:177], v[182:185], v[48:51]
	v_mfma_f32_16x16x32_bf16 v[32:35], v[174:177], v[190:193], v[32:35]
	v_mfma_f32_16x16x32_bf16 v[36:39], v[166:169], v[190:193], v[36:39]
	v_mfma_f32_16x16x32_bf16 v[20:23], v[166:169], v[206:209], v[20:23]
	v_mfma_f32_16x16x32_bf16 v[16:19], v[174:177], v[206:209], v[16:19]
	v_mfma_f32_16x16x32_bf16 v[0:3], v[174:177], v[214:217], v[0:3]
	v_mfma_f32_16x16x32_bf16 v[4:7], v[166:169], v[214:217], v[4:7]
	s_setprio 0
	s_barrier
	s_add_i32 s57, s57, 2
	s_add_u32 s28, s28, 0x100
	s_addc_u32 s29, s29, 0
	s_add_u32 s1, s1, 0x100
	s_addc_u32 s10, s10, 0
	s_cmp_gt_u32 s57, 41
	s_cbranch_scc0 .LBB0_1124
	s_and_b64 vcc, exec, s[22:23]
	s_cbranch_vccz .LBB0_1127
	s_barrier

; #define LAS __attribute__((address_space(3)))
; __global__ void __launch_bounds__(512, 2) fwd_kernel(Args a0) {
;     extern __shared__ __attribute__((aligned(16))) unsigned char lds_raw[];
;     LAS unsigned char* lds = (LAS unsigned char*)lds_raw;
	.amdhsa_kernel _Z10fwd_kernel4Args
		.amdhsa_group_segment_fixed_size 0
		.amdhsa_private_segment_fixed_size 0
		.amdhsa_kernarg_size 408
		.amdhsa_user_sgpr_count 2
		.amdhsa_user_sgpr_dispatch_ptr 0
		.amdhsa_user_sgpr_queue_ptr 0
		.amdhsa_user_sgpr_kernarg_segment_ptr 1
		.amdhsa_user_sgpr_dispatch_id 0
		.amdhsa_user_sgpr_kernarg_preload_length 0
		.amdhsa_user_sgpr_kernarg_preload_offset 0
		.amdhsa_user_sgpr_private_segment_size 0
		.amdhsa_uses_dynamic_stack 0
		.amdhsa_enable_private_segment 0
		.amdhsa_system_sgpr_workgroup_id_x 1
		.amdhsa_system_sgpr_workgroup_id_y 0
		.amdhsa_system_sgpr_workgroup_id_z 0
		.amdhsa_system_sgpr_workgroup_info 0
		.amdhsa_system_vgpr_workitem_id 2
		.amdhsa_next_free_vgpr 252
		.amdhsa_next_free_sgpr 100
		.amdhsa_accum_offset 252
		.amdhsa_reserve_vcc 1
		.amdhsa_float_round_mode_32 0
		.amdhsa_float_round_mode_16_64 0
		.amdhsa_float_denorm_mode_32 3
		.amdhsa_float_denorm_mode_16_64 3
		.amdhsa_dx10_clamp 1
		.amdhsa_ieee_mode 1
		.amdhsa_fp16_overflow 0
		.amdhsa_tg_split 0
		.amdhsa_exception_fp_ieee_invalid_op 0
		.amdhsa_exception_fp_denorm_src 0
		.amdhsa_exception_fp_ieee_div_zero 0
		.amdhsa_exception_fp_ieee_overflow 0
		.amdhsa_exception_fp_ieee_underflow 0
		.amdhsa_exception_fp_ieee_inexact 0
		.amdhsa_exception_int_div_zero 0
	.end_amdhsa_kernel

; __global__ void __launch_bounds__(512, 2) fwd_kernel(Args a0) {
amdhsa.kernels:
  - .agpr_count:     0
    .args:
      - .offset:         0
        .size:           152
        .value_kind:     by_value
      - .offset:         152
        .size:           4
        .value_kind:     hidden_block_count_x
      - .offset:         156
        .size:           4
        .value_kind:     hidden_block_count_y
      - .offset:         160
        .size:           4
        .value_kind:     hidden_block_count_z
      - .offset:         164
        .size:           2
        .value_kind:     hidden_group_size_x
      - .offset:         166
        .size:           2
        .value_kind:     hidden_group_size_y
      - .offset:         168
        .size:           2
        .value_kind:     hidden_group_size_z
      - .offset:         170
        .size:           2
        .value_kind:     hidden_remainder_x
      - .offset:         172
        .size:           2
        .value_kind:     hidden_remainder_y
      - .offset:         174
        .size:           2
        .value_kind:     hidden_remainder_z
      - .offset:         192
        .size:           8
        .value_kind:     hidden_global_offset_x
      - .offset:         200
        .size:           8
        .value_kind:     hidden_global_offset_y
      - .offset:         208
        .size:           8
        .value_kind:     hidden_global_offset_z
      - .offset:         216
        .size:           2
        .value_kind:     hidden_grid_dims
      - .offset:         240
        .size:           8
        .value_kind:     hidden_multigrid_sync_arg
      - .offset:         272
        .size:           4
        .value_kind:     hidden_dynamic_lds_size
    .group_segment_fixed_size: 0
    .kernarg_segment_align: 8
    .kernarg_segment_size: 408
    .language:       OpenCL C
    .language_version:
      - 2
      - 0
    .max_flat_workgroup_size: 512
    .name:           _Z10fwd_kernel4Args
    .private_segment_fixed_size: 0
    .sgpr_count:     106
    .sgpr_spill_count: 145
    .symbol:         _Z10fwd_kernel4Args.kd
    .uniform_work_group_size: 1
    .uses_dynamic_stack: false
    .vgpr_count:     252
    .vgpr_spill_count: 0
    .wavefront_size: 64
